# GEMM loops: first MFMA issues right after the barrier release (redundant post-barrier lgkmcnt wait and mid-block priority drop removed, net -8 bytes per block)
# speedup vs baseline: 1.0092x; 1.0092x over previous
; #define PG8_STAGE(bufoff, gbase, voff) do { _Pragma("unroll") for (int _i = 0; _i < 2; ++_i) \
;         __builtin_amdgcn_global_load_lds((const unsigned*)((const char*)(gbase) + (voff)[_i]), (PG8_LAS unsigned*)(lds + (bufoff) + ldsw + _i * 8192), 16, 0, 0); } while (0)
; #define PG8_LDA(dst, b, h) do { _Pragma("unroll") for (int m = 0; m < 4; ++m) _Pragma("unroll") for (int k = 0; k < 2; ++k) dst[m][k] = *(const PG8_LAS bf16x8*)(lds + PG8_SA(b, h) + aoff + m * 2048 + k * 1024); } while (0)
; #define PG8_LDB(dst, b, h) do { _Pragma("unroll") for (int n = 0; n < 2; ++n) _Pragma("unroll") for (int k = 0; k < 2; ++k) dst[n][k] = *(const PG8_LAS bf16x8*)(lds + PG8_SB(b, h) + boff + n * 2048 + k * 1024); } while (0)
; #define PG8_MMA(ai, bj, At, Bt) do { __builtin_amdgcn_s_setprio(1); _Pragma("unroll") for (int m = 0; m < 4; ++m) _Pragma("unroll") for (int n = 0; n < 2; ++n) _Pragma("unroll") for (int k = 0; k < 2; ++k) \
;         acc[ai][bj][m][n] = __builtin_amdgcn_mfma_f32_16x16x32_bf16(Bt[n][k], At[m][k], acc[ai][bj][m][n], 0, 0, 0); __builtin_amdgcn_s_setprio(0); } while (0)
; #define PG8_WAIT_V(n) asm volatile("s_waitcnt vmcnt(" #n ")" ::: "memory")
; #define PG8_WAIT_L(n) asm volatile("s_waitcnt lgkmcnt(" #n ")" ::: "memory")
; #define PG8_BAR __builtin_amdgcn_s_barrier()
; #define PG8_SCHED __builtin_amdgcn_sched_barrier(0)
; template <class Epi, class Sched, bool ALIGN_EPI = false, bool SP2 = false>
; __device__ __forceinline__ void gemm_phase(PG8_LAS unsigned char* lds, const Gemm g, const Sched& S, const Epi& E) {
;     ...
;             if constexpr (SP2) {
;             PG8_LDB(B0, 0, 0); PG8_LDB(B1, 0, 1); PG8_SCHED; PG8_LDA(At, 0, 0); PG8_STAGE(PG8_SA(1, 1), a1 + hstepA, voffA);
;             PG8_WAIT_V(8); PG8_WAIT_L(0); PG8_BAR; PG8_MMA(0, 0, At, B0); PG8_MMA(0, 1, At, B1); PG8_BAR; PG8_SCHED;
;             PG8_LDA(At, 0, 1); PG8_STAGE(PG8_SB(0, 0), b2, voffB); PG8_STAGE(PG8_SB(0, 1), b2 + hstepB, voffB); PG8_STAGE(PG8_SA(0, 0), a2, voffA);
.LBB0_244:
	ds_read_b128 v[152:155], v147
	ds_read_b128 v[156:159], v147 offset:1024
	ds_read_b128 v[160:163], v147 offset:2048
	ds_read_b128 v[164:167], v147 offset:3072
	ds_read_b128 v[168:171], v148
	ds_read_b128 v[172:175], v148 offset:1024
	ds_read_b128 v[176:179], v148 offset:2048
	ds_read_b128 v[180:183], v148 offset:3072
	s_add_u32 s28, s26, 0xfffc0080
	s_addc_u32 s29, s27, -1
	s_cmp_eq_u32 s68, 12
	s_cselect_b32 s31, s15, s29
	s_cselect_b32 s30, s62, s28
	s_cselect_b32 s29, s13, s67
	s_cselect_b32 s28, s63, s66
	v_lshl_add_u64 v[184:185], s[26:27], 0, v[136:137]
	s_add_i32 m0, s25, 0xc000
	ds_read_b128 v[188:191], v149
	ds_read_b128 v[192:195], v149 offset:1024
	ds_read_b128 v[196:199], v149 offset:2048
	ds_read_b128 v[200:203], v149 offset:3072
	ds_read_b128 v[204:207], v149 offset:4096
	ds_read_b128 v[208:211], v149 offset:5120
	ds_read_b128 v[212:215], v149 offset:6144
	ds_read_b128 v[216:219], v149 offset:7168
	global_load_lds_dwordx4 v[184:185], off
	v_lshl_add_u64 v[184:185], s[26:27], 0, v[138:139]
	s_add_i32 m0, s25, 0xe000
	s_nop 0
	global_load_lds_dwordx4 v[184:185], off
	s_waitcnt vmcnt(8)
	s_waitcnt lgkmcnt(0)
	s_barrier
	s_setprio 1
	v_mfma_f32_16x16x32_bf16 v[116:119], v[152:155], v[188:191], v[116:119]
	v_mfma_f32_16x16x32_bf16 v[108:111], v[160:163], v[188:191], v[108:111]
	v_mfma_f32_16x16x32_bf16 v[104:107], v[152:155], v[196:199], v[104:107]
	v_mfma_f32_16x16x32_bf16 v[100:103], v[160:163], v[196:199], v[100:103]
	v_mfma_f32_16x16x32_bf16 v[92:95], v[152:155], v[204:207], v[92:95]
	v_mfma_f32_16x16x32_bf16 v[84:87], v[160:163], v[204:207], v[84:87]
	v_mfma_f32_16x16x32_bf16 v[76:79], v[152:155], v[212:215], v[76:79]
	v_mfma_f32_16x16x32_bf16 v[68:71], v[160:163], v[212:215], v[68:71]
	v_mfma_f32_16x16x32_bf16 v[116:119], v[156:159], v[192:195], v[116:119]
	v_mfma_f32_16x16x32_bf16 v[108:111], v[164:167], v[192:195], v[108:111]
	v_mfma_f32_16x16x32_bf16 v[104:107], v[156:159], v[200:203], v[104:107]
	v_mfma_f32_16x16x32_bf16 v[100:103], v[164:167], v[200:203], v[100:103]
	v_mfma_f32_16x16x32_bf16 v[92:95], v[156:159], v[208:211], v[92:95]
	v_mfma_f32_16x16x32_bf16 v[84:87], v[164:167], v[208:211], v[84:87]
	v_mfma_f32_16x16x32_bf16 v[76:79], v[156:159], v[216:219], v[76:79]
	v_mfma_f32_16x16x32_bf16 v[68:71], v[164:167], v[216:219], v[68:71]
	s_setprio 1
	v_mfma_f32_16x16x32_bf16 v[124:127], v[168:171], v[188:191], v[124:127]
	v_mfma_f32_16x16x32_bf16 v[120:123], v[176:179], v[188:191], v[120:123]
	v_mfma_f32_16x16x32_bf16 v[112:115], v[168:171], v[196:199], v[112:115]
	v_mfma_f32_16x16x32_bf16 v[96:99], v[176:179], v[196:199], v[96:99]
	v_mfma_f32_16x16x32_bf16 v[88:91], v[168:171], v[204:207], v[88:91]
	v_mfma_f32_16x16x32_bf16 v[80:83], v[176:179], v[204:207], v[80:83]
	v_mfma_f32_16x16x32_bf16 v[72:75], v[168:171], v[212:215], v[72:75]
	v_mfma_f32_16x16x32_bf16 v[64:67], v[176:179], v[212:215], v[64:67]
	v_mfma_f32_16x16x32_bf16 v[124:127], v[172:175], v[192:195], v[124:127]
	v_mfma_f32_16x16x32_bf16 v[120:123], v[180:183], v[192:195], v[120:123]
	v_mfma_f32_16x16x32_bf16 v[112:115], v[172:175], v[200:203], v[112:115]
	v_mfma_f32_16x16x32_bf16 v[96:99], v[180:183], v[200:203], v[96:99]
	v_mfma_f32_16x16x32_bf16 v[88:91], v[172:175], v[208:211], v[88:91]
	v_mfma_f32_16x16x32_bf16 v[80:83], v[180:183], v[208:211], v[80:83]
	v_mfma_f32_16x16x32_bf16 v[72:75], v[172:175], v[216:219], v[72:75]
	v_mfma_f32_16x16x32_bf16 v[64:67], v[180:183], v[216:219], v[64:67]
	s_barrier
	s_setprio 0
	s_add_i32 s58, s46, s36
	v_lshl_add_u64 v[184:185], s[28:29], 0, v[132:133]
	s_mov_b32 m0, s58
	ds_read_b128 v[188:191], v149 offset:16384
	ds_read_b128 v[192:195], v149 offset:17408
	ds_read_b128 v[196:199], v149 offset:18432
	ds_read_b128 v[200:203], v149 offset:19456
	ds_read_b128 v[204:207], v149 offset:20480
	ds_read_b128 v[208:211], v149 offset:21504
	ds_read_b128 v[212:215], v149 offset:22528
	ds_read_b128 v[216:219], v149 offset:23552
	global_load_lds_dwordx4 v[184:185], off
	s_add_i32 m0, s58, 0x2000
	s_add_u32 s58, s28, 0x40000
	v_lshl_add_u64 v[220:221], s[28:29], 0, v[128:129]
	s_addc_u32 s59, s29, 0
	s_add_i32 s69, s47, s36
	global_load_lds_dwordx4 v[220:221], off
	v_lshl_add_u64 v[222:223], s[58:59], 0, v[132:133]
	s_mov_b32 m0, s69
	v_lshl_add_u64 v[224:225], s[30:31], 0, v[130:131]
	global_load_lds_dwordx4 v[222:223], off
	v_lshl_add_u64 v[222:223], s[58:59], 0, v[128:129]
	s_add_i32 m0, s69, 0x2000
	s_nop 0
	global_load_lds_dwordx4 v[222:223], off
	v_lshl_add_u64 v[222:223], s[30:31], 0, v[134:135]
	s_mov_b32 m0, s25
	s_nop 0
	global_load_lds_dwordx4 v[222:223], off
	s_mov_b32 m0, s39
	s_nop 0
	global_load_lds_dwordx4 v[224:225], off
	s_waitcnt vmcnt(8)
	s_waitcnt lgkmcnt(0)
	s_barrier
; #define PG8_STAGE(bufoff, gbase, voff) do { _Pragma("unroll") for (int _i = 0; _i < 2; ++_i) \
;         __builtin_amdgcn_global_load_lds((const unsigned*)((const char*)(gbase) + (voff)[_i]), (PG8_LAS unsigned*)(lds + (bufoff) + ldsw + _i * 8192), 16, 0, 0); } while (0)
; #define PG8_LDA(dst, b, h) do { _Pragma("unroll") for (int m = 0; m < 4; ++m) _Pragma("unroll") for (int k = 0; k < 2; ++k) dst[m][k] = *(const PG8_LAS bf16x8*)(lds + PG8_SA(b, h) + aoff + m * 2048 + k * 1024); } while (0)
; #define PG8_LDB(dst, b, h) do { _Pragma("unroll") for (int n = 0; n < 2; ++n) _Pragma("unroll") for (int k = 0; k < 2; ++k) dst[n][k] = *(const PG8_LAS bf16x8*)(lds + PG8_SB(b, h) + boff + n * 2048 + k * 1024); } while (0)
; #define PG8_MMA(ai, bj, At, Bt) do { __builtin_amdgcn_s_setprio(1); _Pragma("unroll") for (int m = 0; m < 4; ++m) _Pragma("unroll") for (int n = 0; n < 2; ++n) _Pragma("unroll") for (int k = 0; k < 2; ++k) \
;         acc[ai][bj][m][n] = __builtin_amdgcn_mfma_f32_16x16x32_bf16(Bt[n][k], At[m][k], acc[ai][bj][m][n], 0, 0, 0); __builtin_amdgcn_s_setprio(0); } while (0)
; #define PG8_WAIT_V(n) asm volatile("s_waitcnt vmcnt(" #n ")" ::: "memory")
; #define PG8_WAIT_L(n) asm volatile("s_waitcnt lgkmcnt(" #n ")" ::: "memory")
; #define PG8_BAR __builtin_amdgcn_s_barrier()
; #define PG8_SCHED __builtin_amdgcn_sched_barrier(0)
; template <class Epi, class Sched, bool ALIGN_EPI = false, bool SP2 = false>
; __device__ __forceinline__ void gemm_phase(PG8_LAS unsigned char* lds, const Gemm g, const Sched& S, const Epi& E) {
;     ...
;             PG8_WAIT_V(8); PG8_WAIT_L(0); PG8_BAR; PG8_MMA(1, 0, At, B0); PG8_MMA(1, 1, At, B1); PG8_BAR; PG8_SCHED;
;             PG8_LDB(B0, 1, 0); PG8_LDB(B1, 1, 1); PG8_SCHED; PG8_LDA(At, 1, 0); PG8_STAGE(PG8_SA(0, 1), a2 + hstepA, voffA);
;             PG8_WAIT_V(8); PG8_WAIT_L(0); PG8_BAR; PG8_MMA(0, 0, At, B0); PG8_MMA(0, 1, At, B1); PG8_BAR; PG8_SCHED;
;             PG8_LDA(At, 1, 1); PG8_STAGE(PG8_SB(1, 0), b3, voffB); PG8_STAGE(PG8_SB(1, 1), b3 + hstepB, voffB); PG8_STAGE(PG8_SA(1, 0), a3, voffA);
;             PG8_WAIT_V(8); PG8_WAIT_L(0); PG8_BAR; PG8_MMA(1, 0, At, B0); PG8_MMA(1, 1, At, B1); PG8_BAR; PG8_SCHED;
	s_setprio 1
	v_mfma_f32_16x16x32_bf16 v[60:63], v[152:155], v[188:191], v[60:63]
	v_mfma_f32_16x16x32_bf16 v[52:55], v[160:163], v[188:191], v[52:55]
	v_mfma_f32_16x16x32_bf16 v[44:47], v[152:155], v[196:199], v[44:47]
	v_mfma_f32_16x16x32_bf16 v[36:39], v[160:163], v[196:199], v[36:39]
	v_mfma_f32_16x16x32_bf16 v[28:31], v[152:155], v[204:207], v[28:31]
	v_mfma_f32_16x16x32_bf16 v[20:23], v[160:163], v[204:207], v[20:23]
	v_mfma_f32_16x16x32_bf16 v[12:15], v[152:155], v[212:215], v[12:15]
	v_mfma_f32_16x16x32_bf16 v[4:7], v[160:163], v[212:215], v[4:7]
	v_mfma_f32_16x16x32_bf16 v[60:63], v[156:159], v[192:195], v[60:63]
	v_mfma_f32_16x16x32_bf16 v[52:55], v[164:167], v[192:195], v[52:55]
	v_mfma_f32_16x16x32_bf16 v[44:47], v[156:159], v[200:203], v[44:47]
	v_mfma_f32_16x16x32_bf16 v[36:39], v[164:167], v[200:203], v[36:39]
	v_mfma_f32_16x16x32_bf16 v[28:31], v[156:159], v[208:211], v[28:31]
	v_mfma_f32_16x16x32_bf16 v[20:23], v[164:167], v[208:211], v[20:23]
	v_mfma_f32_16x16x32_bf16 v[12:15], v[156:159], v[216:219], v[12:15]
	v_mfma_f32_16x16x32_bf16 v[4:7], v[164:167], v[216:219], v[4:7]
	s_setprio 1
	v_mfma_f32_16x16x32_bf16 v[56:59], v[168:171], v[188:191], v[56:59]
	v_mfma_f32_16x16x32_bf16 v[48:51], v[176:179], v[188:191], v[48:51]
	v_mfma_f32_16x16x32_bf16 v[40:43], v[168:171], v[196:199], v[40:43]
	v_mfma_f32_16x16x32_bf16 v[32:35], v[176:179], v[196:199], v[32:35]
	v_mfma_f32_16x16x32_bf16 v[24:27], v[168:171], v[204:207], v[24:27]
	v_mfma_f32_16x16x32_bf16 v[16:19], v[176:179], v[204:207], v[16:19]
	v_mfma_f32_16x16x32_bf16 v[8:11], v[168:171], v[212:215], v[8:11]
	v_mfma_f32_16x16x32_bf16 v[0:3], v[176:179], v[212:215], v[0:3]
	v_mfma_f32_16x16x32_bf16 v[56:59], v[172:175], v[192:195], v[56:59]
	v_mfma_f32_16x16x32_bf16 v[48:51], v[180:183], v[192:195], v[48:51]
	v_mfma_f32_16x16x32_bf16 v[40:43], v[172:175], v[200:203], v[40:43]
	v_mfma_f32_16x16x32_bf16 v[32:35], v[180:183], v[200:203], v[32:35]
	v_mfma_f32_16x16x32_bf16 v[24:27], v[172:175], v[208:211], v[24:27]
	v_mfma_f32_16x16x32_bf16 v[16:19], v[180:183], v[208:211], v[16:19]
	v_mfma_f32_16x16x32_bf16 v[8:11], v[172:175], v[216:219], v[8:11]
	v_mfma_f32_16x16x32_bf16 v[0:3], v[180:183], v[216:219], v[0:3]
	s_barrier
	s_setprio 0
	s_add_i32 s58, 0, 0x18000
	v_add_u32_e32 v151, s58, v145
	s_add_i32 s59, 0, 0x1c000
	ds_read_b128 v[152:155], v151
	ds_read_b128 v[156:159], v151 offset:1024
	ds_read_b128 v[160:163], v151 offset:2048
	ds_read_b128 v[164:167], v151 offset:3072
	v_add_u32_e32 v151, s59, v145
	ds_read_b128 v[168:171], v151
	ds_read_b128 v[172:175], v151 offset:1024
	ds_read_b128 v[176:179], v151 offset:2048
	ds_read_b128 v[180:183], v151 offset:3072
	s_add_u32 s30, s30, 0x40000
	s_addc_u32 s31, s31, 0
	s_mov_b32 m0, s40
	v_lshl_add_u64 v[226:227], s[30:31], 0, v[134:135]
	ds_read_b128 v[188:191], v149 offset:32768
	ds_read_b128 v[192:195], v149 offset:33792
	ds_read_b128 v[196:199], v149 offset:34816
	ds_read_b128 v[200:203], v149 offset:35840
	ds_read_b128 v[204:207], v149 offset:36864
	ds_read_b128 v[208:211], v149 offset:37888
	ds_read_b128 v[212:215], v149 offset:38912
	ds_read_b128 v[216:219], v149 offset:39936
	global_load_lds_dwordx4 v[226:227], off
	v_lshl_add_u64 v[226:227], s[30:31], 0, v[130:131]
	s_mov_b32 m0, s41
	s_nop 0
	global_load_lds_dwordx4 v[226:227], off
	s_waitcnt vmcnt(8)
	s_waitcnt lgkmcnt(0)
	s_barrier
	s_setprio 1
	v_mfma_f32_16x16x32_bf16 v[116:119], v[152:155], v[188:191], v[116:119]
	v_mfma_f32_16x16x32_bf16 v[108:111], v[160:163], v[188:191], v[108:111]
	v_mfma_f32_16x16x32_bf16 v[104:107], v[152:155], v[196:199], v[104:107]
	v_mfma_f32_16x16x32_bf16 v[100:103], v[160:163], v[196:199], v[100:103]
	v_mfma_f32_16x16x32_bf16 v[92:95], v[152:155], v[204:207], v[92:95]
	v_mfma_f32_16x16x32_bf16 v[84:87], v[160:163], v[204:207], v[84:87]
	v_mfma_f32_16x16x32_bf16 v[76:79], v[152:155], v[212:215], v[76:79]
	v_mfma_f32_16x16x32_bf16 v[68:71], v[160:163], v[212:215], v[68:71]
	v_mfma_f32_16x16x32_bf16 v[116:119], v[156:159], v[192:195], v[116:119]
	v_mfma_f32_16x16x32_bf16 v[108:111], v[164:167], v[192:195], v[108:111]
	v_mfma_f32_16x16x32_bf16 v[104:107], v[156:159], v[200:203], v[104:107]
	v_mfma_f32_16x16x32_bf16 v[100:103], v[164:167], v[200:203], v[100:103]
	v_mfma_f32_16x16x32_bf16 v[92:95], v[156:159], v[208:211], v[92:95]
	v_mfma_f32_16x16x32_bf16 v[84:87], v[164:167], v[208:211], v[84:87]
	v_mfma_f32_16x16x32_bf16 v[76:79], v[156:159], v[216:219], v[76:79]
	v_mfma_f32_16x16x32_bf16 v[68:71], v[164:167], v[216:219], v[68:71]
	s_setprio 1
	v_mfma_f32_16x16x32_bf16 v[124:127], v[168:171], v[188:191], v[124:127]
	v_mfma_f32_16x16x32_bf16 v[120:123], v[176:179], v[188:191], v[120:123]
	v_mfma_f32_16x16x32_bf16 v[112:115], v[168:171], v[196:199], v[112:115]
	v_mfma_f32_16x16x32_bf16 v[96:99], v[176:179], v[196:199], v[96:99]
	v_mfma_f32_16x16x32_bf16 v[88:91], v[168:171], v[204:207], v[88:91]
	v_mfma_f32_16x16x32_bf16 v[80:83], v[176:179], v[204:207], v[80:83]
	v_mfma_f32_16x16x32_bf16 v[72:75], v[168:171], v[212:215], v[72:75]
	v_mfma_f32_16x16x32_bf16 v[64:67], v[176:179], v[212:215], v[64:67]
	v_mfma_f32_16x16x32_bf16 v[124:127], v[172:175], v[192:195], v[124:127]
	v_mfma_f32_16x16x32_bf16 v[120:123], v[180:183], v[192:195], v[120:123]
	v_mfma_f32_16x16x32_bf16 v[112:115], v[172:175], v[200:203], v[112:115]
	v_mfma_f32_16x16x32_bf16 v[96:99], v[180:183], v[200:203], v[96:99]
	v_mfma_f32_16x16x32_bf16 v[88:91], v[172:175], v[208:211], v[88:91]
	v_mfma_f32_16x16x32_bf16 v[80:83], v[180:183], v[208:211], v[80:83]
	v_mfma_f32_16x16x32_bf16 v[72:75], v[172:175], v[216:219], v[72:75]
	v_mfma_f32_16x16x32_bf16 v[64:67], v[180:183], v[216:219], v[64:67]
	s_barrier
; #define PG8_STAGE(bufoff, gbase, voff) do { _Pragma("unroll") for (int _i = 0; _i < 2; ++_i) \
;         __builtin_amdgcn_global_load_lds((const unsigned*)((const char*)(gbase) + (voff)[_i]), (PG8_LAS unsigned*)(lds + (bufoff) + ldsw + _i * 8192), 16, 0, 0); } while (0)
; #define PG8_LDA(dst, b, h) do { _Pragma("unroll") for (int m = 0; m < 4; ++m) _Pragma("unroll") for (int k = 0; k < 2; ++k) dst[m][k] = *(const PG8_LAS bf16x8*)(lds + PG8_SA(b, h) + aoff + m * 2048 + k * 1024); } while (0)
; #define PG8_MMA(ai, bj, At, Bt) do { __builtin_amdgcn_s_setprio(1); _Pragma("unroll") for (int m = 0; m < 4; ++m) _Pragma("unroll") for (int n = 0; n < 2; ++n) _Pragma("unroll") for (int k = 0; k < 2; ++k) \
;         acc[ai][bj][m][n] = __builtin_amdgcn_mfma_f32_16x16x32_bf16(Bt[n][k], At[m][k], acc[ai][bj][m][n], 0, 0, 0); __builtin_amdgcn_s_setprio(0); } while (0)
; #define PG8_WAIT_V(n) asm volatile("s_waitcnt vmcnt(" #n ")" ::: "memory")
; #define PG8_WAIT_L(n) asm volatile("s_waitcnt lgkmcnt(" #n ")" ::: "memory")
; #define PG8_BAR __builtin_amdgcn_s_barrier()
; #define PG8_SCHED __builtin_amdgcn_sched_barrier(0)
; template <class Epi, class Sched, bool ALIGN_EPI = false, bool SP2 = false>
; __device__ __forceinline__ void gemm_phase(PG8_LAS unsigned char* lds, const Gemm g, const Sched& S, const Epi& E) {
;     ...
;             PG8_LDA(At, 1, 1); PG8_STAGE(PG8_SB(1, 0), b3, voffB); PG8_STAGE(PG8_SB(1, 1), b3 + hstepB, voffB); PG8_STAGE(PG8_SA(1, 0), a3, voffA);
;             PG8_WAIT_V(8); PG8_WAIT_L(0); PG8_BAR; PG8_MMA(1, 0, At, B0); PG8_MMA(1, 1, At, B1); PG8_BAR; PG8_SCHED;
	s_setprio 0
	s_add_i32 s30, s58, s36
	v_lshl_add_u64 v[184:185], v[184:185], 0, s[8:9]
	s_mov_b32 m0, s30
	ds_read_b128 v[188:191], v149 offset:49152
	ds_read_b128 v[192:195], v149 offset:50176
	ds_read_b128 v[196:199], v149 offset:51200
	ds_read_b128 v[200:203], v149 offset:52224
	ds_read_b128 v[204:207], v149 offset:53248
	ds_read_b128 v[208:211], v149 offset:54272
	ds_read_b128 v[212:215], v149 offset:55296
	ds_read_b128 v[216:219], v149 offset:56320
	global_load_lds_dwordx4 v[184:185], off
	s_add_i32 m0, s30, 0x2000
	s_add_u32 s28, s28, 0x40080
	v_lshl_add_u64 v[184:185], v[220:221], 0, s[8:9]
	s_addc_u32 s29, s29, 0
	s_add_i32 s30, s59, s36
	global_load_lds_dwordx4 v[184:185], off
	v_lshl_add_u64 v[184:185], s[28:29], 0, v[132:133]
	s_mov_b32 m0, s30
	s_nop 0
	global_load_lds_dwordx4 v[184:185], off
	v_lshl_add_u64 v[184:185], s[28:29], 0, v[128:129]
	s_add_i32 m0, s30, 0x2000
	s_nop 0
	global_load_lds_dwordx4 v[184:185], off
	v_lshl_add_u64 v[184:185], v[222:223], 0, s[8:9]
	s_mov_b32 m0, s43
	s_nop 0
	global_load_lds_dwordx4 v[184:185], off
	v_lshl_add_u64 v[184:185], v[224:225], 0, s[8:9]
	s_mov_b32 m0, s44
	s_nop 0
	global_load_lds_dwordx4 v[184:185], off
	s_waitcnt vmcnt(8)
	s_waitcnt lgkmcnt(0)
	s_barrier
	s_setprio 1
	v_mfma_f32_16x16x32_bf16 v[60:63], v[152:155], v[188:191], v[60:63]
	v_mfma_f32_16x16x32_bf16 v[52:55], v[160:163], v[188:191], v[52:55]
	v_mfma_f32_16x16x32_bf16 v[44:47], v[152:155], v[196:199], v[44:47]
	v_mfma_f32_16x16x32_bf16 v[36:39], v[160:163], v[196:199], v[36:39]
	v_mfma_f32_16x16x32_bf16 v[28:31], v[152:155], v[204:207], v[28:31]
	v_mfma_f32_16x16x32_bf16 v[20:23], v[160:163], v[204:207], v[20:23]
	v_mfma_f32_16x16x32_bf16 v[12:15], v[152:155], v[212:215], v[12:15]
	v_mfma_f32_16x16x32_bf16 v[4:7], v[160:163], v[212:215], v[4:7]
	v_mfma_f32_16x16x32_bf16 v[60:63], v[156:159], v[192:195], v[60:63]
	v_mfma_f32_16x16x32_bf16 v[52:55], v[164:167], v[192:195], v[52:55]
	v_mfma_f32_16x16x32_bf16 v[44:47], v[156:159], v[200:203], v[44:47]
	v_mfma_f32_16x16x32_bf16 v[36:39], v[164:167], v[200:203], v[36:39]
	v_mfma_f32_16x16x32_bf16 v[28:31], v[156:159], v[208:211], v[28:31]
	v_mfma_f32_16x16x32_bf16 v[20:23], v[164:167], v[208:211], v[20:23]
	v_mfma_f32_16x16x32_bf16 v[12:15], v[156:159], v[216:219], v[12:15]
	v_mfma_f32_16x16x32_bf16 v[4:7], v[164:167], v[216:219], v[4:7]
	s_setprio 1
	v_mfma_f32_16x16x32_bf16 v[56:59], v[168:171], v[188:191], v[56:59]
	v_mfma_f32_16x16x32_bf16 v[48:51], v[176:179], v[188:191], v[48:51]
	v_mfma_f32_16x16x32_bf16 v[40:43], v[168:171], v[196:199], v[40:43]
	v_mfma_f32_16x16x32_bf16 v[32:35], v[176:179], v[196:199], v[32:35]
	v_mfma_f32_16x16x32_bf16 v[24:27], v[168:171], v[204:207], v[24:27]
	v_mfma_f32_16x16x32_bf16 v[16:19], v[176:179], v[204:207], v[16:19]
	v_mfma_f32_16x16x32_bf16 v[8:11], v[168:171], v[212:215], v[8:11]
	v_mfma_f32_16x16x32_bf16 v[0:3], v[176:179], v[212:215], v[0:3]
	v_mfma_f32_16x16x32_bf16 v[56:59], v[172:175], v[192:195], v[56:59]
	v_mfma_f32_16x16x32_bf16 v[48:51], v[180:183], v[192:195], v[48:51]
	v_mfma_f32_16x16x32_bf16 v[40:43], v[172:175], v[200:203], v[40:43]
	v_mfma_f32_16x16x32_bf16 v[32:35], v[180:183], v[200:203], v[32:35]
	v_mfma_f32_16x16x32_bf16 v[24:27], v[172:175], v[208:211], v[24:27]
	v_mfma_f32_16x16x32_bf16 v[16:19], v[180:183], v[208:211], v[16:19]
	v_mfma_f32_16x16x32_bf16 v[8:11], v[172:175], v[216:219], v[8:11]
	v_mfma_f32_16x16x32_bf16 v[0:3], v[180:183], v[216:219], v[0:3]
	s_barrier
	s_setprio 0
	s_add_i32 s68, s68, 2
	s_add_u32 s26, s26, 0x100
	s_addc_u32 s27, s27, 0
	s_add_u32 s66, s66, 0x100
	s_addc_u32 s67, s67, 0
	s_cmp_gt_u32 s68, 13
	s_cbranch_scc0 .LBB0_244
	s_and_b64 vcc, exec, s[10:11]
	s_cbranch_vccz .LBB0_247
	s_barrier

; #define PG8_STAGE(bufoff, gbase, voff) do { _Pragma("unroll") for (int _i = 0; _i < 2; ++_i) \
;         __builtin_amdgcn_global_load_lds((const unsigned*)((const char*)(gbase) + (voff)[_i]), (PG8_LAS unsigned*)(lds + (bufoff) + ldsw + _i * 8192), 16, 0, 0); } while (0)
; #define PG8_LDA(dst, b, h) do { _Pragma("unroll") for (int m = 0; m < 4; ++m) _Pragma("unroll") for (int k = 0; k < 2; ++k) dst[m][k] = *(const PG8_LAS bf16x8*)(lds + PG8_SA(b, h) + aoff + m * 2048 + k * 1024); } while (0)
; #define PG8_LDB(dst, b, h) do { _Pragma("unroll") for (int n = 0; n < 2; ++n) _Pragma("unroll") for (int k = 0; k < 2; ++k) dst[n][k] = *(const PG8_LAS bf16x8*)(lds + PG8_SB(b, h) + boff + n * 2048 + k * 1024); } while (0)
; #define PG8_MMA(ai, bj, At, Bt) do { __builtin_amdgcn_s_setprio(1); _Pragma("unroll") for (int m = 0; m < 4; ++m) _Pragma("unroll") for (int n = 0; n < 2; ++n) _Pragma("unroll") for (int k = 0; k < 2; ++k) \
;         acc[ai][bj][m][n] = __builtin_amdgcn_mfma_f32_16x16x32_bf16(Bt[n][k], At[m][k], acc[ai][bj][m][n], 0, 0, 0); __builtin_amdgcn_s_setprio(0); } while (0)
; #define PG8_WAIT_V(n) asm volatile("s_waitcnt vmcnt(" #n ")" ::: "memory")
; #define PG8_WAIT_L(n) asm volatile("s_waitcnt lgkmcnt(" #n ")" ::: "memory")
; #define PG8_BAR __builtin_amdgcn_s_barrier()
; template <class Epi, class Sched, bool ALIGN_EPI = false, bool SP2 = false>
; __device__ __forceinline__ void gemm_phase(PG8_LAS unsigned char* lds, const Gemm g, const Sched& S, const Epi& E) {
;     ...
;             const char* a1 = cA + (size_t)(t + 1) * kstep;
;             const char* a2 = last ? nA : cA + (size_t)(t + 2) * kstep; const char* b2 = last ? nB : cB + (size_t)(t + 2) * kstep;
;             const char* a3 = a2 + kstep; const char* b3 = b2 + kstep;
;             if (last && has_next) S.a_ready(nxt);
;             if constexpr (SP2) {
;             PG8_LDB(B0, 0, 0); PG8_LDB(B1, 0, 1); PG8_SCHED; PG8_LDA(At, 0, 0); PG8_STAGE(PG8_SA(1, 1), a1 + hstepA, voffA);
;             PG8_WAIT_V(8); PG8_WAIT_L(0); PG8_BAR; PG8_MMA(0, 0, At, B0); PG8_MMA(0, 1, At, B1); PG8_BAR; PG8_SCHED;
;             PG8_LDA(At, 0, 1); PG8_STAGE(PG8_SB(0, 0), b2, voffB); PG8_STAGE(PG8_SB(0, 1), b2 + hstepB, voffB); PG8_STAGE(PG8_SA(0, 0), a2, voffA);
;             PG8_WAIT_V(8); PG8_WAIT_L(0); PG8_BAR; PG8_MMA(1, 0, At, B0); PG8_MMA(1, 1, At, B1); PG8_BAR; PG8_SCHED;
.LBB0_318:
	ds_read_b128 v[128:131], v191
	ds_read_b128 v[132:135], v191 offset:1024
	ds_read_b128 v[136:139], v191 offset:2048
	ds_read_b128 v[140:143], v191 offset:3072
	ds_read_b128 v[144:147], v192
	ds_read_b128 v[148:151], v192 offset:1024
	ds_read_b128 v[168:171], v192 offset:2048
	ds_read_b128 v[172:175], v192 offset:3072
	s_add_u32 s28, s26, 0x100
	s_addc_u32 s29, s27, 0
	s_cmp_eq_u32 s72, 40
	s_cselect_b32 s35, s11, s29
	s_cselect_b32 s34, s10, s28
	s_cselect_b32 s31, s23, s71
	s_cselect_b32 s30, s22, s70
	v_lshl_add_u64 v[184:185], s[26:27], 0, v[160:161]
	s_add_i32 m0, s39, 0xc000
	ds_read_b128 v[176:179], v193
	ds_read_b128 v[180:183], v193 offset:1024
	ds_read_b128 v[196:199], v193 offset:2048
	ds_read_b128 v[200:203], v193 offset:3072
	ds_read_b128 v[204:207], v193 offset:4096
	ds_read_b128 v[208:211], v193 offset:5120
	ds_read_b128 v[212:215], v193 offset:6144
	ds_read_b128 v[216:219], v193 offset:7168
	global_load_lds_dwordx4 v[184:185], off
	v_lshl_add_u64 v[184:185], s[26:27], 0, v[162:163]
	s_add_i32 m0, s39, 0xe000
	s_nop 0
	global_load_lds_dwordx4 v[184:185], off
	s_waitcnt vmcnt(8)
	s_waitcnt lgkmcnt(0)
	s_barrier
	s_setprio 1
	v_mfma_f32_16x16x32_bf16 v[124:127], v[128:131], v[176:179], v[124:127]
	v_mfma_f32_16x16x32_bf16 v[120:123], v[136:139], v[176:179], v[120:123]
	v_mfma_f32_16x16x32_bf16 v[108:111], v[128:131], v[196:199], v[108:111]
	v_mfma_f32_16x16x32_bf16 v[104:107], v[136:139], v[196:199], v[104:107]
	v_mfma_f32_16x16x32_bf16 v[92:95], v[128:131], v[204:207], v[92:95]
	v_mfma_f32_16x16x32_bf16 v[88:91], v[136:139], v[204:207], v[88:91]
	v_mfma_f32_16x16x32_bf16 v[76:79], v[128:131], v[212:215], v[76:79]
	v_mfma_f32_16x16x32_bf16 v[72:75], v[136:139], v[212:215], v[72:75]
	v_mfma_f32_16x16x32_bf16 v[124:127], v[132:135], v[180:183], v[124:127]
	v_mfma_f32_16x16x32_bf16 v[120:123], v[140:143], v[180:183], v[120:123]
	v_mfma_f32_16x16x32_bf16 v[108:111], v[132:135], v[200:203], v[108:111]
	v_mfma_f32_16x16x32_bf16 v[104:107], v[140:143], v[200:203], v[104:107]
	v_mfma_f32_16x16x32_bf16 v[92:95], v[132:135], v[208:211], v[92:95]
	v_mfma_f32_16x16x32_bf16 v[88:91], v[140:143], v[208:211], v[88:91]
	v_mfma_f32_16x16x32_bf16 v[76:79], v[132:135], v[216:219], v[76:79]
	v_mfma_f32_16x16x32_bf16 v[72:75], v[140:143], v[216:219], v[72:75]
	s_setprio 1
	v_mfma_f32_16x16x32_bf16 v[116:119], v[144:147], v[176:179], v[116:119]
	v_mfma_f32_16x16x32_bf16 v[112:115], v[168:171], v[176:179], v[112:115]
	v_mfma_f32_16x16x32_bf16 v[100:103], v[144:147], v[196:199], v[100:103]
	v_mfma_f32_16x16x32_bf16 v[96:99], v[168:171], v[196:199], v[96:99]
	v_mfma_f32_16x16x32_bf16 v[84:87], v[144:147], v[204:207], v[84:87]
	v_mfma_f32_16x16x32_bf16 v[80:83], v[168:171], v[204:207], v[80:83]
	v_mfma_f32_16x16x32_bf16 v[68:71], v[144:147], v[212:215], v[68:71]
	v_mfma_f32_16x16x32_bf16 v[64:67], v[168:171], v[212:215], v[64:67]
	v_mfma_f32_16x16x32_bf16 v[116:119], v[148:151], v[180:183], v[116:119]
	v_mfma_f32_16x16x32_bf16 v[112:115], v[172:175], v[180:183], v[112:115]
	v_mfma_f32_16x16x32_bf16 v[100:103], v[148:151], v[200:203], v[100:103]
	v_mfma_f32_16x16x32_bf16 v[96:99], v[172:175], v[200:203], v[96:99]
	v_mfma_f32_16x16x32_bf16 v[84:87], v[148:151], v[208:211], v[84:87]
	v_mfma_f32_16x16x32_bf16 v[80:83], v[172:175], v[208:211], v[80:83]
	v_mfma_f32_16x16x32_bf16 v[68:71], v[148:151], v[216:219], v[68:71]
	v_mfma_f32_16x16x32_bf16 v[64:67], v[172:175], v[216:219], v[64:67]
	s_barrier
	s_setprio 0
	s_add_i32 s26, s49, s38
	v_lshl_add_u64 v[184:185], s[30:31], 0, v[154:155]
	s_mov_b32 m0, s26
	ds_read_b128 v[176:179], v193 offset:16384
	ds_read_b128 v[180:183], v193 offset:17408
	ds_read_b128 v[196:199], v193 offset:18432
	ds_read_b128 v[200:203], v193 offset:19456
	ds_read_b128 v[204:207], v193 offset:20480
	ds_read_b128 v[208:211], v193 offset:21504
	ds_read_b128 v[212:215], v193 offset:22528
	ds_read_b128 v[216:219], v193 offset:23552
	global_load_lds_dwordx4 v[184:185], off
	s_add_i32 m0, s26, 0x2000
	s_add_u32 s26, s30, 0xb0000
	v_lshl_add_u64 v[220:221], s[30:31], 0, v[158:159]
	s_addc_u32 s27, s31, 0
	s_add_i32 s58, s62, s38
	global_load_lds_dwordx4 v[220:221], off
	v_lshl_add_u64 v[222:223], s[26:27], 0, v[154:155]
	s_mov_b32 m0, s58
	v_lshl_add_u64 v[224:225], s[34:35], 0, v[156:157]
	global_load_lds_dwordx4 v[222:223], off
	v_lshl_add_u64 v[222:223], s[26:27], 0, v[158:159]
	s_add_i32 m0, s58, 0x2000
	s_nop 0
	global_load_lds_dwordx4 v[222:223], off
	v_lshl_add_u64 v[222:223], s[34:35], 0, v[152:153]
	s_mov_b32 m0, s39
	s_nop 0
	global_load_lds_dwordx4 v[222:223], off
	s_mov_b32 m0, s40
	s_nop 0
	global_load_lds_dwordx4 v[224:225], off
	s_waitcnt vmcnt(8)
	s_waitcnt lgkmcnt(0)
	s_barrier
; #define PG8_STAGE(bufoff, gbase, voff) do { _Pragma("unroll") for (int _i = 0; _i < 2; ++_i) \
;         __builtin_amdgcn_global_load_lds((const unsigned*)((const char*)(gbase) + (voff)[_i]), (PG8_LAS unsigned*)(lds + (bufoff) + ldsw + _i * 8192), 16, 0, 0); } while (0)
; #define PG8_LDA(dst, b, h) do { _Pragma("unroll") for (int m = 0; m < 4; ++m) _Pragma("unroll") for (int k = 0; k < 2; ++k) dst[m][k] = *(const PG8_LAS bf16x8*)(lds + PG8_SA(b, h) + aoff + m * 2048 + k * 1024); } while (0)
; #define PG8_LDB(dst, b, h) do { _Pragma("unroll") for (int n = 0; n < 2; ++n) _Pragma("unroll") for (int k = 0; k < 2; ++k) dst[n][k] = *(const PG8_LAS bf16x8*)(lds + PG8_SB(b, h) + boff + n * 2048 + k * 1024); } while (0)
; #define PG8_MMA(ai, bj, At, Bt) do { __builtin_amdgcn_s_setprio(1); _Pragma("unroll") for (int m = 0; m < 4; ++m) _Pragma("unroll") for (int n = 0; n < 2; ++n) _Pragma("unroll") for (int k = 0; k < 2; ++k) \
;         acc[ai][bj][m][n] = __builtin_amdgcn_mfma_f32_16x16x32_bf16(Bt[n][k], At[m][k], acc[ai][bj][m][n], 0, 0, 0); __builtin_amdgcn_s_setprio(0); } while (0)
; #define PG8_WAIT_V(n) asm volatile("s_waitcnt vmcnt(" #n ")" ::: "memory")
; #define PG8_WAIT_L(n) asm volatile("s_waitcnt lgkmcnt(" #n ")" ::: "memory")
; #define PG8_BAR __builtin_amdgcn_s_barrier()
; #define PG8_SCHED __builtin_amdgcn_sched_barrier(0)
; template <class Epi, class Sched, bool ALIGN_EPI = false, bool SP2 = false>
; __device__ __forceinline__ void gemm_phase(PG8_LAS unsigned char* lds, const Gemm g, const Sched& S, const Epi& E) {
;     ...
;             PG8_WAIT_V(8); PG8_WAIT_L(0); PG8_BAR; PG8_MMA(1, 0, At, B0); PG8_MMA(1, 1, At, B1); PG8_BAR; PG8_SCHED;
;             PG8_LDB(B0, 1, 0); PG8_LDB(B1, 1, 1); PG8_SCHED; PG8_LDA(At, 1, 0); PG8_STAGE(PG8_SA(0, 1), a2 + hstepA, voffA);
;             PG8_WAIT_V(8); PG8_WAIT_L(0); PG8_BAR; PG8_MMA(0, 0, At, B0); PG8_MMA(0, 1, At, B1); PG8_BAR; PG8_SCHED;
	s_setprio 1
	v_mfma_f32_16x16x32_bf16 v[60:63], v[128:131], v[176:179], v[60:63]
	v_mfma_f32_16x16x32_bf16 v[56:59], v[136:139], v[176:179], v[56:59]
	v_mfma_f32_16x16x32_bf16 v[44:47], v[128:131], v[196:199], v[44:47]
	v_mfma_f32_16x16x32_bf16 v[40:43], v[136:139], v[196:199], v[40:43]
	v_mfma_f32_16x16x32_bf16 v[28:31], v[128:131], v[204:207], v[28:31]
	v_mfma_f32_16x16x32_bf16 v[24:27], v[136:139], v[204:207], v[24:27]
	v_mfma_f32_16x16x32_bf16 v[12:15], v[128:131], v[212:215], v[12:15]
	v_mfma_f32_16x16x32_bf16 v[8:11], v[136:139], v[212:215], v[8:11]
	v_mfma_f32_16x16x32_bf16 v[60:63], v[132:135], v[180:183], v[60:63]
	v_mfma_f32_16x16x32_bf16 v[56:59], v[140:143], v[180:183], v[56:59]
	v_mfma_f32_16x16x32_bf16 v[44:47], v[132:135], v[200:203], v[44:47]
	v_mfma_f32_16x16x32_bf16 v[40:43], v[140:143], v[200:203], v[40:43]
	v_mfma_f32_16x16x32_bf16 v[28:31], v[132:135], v[208:211], v[28:31]
	v_mfma_f32_16x16x32_bf16 v[24:27], v[140:143], v[208:211], v[24:27]
	v_mfma_f32_16x16x32_bf16 v[12:15], v[132:135], v[216:219], v[12:15]
	v_mfma_f32_16x16x32_bf16 v[8:11], v[140:143], v[216:219], v[8:11]
	s_setprio 1
	v_mfma_f32_16x16x32_bf16 v[52:55], v[144:147], v[176:179], v[52:55]
	v_mfma_f32_16x16x32_bf16 v[48:51], v[168:171], v[176:179], v[48:51]
	v_mfma_f32_16x16x32_bf16 v[36:39], v[144:147], v[196:199], v[36:39]
	v_mfma_f32_16x16x32_bf16 v[32:35], v[168:171], v[196:199], v[32:35]
	v_mfma_f32_16x16x32_bf16 v[20:23], v[144:147], v[204:207], v[20:23]
	v_mfma_f32_16x16x32_bf16 v[16:19], v[168:171], v[204:207], v[16:19]
	v_mfma_f32_16x16x32_bf16 v[4:7], v[144:147], v[212:215], v[4:7]
	v_mfma_f32_16x16x32_bf16 v[0:3], v[168:171], v[212:215], v[0:3]
	v_mfma_f32_16x16x32_bf16 v[52:55], v[148:151], v[180:183], v[52:55]
	v_mfma_f32_16x16x32_bf16 v[48:51], v[172:175], v[180:183], v[48:51]
	v_mfma_f32_16x16x32_bf16 v[36:39], v[148:151], v[200:203], v[36:39]
	v_mfma_f32_16x16x32_bf16 v[32:35], v[172:175], v[200:203], v[32:35]
	v_mfma_f32_16x16x32_bf16 v[20:23], v[148:151], v[208:211], v[20:23]
	v_mfma_f32_16x16x32_bf16 v[16:19], v[172:175], v[208:211], v[16:19]
	v_mfma_f32_16x16x32_bf16 v[4:7], v[148:151], v[216:219], v[4:7]
	v_mfma_f32_16x16x32_bf16 v[0:3], v[172:175], v[216:219], v[0:3]
	s_barrier
	s_setprio 0
	s_add_i32 s58, 0, 0x18000
	s_add_i32 s59, 0, 0x1c000
	v_add_u32_e32 v140, s58, v189
	v_add_u32_e32 v172, s59, v189
	ds_read_b128 v[128:131], v140
	ds_read_b128 v[132:135], v140 offset:1024
	ds_read_b128 v[136:139], v140 offset:2048
	ds_read_b128 v[140:143], v140 offset:3072
	ds_read_b128 v[144:147], v172
	ds_read_b128 v[148:151], v172 offset:1024
	ds_read_b128 v[168:171], v172 offset:2048
	ds_read_b128 v[172:175], v172 offset:3072
	s_add_u32 s26, s34, 0xb0000
	s_addc_u32 s27, s35, 0
	s_mov_b32 m0, s41
	v_lshl_add_u64 v[226:227], s[26:27], 0, v[152:153]
	ds_read_b128 v[176:179], v193 offset:32768
	ds_read_b128 v[180:183], v193 offset:33792
	ds_read_b128 v[196:199], v193 offset:34816
	ds_read_b128 v[200:203], v193 offset:35840
	ds_read_b128 v[204:207], v193 offset:36864
	ds_read_b128 v[208:211], v193 offset:37888
	ds_read_b128 v[212:215], v193 offset:38912
	ds_read_b128 v[216:219], v193 offset:39936
	global_load_lds_dwordx4 v[226:227], off
	v_lshl_add_u64 v[226:227], s[26:27], 0, v[156:157]
	s_mov_b32 m0, s42
	s_nop 0
	global_load_lds_dwordx4 v[226:227], off
	s_waitcnt vmcnt(8)
	s_waitcnt lgkmcnt(0)
	s_barrier
	s_setprio 1
	v_mfma_f32_16x16x32_bf16 v[124:127], v[128:131], v[176:179], v[124:127]
	v_mfma_f32_16x16x32_bf16 v[120:123], v[136:139], v[176:179], v[120:123]
	v_mfma_f32_16x16x32_bf16 v[108:111], v[128:131], v[196:199], v[108:111]
	v_mfma_f32_16x16x32_bf16 v[104:107], v[136:139], v[196:199], v[104:107]
	v_mfma_f32_16x16x32_bf16 v[92:95], v[128:131], v[204:207], v[92:95]
	v_mfma_f32_16x16x32_bf16 v[88:91], v[136:139], v[204:207], v[88:91]
	v_mfma_f32_16x16x32_bf16 v[76:79], v[128:131], v[212:215], v[76:79]
	v_mfma_f32_16x16x32_bf16 v[72:75], v[136:139], v[212:215], v[72:75]
	v_mfma_f32_16x16x32_bf16 v[124:127], v[132:135], v[180:183], v[124:127]
	v_mfma_f32_16x16x32_bf16 v[120:123], v[140:143], v[180:183], v[120:123]
	v_mfma_f32_16x16x32_bf16 v[108:111], v[132:135], v[200:203], v[108:111]
	v_mfma_f32_16x16x32_bf16 v[104:107], v[140:143], v[200:203], v[104:107]
	v_mfma_f32_16x16x32_bf16 v[92:95], v[132:135], v[208:211], v[92:95]
	v_mfma_f32_16x16x32_bf16 v[88:91], v[140:143], v[208:211], v[88:91]
	v_mfma_f32_16x16x32_bf16 v[76:79], v[132:135], v[216:219], v[76:79]
	v_mfma_f32_16x16x32_bf16 v[72:75], v[140:143], v[216:219], v[72:75]
	s_setprio 1
	v_mfma_f32_16x16x32_bf16 v[116:119], v[144:147], v[176:179], v[116:119]
	v_mfma_f32_16x16x32_bf16 v[112:115], v[168:171], v[176:179], v[112:115]
	v_mfma_f32_16x16x32_bf16 v[100:103], v[144:147], v[196:199], v[100:103]
	v_mfma_f32_16x16x32_bf16 v[96:99], v[168:171], v[196:199], v[96:99]
	v_mfma_f32_16x16x32_bf16 v[84:87], v[144:147], v[204:207], v[84:87]
	v_mfma_f32_16x16x32_bf16 v[80:83], v[168:171], v[204:207], v[80:83]
	v_mfma_f32_16x16x32_bf16 v[68:71], v[144:147], v[212:215], v[68:71]
	v_mfma_f32_16x16x32_bf16 v[64:67], v[168:171], v[212:215], v[64:67]
	v_mfma_f32_16x16x32_bf16 v[116:119], v[148:151], v[180:183], v[116:119]
	v_mfma_f32_16x16x32_bf16 v[112:115], v[172:175], v[180:183], v[112:115]
	v_mfma_f32_16x16x32_bf16 v[100:103], v[148:151], v[200:203], v[100:103]
	v_mfma_f32_16x16x32_bf16 v[96:99], v[172:175], v[200:203], v[96:99]
	v_mfma_f32_16x16x32_bf16 v[84:87], v[148:151], v[208:211], v[84:87]
	v_mfma_f32_16x16x32_bf16 v[80:83], v[172:175], v[208:211], v[80:83]
	v_mfma_f32_16x16x32_bf16 v[68:71], v[148:151], v[216:219], v[68:71]
	v_mfma_f32_16x16x32_bf16 v[64:67], v[172:175], v[216:219], v[64:67]
	s_barrier
; #define PG8_STAGE(bufoff, gbase, voff) do { _Pragma("unroll") for (int _i = 0; _i < 2; ++_i) \
;         __builtin_amdgcn_global_load_lds((const unsigned*)((const char*)(gbase) + (voff)[_i]), (PG8_LAS unsigned*)(lds + (bufoff) + ldsw + _i * 8192), 16, 0, 0); } while (0)
; #define PG8_LDA(dst, b, h) do { _Pragma("unroll") for (int m = 0; m < 4; ++m) _Pragma("unroll") for (int k = 0; k < 2; ++k) dst[m][k] = *(const PG8_LAS bf16x8*)(lds + PG8_SA(b, h) + aoff + m * 2048 + k * 1024); } while (0)
; #define PG8_MMA(ai, bj, At, Bt) do { __builtin_amdgcn_s_setprio(1); _Pragma("unroll") for (int m = 0; m < 4; ++m) _Pragma("unroll") for (int n = 0; n < 2; ++n) _Pragma("unroll") for (int k = 0; k < 2; ++k) \
;         acc[ai][bj][m][n] = __builtin_amdgcn_mfma_f32_16x16x32_bf16(Bt[n][k], At[m][k], acc[ai][bj][m][n], 0, 0, 0); __builtin_amdgcn_s_setprio(0); } while (0)
; #define PG8_WAIT_V(n) asm volatile("s_waitcnt vmcnt(" #n ")" ::: "memory")
; #define PG8_WAIT_L(n) asm volatile("s_waitcnt lgkmcnt(" #n ")" ::: "memory")
; #define PG8_BAR __builtin_amdgcn_s_barrier()
; #define PG8_SCHED __builtin_amdgcn_sched_barrier(0)
; template <class Epi, class Sched, bool ALIGN_EPI = false, bool SP2 = false>
; __device__ __forceinline__ void gemm_phase(PG8_LAS unsigned char* lds, const Gemm g, const Sched& S, const Epi& E) {
;     ...
;         for (int t = 0; t < nt; t += 2) {
;             const bool last = (t == nt - 2);
;     ...
;             PG8_LDA(At, 1, 1); PG8_STAGE(PG8_SB(1, 0), b3, voffB); PG8_STAGE(PG8_SB(1, 1), b3 + hstepB, voffB); PG8_STAGE(PG8_SA(1, 0), a3, voffA);
;             PG8_WAIT_V(8); PG8_WAIT_L(0); PG8_BAR; PG8_MMA(1, 0, At, B0); PG8_MMA(1, 1, At, B1); PG8_BAR; PG8_SCHED;
	s_setprio 0
	s_add_i32 s26, s58, s38
	v_lshl_add_u64 v[184:185], v[184:185], 0, s[14:15]
	s_mov_b32 m0, s26
	ds_read_b128 v[176:179], v193 offset:49152
	ds_read_b128 v[180:183], v193 offset:50176
	ds_read_b128 v[196:199], v193 offset:51200
	ds_read_b128 v[200:203], v193 offset:52224
	ds_read_b128 v[204:207], v193 offset:53248
	ds_read_b128 v[208:211], v193 offset:54272
	ds_read_b128 v[212:215], v193 offset:55296
	ds_read_b128 v[216:219], v193 offset:56320
	global_load_lds_dwordx4 v[184:185], off
	s_add_i32 m0, s26, 0x2000
	s_add_u32 s26, s30, 0xb0080
	v_lshl_add_u64 v[184:185], v[220:221], 0, s[14:15]
	s_addc_u32 s27, s31, 0
	s_add_i32 s30, s59, s38
	global_load_lds_dwordx4 v[184:185], off
	v_lshl_add_u64 v[184:185], s[26:27], 0, v[154:155]
	s_mov_b32 m0, s30
	s_nop 0
	global_load_lds_dwordx4 v[184:185], off
	v_lshl_add_u64 v[184:185], s[26:27], 0, v[158:159]
	s_add_i32 m0, s30, 0x2000
	s_nop 0
	global_load_lds_dwordx4 v[184:185], off
	v_lshl_add_u64 v[184:185], v[222:223], 0, s[14:15]
	s_mov_b32 m0, s44
	s_nop 0
	global_load_lds_dwordx4 v[184:185], off
	v_lshl_add_u64 v[184:185], v[224:225], 0, s[14:15]
	s_mov_b32 m0, s45
	s_nop 0
	global_load_lds_dwordx4 v[184:185], off
	s_waitcnt vmcnt(8)
	s_waitcnt lgkmcnt(0)
	s_barrier
	s_setprio 1
	v_mfma_f32_16x16x32_bf16 v[60:63], v[128:131], v[176:179], v[60:63]
	v_mfma_f32_16x16x32_bf16 v[56:59], v[136:139], v[176:179], v[56:59]
	v_mfma_f32_16x16x32_bf16 v[44:47], v[128:131], v[196:199], v[44:47]
	v_mfma_f32_16x16x32_bf16 v[40:43], v[136:139], v[196:199], v[40:43]
	v_mfma_f32_16x16x32_bf16 v[28:31], v[128:131], v[204:207], v[28:31]
	v_mfma_f32_16x16x32_bf16 v[24:27], v[136:139], v[204:207], v[24:27]
	v_mfma_f32_16x16x32_bf16 v[12:15], v[128:131], v[212:215], v[12:15]
	v_mfma_f32_16x16x32_bf16 v[8:11], v[136:139], v[212:215], v[8:11]
	v_mfma_f32_16x16x32_bf16 v[60:63], v[132:135], v[180:183], v[60:63]
	v_mfma_f32_16x16x32_bf16 v[56:59], v[140:143], v[180:183], v[56:59]
	v_mfma_f32_16x16x32_bf16 v[44:47], v[132:135], v[200:203], v[44:47]
	v_mfma_f32_16x16x32_bf16 v[40:43], v[140:143], v[200:203], v[40:43]
	v_mfma_f32_16x16x32_bf16 v[28:31], v[132:135], v[208:211], v[28:31]
	v_mfma_f32_16x16x32_bf16 v[24:27], v[140:143], v[208:211], v[24:27]
	v_mfma_f32_16x16x32_bf16 v[12:15], v[132:135], v[216:219], v[12:15]
	v_mfma_f32_16x16x32_bf16 v[8:11], v[140:143], v[216:219], v[8:11]
	s_setprio 1
	v_mfma_f32_16x16x32_bf16 v[52:55], v[144:147], v[176:179], v[52:55]
	v_mfma_f32_16x16x32_bf16 v[48:51], v[168:171], v[176:179], v[48:51]
	v_mfma_f32_16x16x32_bf16 v[36:39], v[144:147], v[196:199], v[36:39]
	v_mfma_f32_16x16x32_bf16 v[32:35], v[168:171], v[196:199], v[32:35]
	v_mfma_f32_16x16x32_bf16 v[20:23], v[144:147], v[204:207], v[20:23]
	v_mfma_f32_16x16x32_bf16 v[16:19], v[168:171], v[204:207], v[16:19]
	v_mfma_f32_16x16x32_bf16 v[4:7], v[144:147], v[212:215], v[4:7]
	v_mfma_f32_16x16x32_bf16 v[0:3], v[168:171], v[212:215], v[0:3]
	v_mfma_f32_16x16x32_bf16 v[52:55], v[148:151], v[180:183], v[52:55]
	v_mfma_f32_16x16x32_bf16 v[48:51], v[172:175], v[180:183], v[48:51]
	v_mfma_f32_16x16x32_bf16 v[36:39], v[148:151], v[200:203], v[36:39]
	v_mfma_f32_16x16x32_bf16 v[32:35], v[172:175], v[200:203], v[32:35]
	v_mfma_f32_16x16x32_bf16 v[20:23], v[148:151], v[208:211], v[20:23]
	v_mfma_f32_16x16x32_bf16 v[16:19], v[172:175], v[208:211], v[16:19]
	v_mfma_f32_16x16x32_bf16 v[4:7], v[148:151], v[216:219], v[4:7]
	v_mfma_f32_16x16x32_bf16 v[0:3], v[172:175], v[216:219], v[0:3]
	s_barrier
	s_setprio 0
	s_add_i32 s72, s72, 2
	s_add_u32 s70, s70, 0x100
	s_addc_u32 s71, s71, 0
	s_cmp_gt_u32 s72, 41
	s_mov_b64 s[26:27], s[28:29]
	s_cbranch_scc0 .LBB0_318
	s_and_b64 vcc, exec, s[20:21]
	s_cbranch_vccz .LBB0_321
	s_barrier

; #define PG8_STAGE(bufoff, gbase, voff) do { _Pragma("unroll") for (int _i = 0; _i < 2; ++_i) \
;         __builtin_amdgcn_global_load_lds((const unsigned*)((const char*)(gbase) + (voff)[_i]), (PG8_LAS unsigned*)(lds + (bufoff) + ldsw + _i * 8192), 16, 0, 0); } while (0)
; #define PG8_LDA(dst, b, h) do { _Pragma("unroll") for (int m = 0; m < 4; ++m) _Pragma("unroll") for (int k = 0; k < 2; ++k) dst[m][k] = *(const PG8_LAS bf16x8*)(lds + PG8_SA(b, h) + aoff + m * 2048 + k * 1024); } while (0)
; #define PG8_LDB(dst, b, h) do { _Pragma("unroll") for (int n = 0; n < 2; ++n) _Pragma("unroll") for (int k = 0; k < 2; ++k) dst[n][k] = *(const PG8_LAS bf16x8*)(lds + PG8_SB(b, h) + boff + n * 2048 + k * 1024); } while (0)
; #define PG8_MMA(ai, bj, At, Bt) do { __builtin_amdgcn_s_setprio(1); _Pragma("unroll") for (int m = 0; m < 4; ++m) _Pragma("unroll") for (int n = 0; n < 2; ++n) _Pragma("unroll") for (int k = 0; k < 2; ++k) \
;         acc[ai][bj][m][n] = __builtin_amdgcn_mfma_f32_16x16x32_bf16(Bt[n][k], At[m][k], acc[ai][bj][m][n], 0, 0, 0); __builtin_amdgcn_s_setprio(0); } while (0)
; #define PG8_WAIT_V(n) asm volatile("s_waitcnt vmcnt(" #n ")" ::: "memory")
; #define PG8_WAIT_L(n) asm volatile("s_waitcnt lgkmcnt(" #n ")" ::: "memory")
; #define PG8_BAR __builtin_amdgcn_s_barrier()
; template <class Epi, class Sched, bool ALIGN_EPI = false, bool SP2 = false>
; __device__ __forceinline__ void gemm_phase(PG8_LAS unsigned char* lds, const Gemm g, const Sched& S, const Epi& E) {
;     ...
;             const char* a1 = cA + (size_t)(t + 1) * kstep;
;             const char* a2 = last ? nA : cA + (size_t)(t + 2) * kstep; const char* b2 = last ? nB : cB + (size_t)(t + 2) * kstep;
;             const char* a3 = a2 + kstep; const char* b3 = b2 + kstep;
;             if (last && has_next) S.a_ready(nxt);
;             if constexpr (SP2) {
;             PG8_LDB(B0, 0, 0); PG8_LDB(B1, 0, 1); PG8_SCHED; PG8_LDA(At, 0, 0); PG8_STAGE(PG8_SA(1, 1), a1 + hstepA, voffA);
;             PG8_WAIT_V(8); PG8_WAIT_L(0); PG8_BAR; PG8_MMA(0, 0, At, B0); PG8_MMA(0, 1, At, B1); PG8_BAR; PG8_SCHED;
;             PG8_LDA(At, 0, 1); PG8_STAGE(PG8_SB(0, 0), b2, voffB); PG8_STAGE(PG8_SB(0, 1), b2 + hstepB, voffB); PG8_STAGE(PG8_SA(0, 0), a2, voffA);
;             PG8_WAIT_V(8); PG8_WAIT_L(0); PG8_BAR; PG8_MMA(1, 0, At, B0); PG8_MMA(1, 1, At, B1); PG8_BAR; PG8_SCHED;
.LBB0_404:
	ds_read_b128 v[152:155], v165
	ds_read_b128 v[156:159], v165 offset:1024
	ds_read_b128 v[178:181], v165 offset:2048
	ds_read_b128 v[182:185], v165 offset:3072
	ds_read_b128 v[188:191], v166
	ds_read_b128 v[192:195], v166 offset:1024
	ds_read_b128 v[196:199], v166 offset:2048
	ds_read_b128 v[200:203], v166 offset:3072
	s_add_u32 s46, s14, 0xfffc0080
	s_addc_u32 s47, s15, -1
	s_cmp_eq_u32 s91, 12
	s_cselect_b32 s49, s11, s47
	s_cselect_b32 s48, s13, s46
	s_cselect_b32 s47, s39, s67
	s_cselect_b32 s46, s41, s66
	v_lshl_add_u64 v[160:161], s[14:15], 0, v[144:145]
	s_add_i32 m0, s71, 0xc000
	ds_read_b128 v[204:207], v167
	ds_read_b128 v[208:211], v167 offset:1024
	ds_read_b128 v[212:215], v167 offset:2048
	ds_read_b128 v[216:219], v167 offset:3072
	ds_read_b128 v[220:223], v167 offset:4096
	ds_read_b128 v[224:227], v167 offset:5120
	ds_read_b128 v[228:231], v167 offset:6144
	ds_read_b128 v[232:235], v167 offset:7168
	global_load_lds_dwordx4 v[160:161], off
	v_lshl_add_u64 v[160:161], s[14:15], 0, v[146:147]
	s_add_i32 m0, s71, 0xe000
	s_nop 0
	global_load_lds_dwordx4 v[160:161], off
	s_waitcnt vmcnt(8)
	s_waitcnt lgkmcnt(0)
	s_barrier
	s_setprio 1
	v_mfma_f32_16x16x32_bf16 v[124:127], v[152:155], v[204:207], v[124:127]
	v_mfma_f32_16x16x32_bf16 v[120:123], v[178:181], v[204:207], v[120:123]
	v_mfma_f32_16x16x32_bf16 v[108:111], v[152:155], v[212:215], v[108:111]
	v_mfma_f32_16x16x32_bf16 v[104:107], v[178:181], v[212:215], v[104:107]
	v_mfma_f32_16x16x32_bf16 v[92:95], v[152:155], v[220:223], v[92:95]
	v_mfma_f32_16x16x32_bf16 v[88:91], v[178:181], v[220:223], v[88:91]
	v_mfma_f32_16x16x32_bf16 v[76:79], v[152:155], v[228:231], v[76:79]
	v_mfma_f32_16x16x32_bf16 v[72:75], v[178:181], v[228:231], v[72:75]
	v_mfma_f32_16x16x32_bf16 v[124:127], v[156:159], v[208:211], v[124:127]
	v_mfma_f32_16x16x32_bf16 v[120:123], v[182:185], v[208:211], v[120:123]
	v_mfma_f32_16x16x32_bf16 v[108:111], v[156:159], v[216:219], v[108:111]
	v_mfma_f32_16x16x32_bf16 v[104:107], v[182:185], v[216:219], v[104:107]
	v_mfma_f32_16x16x32_bf16 v[92:95], v[156:159], v[224:227], v[92:95]
	v_mfma_f32_16x16x32_bf16 v[88:91], v[182:185], v[224:227], v[88:91]
	v_mfma_f32_16x16x32_bf16 v[76:79], v[156:159], v[232:235], v[76:79]
	v_mfma_f32_16x16x32_bf16 v[72:75], v[182:185], v[232:235], v[72:75]
	s_setprio 1
	v_mfma_f32_16x16x32_bf16 v[116:119], v[188:191], v[204:207], v[116:119]
	v_mfma_f32_16x16x32_bf16 v[112:115], v[196:199], v[204:207], v[112:115]
	v_mfma_f32_16x16x32_bf16 v[100:103], v[188:191], v[212:215], v[100:103]
	v_mfma_f32_16x16x32_bf16 v[96:99], v[196:199], v[212:215], v[96:99]
	v_mfma_f32_16x16x32_bf16 v[84:87], v[188:191], v[220:223], v[84:87]
	v_mfma_f32_16x16x32_bf16 v[80:83], v[196:199], v[220:223], v[80:83]
	v_mfma_f32_16x16x32_bf16 v[68:71], v[188:191], v[228:231], v[68:71]
	v_mfma_f32_16x16x32_bf16 v[64:67], v[196:199], v[228:231], v[64:67]
	v_mfma_f32_16x16x32_bf16 v[116:119], v[192:195], v[208:211], v[116:119]
	v_mfma_f32_16x16x32_bf16 v[112:115], v[200:203], v[208:211], v[112:115]
	v_mfma_f32_16x16x32_bf16 v[100:103], v[192:195], v[216:219], v[100:103]
	v_mfma_f32_16x16x32_bf16 v[96:99], v[200:203], v[216:219], v[96:99]
	v_mfma_f32_16x16x32_bf16 v[84:87], v[192:195], v[224:227], v[84:87]
	v_mfma_f32_16x16x32_bf16 v[80:83], v[200:203], v[224:227], v[80:83]
	v_mfma_f32_16x16x32_bf16 v[68:71], v[192:195], v[232:235], v[68:71]
	v_mfma_f32_16x16x32_bf16 v[64:67], v[200:203], v[232:235], v[64:67]
	s_barrier
	s_setprio 0
	s_add_i32 s58, s83, s70
	v_lshl_add_u64 v[160:161], s[46:47], 0, v[130:131]
	s_mov_b32 m0, s58
	ds_read_b128 v[204:207], v167 offset:16384
	ds_read_b128 v[208:211], v167 offset:17408
	ds_read_b128 v[212:215], v167 offset:18432
	ds_read_b128 v[216:219], v167 offset:19456
	ds_read_b128 v[220:223], v167 offset:20480
	ds_read_b128 v[224:227], v167 offset:21504
	ds_read_b128 v[228:231], v167 offset:22528
	ds_read_b128 v[232:235], v167 offset:23552
	global_load_lds_dwordx4 v[160:161], off
	s_add_i32 m0, s58, 0x2000
	s_add_u32 s58, s46, 0x40000
	v_lshl_add_u64 v[236:237], s[46:47], 0, v[134:135]
	s_addc_u32 s59, s47, 0
	s_add_i32 s92, s84, s70
	global_load_lds_dwordx4 v[236:237], off
	v_lshl_add_u64 v[238:239], s[58:59], 0, v[130:131]
	s_mov_b32 m0, s92
	v_lshl_add_u64 v[240:241], s[48:49], 0, v[132:133]
	global_load_lds_dwordx4 v[238:239], off
	v_lshl_add_u64 v[238:239], s[58:59], 0, v[134:135]
	s_add_i32 m0, s92, 0x2000
	s_nop 0
	global_load_lds_dwordx4 v[238:239], off
	v_lshl_add_u64 v[238:239], s[48:49], 0, v[128:129]
	s_mov_b32 m0, s71
	s_nop 0
	global_load_lds_dwordx4 v[238:239], off
	s_mov_b32 m0, s72
	s_nop 0
	global_load_lds_dwordx4 v[240:241], off
	s_waitcnt vmcnt(8)
	s_waitcnt lgkmcnt(0)
	s_barrier
; #define PG8_STAGE(bufoff, gbase, voff) do { _Pragma("unroll") for (int _i = 0; _i < 2; ++_i) \
;         __builtin_amdgcn_global_load_lds((const unsigned*)((const char*)(gbase) + (voff)[_i]), (PG8_LAS unsigned*)(lds + (bufoff) + ldsw + _i * 8192), 16, 0, 0); } while (0)
; #define PG8_LDA(dst, b, h) do { _Pragma("unroll") for (int m = 0; m < 4; ++m) _Pragma("unroll") for (int k = 0; k < 2; ++k) dst[m][k] = *(const PG8_LAS bf16x8*)(lds + PG8_SA(b, h) + aoff + m * 2048 + k * 1024); } while (0)
; #define PG8_LDB(dst, b, h) do { _Pragma("unroll") for (int n = 0; n < 2; ++n) _Pragma("unroll") for (int k = 0; k < 2; ++k) dst[n][k] = *(const PG8_LAS bf16x8*)(lds + PG8_SB(b, h) + boff + n * 2048 + k * 1024); } while (0)
; #define PG8_MMA(ai, bj, At, Bt) do { __builtin_amdgcn_s_setprio(1); _Pragma("unroll") for (int m = 0; m < 4; ++m) _Pragma("unroll") for (int n = 0; n < 2; ++n) _Pragma("unroll") for (int k = 0; k < 2; ++k) \
;         acc[ai][bj][m][n] = __builtin_amdgcn_mfma_f32_16x16x32_bf16(Bt[n][k], At[m][k], acc[ai][bj][m][n], 0, 0, 0); __builtin_amdgcn_s_setprio(0); } while (0)
; #define PG8_WAIT_V(n) asm volatile("s_waitcnt vmcnt(" #n ")" ::: "memory")
; #define PG8_WAIT_L(n) asm volatile("s_waitcnt lgkmcnt(" #n ")" ::: "memory")
; #define PG8_BAR __builtin_amdgcn_s_barrier()
; #define PG8_SCHED __builtin_amdgcn_sched_barrier(0)
; template <class Epi, class Sched, bool ALIGN_EPI = false, bool SP2 = false>
; __device__ __forceinline__ void gemm_phase(PG8_LAS unsigned char* lds, const Gemm g, const Sched& S, const Epi& E) {
;     ...
;             PG8_WAIT_V(8); PG8_WAIT_L(0); PG8_BAR; PG8_MMA(1, 0, At, B0); PG8_MMA(1, 1, At, B1); PG8_BAR; PG8_SCHED;
;             PG8_LDB(B0, 1, 0); PG8_LDB(B1, 1, 1); PG8_SCHED; PG8_LDA(At, 1, 0); PG8_STAGE(PG8_SA(0, 1), a2 + hstepA, voffA);
;             PG8_WAIT_V(8); PG8_WAIT_L(0); PG8_BAR; PG8_MMA(0, 0, At, B0); PG8_MMA(0, 1, At, B1); PG8_BAR; PG8_SCHED;
	s_setprio 1
	v_mfma_f32_16x16x32_bf16 v[60:63], v[152:155], v[204:207], v[60:63]
	v_mfma_f32_16x16x32_bf16 v[56:59], v[178:181], v[204:207], v[56:59]
	v_mfma_f32_16x16x32_bf16 v[44:47], v[152:155], v[212:215], v[44:47]
	v_mfma_f32_16x16x32_bf16 v[40:43], v[178:181], v[212:215], v[40:43]
	v_mfma_f32_16x16x32_bf16 v[28:31], v[152:155], v[220:223], v[28:31]
	v_mfma_f32_16x16x32_bf16 v[24:27], v[178:181], v[220:223], v[24:27]
	v_mfma_f32_16x16x32_bf16 v[12:15], v[152:155], v[228:231], v[12:15]
	v_mfma_f32_16x16x32_bf16 v[8:11], v[178:181], v[228:231], v[8:11]
	v_mfma_f32_16x16x32_bf16 v[60:63], v[156:159], v[208:211], v[60:63]
	v_mfma_f32_16x16x32_bf16 v[56:59], v[182:185], v[208:211], v[56:59]
	v_mfma_f32_16x16x32_bf16 v[44:47], v[156:159], v[216:219], v[44:47]
	v_mfma_f32_16x16x32_bf16 v[40:43], v[182:185], v[216:219], v[40:43]
	v_mfma_f32_16x16x32_bf16 v[28:31], v[156:159], v[224:227], v[28:31]
	v_mfma_f32_16x16x32_bf16 v[24:27], v[182:185], v[224:227], v[24:27]
	v_mfma_f32_16x16x32_bf16 v[12:15], v[156:159], v[232:235], v[12:15]
	v_mfma_f32_16x16x32_bf16 v[8:11], v[182:185], v[232:235], v[8:11]
	s_setprio 1
	v_mfma_f32_16x16x32_bf16 v[52:55], v[188:191], v[204:207], v[52:55]
	v_mfma_f32_16x16x32_bf16 v[48:51], v[196:199], v[204:207], v[48:51]
	v_mfma_f32_16x16x32_bf16 v[36:39], v[188:191], v[212:215], v[36:39]
	v_mfma_f32_16x16x32_bf16 v[32:35], v[196:199], v[212:215], v[32:35]
	v_mfma_f32_16x16x32_bf16 v[20:23], v[188:191], v[220:223], v[20:23]
	v_mfma_f32_16x16x32_bf16 v[16:19], v[196:199], v[220:223], v[16:19]
	v_mfma_f32_16x16x32_bf16 v[4:7], v[188:191], v[228:231], v[4:7]
	v_mfma_f32_16x16x32_bf16 v[0:3], v[196:199], v[228:231], v[0:3]
	v_mfma_f32_16x16x32_bf16 v[52:55], v[192:195], v[208:211], v[52:55]
	v_mfma_f32_16x16x32_bf16 v[48:51], v[200:203], v[208:211], v[48:51]
	v_mfma_f32_16x16x32_bf16 v[36:39], v[192:195], v[216:219], v[36:39]
	v_mfma_f32_16x16x32_bf16 v[32:35], v[200:203], v[216:219], v[32:35]
	v_mfma_f32_16x16x32_bf16 v[20:23], v[192:195], v[224:227], v[20:23]
	v_mfma_f32_16x16x32_bf16 v[16:19], v[200:203], v[224:227], v[16:19]
	v_mfma_f32_16x16x32_bf16 v[4:7], v[192:195], v[232:235], v[4:7]
	v_mfma_f32_16x16x32_bf16 v[0:3], v[200:203], v[232:235], v[0:3]
	s_barrier
	s_setprio 0
	s_add_i32 s58, 0, 0x18000
	v_add_u32_e32 v136, s58, v163
	s_add_i32 s59, 0, 0x1c000
	ds_read_b128 v[152:155], v136
	ds_read_b128 v[156:159], v136 offset:1024
	ds_read_b128 v[178:181], v136 offset:2048
	ds_read_b128 v[182:185], v136 offset:3072
	v_add_u32_e32 v136, s59, v163
	ds_read_b128 v[188:191], v136
	ds_read_b128 v[192:195], v136 offset:1024
	ds_read_b128 v[196:199], v136 offset:2048
	ds_read_b128 v[200:203], v136 offset:3072
	s_add_u32 s48, s48, 0x40000
	s_addc_u32 s49, s49, 0
	s_mov_b32 m0, s73
	v_lshl_add_u64 v[242:243], s[48:49], 0, v[128:129]
	ds_read_b128 v[204:207], v167 offset:32768
	ds_read_b128 v[208:211], v167 offset:33792
	ds_read_b128 v[212:215], v167 offset:34816
	ds_read_b128 v[216:219], v167 offset:35840
	ds_read_b128 v[220:223], v167 offset:36864
	ds_read_b128 v[224:227], v167 offset:37888
	ds_read_b128 v[228:231], v167 offset:38912
	ds_read_b128 v[232:235], v167 offset:39936
	global_load_lds_dwordx4 v[242:243], off
	v_lshl_add_u64 v[242:243], s[48:49], 0, v[132:133]
	s_mov_b32 m0, s74
	s_nop 0
	global_load_lds_dwordx4 v[242:243], off
	s_waitcnt vmcnt(8)
	s_waitcnt lgkmcnt(0)
	s_barrier
	s_setprio 1
	v_mfma_f32_16x16x32_bf16 v[124:127], v[152:155], v[204:207], v[124:127]
	v_mfma_f32_16x16x32_bf16 v[120:123], v[178:181], v[204:207], v[120:123]
	v_mfma_f32_16x16x32_bf16 v[108:111], v[152:155], v[212:215], v[108:111]
	v_mfma_f32_16x16x32_bf16 v[104:107], v[178:181], v[212:215], v[104:107]
	v_mfma_f32_16x16x32_bf16 v[92:95], v[152:155], v[220:223], v[92:95]
	v_mfma_f32_16x16x32_bf16 v[88:91], v[178:181], v[220:223], v[88:91]
	v_mfma_f32_16x16x32_bf16 v[76:79], v[152:155], v[228:231], v[76:79]
	v_mfma_f32_16x16x32_bf16 v[72:75], v[178:181], v[228:231], v[72:75]
	v_mfma_f32_16x16x32_bf16 v[124:127], v[156:159], v[208:211], v[124:127]
	v_mfma_f32_16x16x32_bf16 v[120:123], v[182:185], v[208:211], v[120:123]
	v_mfma_f32_16x16x32_bf16 v[108:111], v[156:159], v[216:219], v[108:111]
	v_mfma_f32_16x16x32_bf16 v[104:107], v[182:185], v[216:219], v[104:107]
	v_mfma_f32_16x16x32_bf16 v[92:95], v[156:159], v[224:227], v[92:95]
	v_mfma_f32_16x16x32_bf16 v[88:91], v[182:185], v[224:227], v[88:91]
	v_mfma_f32_16x16x32_bf16 v[76:79], v[156:159], v[232:235], v[76:79]
	v_mfma_f32_16x16x32_bf16 v[72:75], v[182:185], v[232:235], v[72:75]
	s_setprio 1
	v_mfma_f32_16x16x32_bf16 v[116:119], v[188:191], v[204:207], v[116:119]
	v_mfma_f32_16x16x32_bf16 v[112:115], v[196:199], v[204:207], v[112:115]
	v_mfma_f32_16x16x32_bf16 v[100:103], v[188:191], v[212:215], v[100:103]
	v_mfma_f32_16x16x32_bf16 v[96:99], v[196:199], v[212:215], v[96:99]
	v_mfma_f32_16x16x32_bf16 v[84:87], v[188:191], v[220:223], v[84:87]
	v_mfma_f32_16x16x32_bf16 v[80:83], v[196:199], v[220:223], v[80:83]
	v_mfma_f32_16x16x32_bf16 v[68:71], v[188:191], v[228:231], v[68:71]
	v_mfma_f32_16x16x32_bf16 v[64:67], v[196:199], v[228:231], v[64:67]
	v_mfma_f32_16x16x32_bf16 v[116:119], v[192:195], v[208:211], v[116:119]
	v_mfma_f32_16x16x32_bf16 v[112:115], v[200:203], v[208:211], v[112:115]
	v_mfma_f32_16x16x32_bf16 v[100:103], v[192:195], v[216:219], v[100:103]
	v_mfma_f32_16x16x32_bf16 v[96:99], v[200:203], v[216:219], v[96:99]
	v_mfma_f32_16x16x32_bf16 v[84:87], v[192:195], v[224:227], v[84:87]
	v_mfma_f32_16x16x32_bf16 v[80:83], v[200:203], v[224:227], v[80:83]
	v_mfma_f32_16x16x32_bf16 v[68:71], v[192:195], v[232:235], v[68:71]
	v_mfma_f32_16x16x32_bf16 v[64:67], v[200:203], v[232:235], v[64:67]
	s_barrier
; #define PG8_STAGE(bufoff, gbase, voff) do { _Pragma("unroll") for (int _i = 0; _i < 2; ++_i) \
;         __builtin_amdgcn_global_load_lds((const unsigned*)((const char*)(gbase) + (voff)[_i]), (PG8_LAS unsigned*)(lds + (bufoff) + ldsw + _i * 8192), 16, 0, 0); } while (0)
; #define PG8_LDA(dst, b, h) do { _Pragma("unroll") for (int m = 0; m < 4; ++m) _Pragma("unroll") for (int k = 0; k < 2; ++k) dst[m][k] = *(const PG8_LAS bf16x8*)(lds + PG8_SA(b, h) + aoff + m * 2048 + k * 1024); } while (0)
; #define PG8_MMA(ai, bj, At, Bt) do { __builtin_amdgcn_s_setprio(1); _Pragma("unroll") for (int m = 0; m < 4; ++m) _Pragma("unroll") for (int n = 0; n < 2; ++n) _Pragma("unroll") for (int k = 0; k < 2; ++k) \
;         acc[ai][bj][m][n] = __builtin_amdgcn_mfma_f32_16x16x32_bf16(Bt[n][k], At[m][k], acc[ai][bj][m][n], 0, 0, 0); __builtin_amdgcn_s_setprio(0); } while (0)
; #define PG8_WAIT_V(n) asm volatile("s_waitcnt vmcnt(" #n ")" ::: "memory")
; #define PG8_WAIT_L(n) asm volatile("s_waitcnt lgkmcnt(" #n ")" ::: "memory")
; #define PG8_BAR __builtin_amdgcn_s_barrier()
; #define PG8_SCHED __builtin_amdgcn_sched_barrier(0)
; template <class Epi, class Sched, bool ALIGN_EPI = false, bool SP2 = false>
; __device__ __forceinline__ void gemm_phase(PG8_LAS unsigned char* lds, const Gemm g, const Sched& S, const Epi& E) {
;     ...
;         for (int t = 0; t < nt; t += 2) {
;             const bool last = (t == nt - 2);
;     ...
;             PG8_LDA(At, 1, 1); PG8_STAGE(PG8_SB(1, 0), b3, voffB); PG8_STAGE(PG8_SB(1, 1), b3 + hstepB, voffB); PG8_STAGE(PG8_SA(1, 0), a3, voffA);
;             PG8_WAIT_V(8); PG8_WAIT_L(0); PG8_BAR; PG8_MMA(1, 0, At, B0); PG8_MMA(1, 1, At, B1); PG8_BAR; PG8_SCHED;
	s_setprio 0
	s_add_i32 s48, s58, s70
	v_lshl_add_u64 v[160:161], v[160:161], 0, s[30:31]
	s_mov_b32 m0, s48
	ds_read_b128 v[204:207], v167 offset:49152
	ds_read_b128 v[208:211], v167 offset:50176
	ds_read_b128 v[212:215], v167 offset:51200
	ds_read_b128 v[216:219], v167 offset:52224
	ds_read_b128 v[220:223], v167 offset:53248
	ds_read_b128 v[224:227], v167 offset:54272
	ds_read_b128 v[228:231], v167 offset:55296
	ds_read_b128 v[232:235], v167 offset:56320
	global_load_lds_dwordx4 v[160:161], off
	s_add_i32 m0, s48, 0x2000
	s_add_u32 s46, s46, 0x40080
	v_lshl_add_u64 v[160:161], v[236:237], 0, s[30:31]
	s_addc_u32 s47, s47, 0
	s_add_i32 s48, s59, s70
	global_load_lds_dwordx4 v[160:161], off
	v_lshl_add_u64 v[160:161], s[46:47], 0, v[130:131]
	s_mov_b32 m0, s48
	s_nop 0
	global_load_lds_dwordx4 v[160:161], off
	v_lshl_add_u64 v[160:161], s[46:47], 0, v[134:135]
	s_add_i32 m0, s48, 0x2000
	s_nop 0
	global_load_lds_dwordx4 v[160:161], off
	v_lshl_add_u64 v[160:161], v[238:239], 0, s[30:31]
	s_mov_b32 m0, s76
	s_nop 0
	global_load_lds_dwordx4 v[160:161], off
	v_lshl_add_u64 v[160:161], v[240:241], 0, s[30:31]
	s_mov_b32 m0, s77
	s_nop 0
	global_load_lds_dwordx4 v[160:161], off
	s_waitcnt vmcnt(8)
	s_waitcnt lgkmcnt(0)
	s_barrier
	s_setprio 1
	v_mfma_f32_16x16x32_bf16 v[60:63], v[152:155], v[204:207], v[60:63]
	v_mfma_f32_16x16x32_bf16 v[56:59], v[178:181], v[204:207], v[56:59]
	v_mfma_f32_16x16x32_bf16 v[44:47], v[152:155], v[212:215], v[44:47]
	v_mfma_f32_16x16x32_bf16 v[40:43], v[178:181], v[212:215], v[40:43]
	v_mfma_f32_16x16x32_bf16 v[28:31], v[152:155], v[220:223], v[28:31]
	v_mfma_f32_16x16x32_bf16 v[24:27], v[178:181], v[220:223], v[24:27]
	v_mfma_f32_16x16x32_bf16 v[12:15], v[152:155], v[228:231], v[12:15]
	v_mfma_f32_16x16x32_bf16 v[8:11], v[178:181], v[228:231], v[8:11]
	v_mfma_f32_16x16x32_bf16 v[60:63], v[156:159], v[208:211], v[60:63]
	v_mfma_f32_16x16x32_bf16 v[56:59], v[182:185], v[208:211], v[56:59]
	v_mfma_f32_16x16x32_bf16 v[44:47], v[156:159], v[216:219], v[44:47]
	v_mfma_f32_16x16x32_bf16 v[40:43], v[182:185], v[216:219], v[40:43]
	v_mfma_f32_16x16x32_bf16 v[28:31], v[156:159], v[224:227], v[28:31]
	v_mfma_f32_16x16x32_bf16 v[24:27], v[182:185], v[224:227], v[24:27]
	v_mfma_f32_16x16x32_bf16 v[12:15], v[156:159], v[232:235], v[12:15]
	v_mfma_f32_16x16x32_bf16 v[8:11], v[182:185], v[232:235], v[8:11]
	s_setprio 1
	v_mfma_f32_16x16x32_bf16 v[52:55], v[188:191], v[204:207], v[52:55]
	v_mfma_f32_16x16x32_bf16 v[48:51], v[196:199], v[204:207], v[48:51]
	v_mfma_f32_16x16x32_bf16 v[36:39], v[188:191], v[212:215], v[36:39]
	v_mfma_f32_16x16x32_bf16 v[32:35], v[196:199], v[212:215], v[32:35]
	v_mfma_f32_16x16x32_bf16 v[20:23], v[188:191], v[220:223], v[20:23]
	v_mfma_f32_16x16x32_bf16 v[16:19], v[196:199], v[220:223], v[16:19]
	v_mfma_f32_16x16x32_bf16 v[4:7], v[188:191], v[228:231], v[4:7]
	v_mfma_f32_16x16x32_bf16 v[0:3], v[196:199], v[228:231], v[0:3]
	v_mfma_f32_16x16x32_bf16 v[52:55], v[192:195], v[208:211], v[52:55]
	v_mfma_f32_16x16x32_bf16 v[48:51], v[200:203], v[208:211], v[48:51]
	v_mfma_f32_16x16x32_bf16 v[36:39], v[192:195], v[216:219], v[36:39]
	v_mfma_f32_16x16x32_bf16 v[32:35], v[200:203], v[216:219], v[32:35]
	v_mfma_f32_16x16x32_bf16 v[20:23], v[192:195], v[224:227], v[20:23]
	v_mfma_f32_16x16x32_bf16 v[16:19], v[200:203], v[224:227], v[16:19]
	v_mfma_f32_16x16x32_bf16 v[4:7], v[192:195], v[232:235], v[4:7]
	v_mfma_f32_16x16x32_bf16 v[0:3], v[200:203], v[232:235], v[0:3]
	s_barrier
	s_setprio 0
	s_add_i32 s91, s91, 2
	s_add_u32 s14, s14, 0x100
	s_addc_u32 s15, s15, 0
	s_add_u32 s66, s66, 0x100
	s_addc_u32 s67, s67, 0
	s_cmp_gt_u32 s91, 13
	s_cbranch_scc0 .LBB0_404
	s_and_b64 vcc, exec, s[34:35]
	s_cbranch_vccz .LBB0_407
	s_barrier

; #define PG8_STAGE(bufoff, gbase, voff) do { _Pragma("unroll") for (int _i = 0; _i < 2; ++_i) \
;         __builtin_amdgcn_global_load_lds((const unsigned*)((const char*)(gbase) + (voff)[_i]), (PG8_LAS unsigned*)(lds + (bufoff) + ldsw + _i * 8192), 16, 0, 0); } while (0)
; #define PG8_LDA(dst, b, h) do { _Pragma("unroll") for (int m = 0; m < 4; ++m) _Pragma("unroll") for (int k = 0; k < 2; ++k) dst[m][k] = *(const PG8_LAS bf16x8*)(lds + PG8_SA(b, h) + aoff + m * 2048 + k * 1024); } while (0)
; #define PG8_LDB(dst, b, h) do { _Pragma("unroll") for (int n = 0; n < 2; ++n) _Pragma("unroll") for (int k = 0; k < 2; ++k) dst[n][k] = *(const PG8_LAS bf16x8*)(lds + PG8_SB(b, h) + boff + n * 2048 + k * 1024); } while (0)
; #define PG8_MMA(ai, bj, At, Bt) do { __builtin_amdgcn_s_setprio(1); _Pragma("unroll") for (int m = 0; m < 4; ++m) _Pragma("unroll") for (int n = 0; n < 2; ++n) _Pragma("unroll") for (int k = 0; k < 2; ++k) \
;         acc[ai][bj][m][n] = __builtin_amdgcn_mfma_f32_16x16x32_bf16(Bt[n][k], At[m][k], acc[ai][bj][m][n], 0, 0, 0); __builtin_amdgcn_s_setprio(0); } while (0)
; #define PG8_WAIT_V(n) asm volatile("s_waitcnt vmcnt(" #n ")" ::: "memory")
; #define PG8_WAIT_L(n) asm volatile("s_waitcnt lgkmcnt(" #n ")" ::: "memory")
; #define PG8_BAR __builtin_amdgcn_s_barrier()
; template <class Epi, class Sched, bool ALIGN_EPI = false, bool SP2 = false>
; __device__ __forceinline__ void gemm_phase(PG8_LAS unsigned char* lds, const Gemm g, const Sched& S, const Epi& E) {
;     ...
;             const char* a1 = cA + (size_t)(t + 1) * kstep;
;             const char* a2 = last ? nA : cA + (size_t)(t + 2) * kstep; const char* b2 = last ? nB : cB + (size_t)(t + 2) * kstep;
;             const char* a3 = a2 + kstep; const char* b3 = b2 + kstep;
;             if (last && has_next) S.a_ready(nxt);
;             if constexpr (SP2) {
;             PG8_LDB(B0, 0, 0); PG8_LDB(B1, 0, 1); PG8_SCHED; PG8_LDA(At, 0, 0); PG8_STAGE(PG8_SA(1, 1), a1 + hstepA, voffA);
;             PG8_WAIT_V(8); PG8_WAIT_L(0); PG8_BAR; PG8_MMA(0, 0, At, B0); PG8_MMA(0, 1, At, B1); PG8_BAR; PG8_SCHED;
;             PG8_LDA(At, 0, 1); PG8_STAGE(PG8_SB(0, 0), b2, voffB); PG8_STAGE(PG8_SB(0, 1), b2 + hstepB, voffB); PG8_STAGE(PG8_SA(0, 0), a2, voffA);
;             PG8_WAIT_V(8); PG8_WAIT_L(0); PG8_BAR; PG8_MMA(1, 0, At, B0); PG8_MMA(1, 1, At, B1); PG8_BAR; PG8_SCHED;
.LBB0_524:
	ds_read_b128 v[144:147], v153
	ds_read_b128 v[158:161], v153 offset:1024
	ds_read_b128 v[162:165], v153 offset:2048
	ds_read_b128 v[166:169], v153 offset:3072
	ds_read_b128 v[170:173], v154
	ds_read_b128 v[174:177], v154 offset:1024
	ds_read_b128 v[178:181], v154 offset:2048
	ds_read_b128 v[182:185], v154 offset:3072
	s_add_u32 s30, s28, 0x100
	s_addc_u32 s31, s29, 0
	s_cmp_eq_u32 s76, 2
	s_cselect_b32 s37, s9, s31
	s_cselect_b32 s36, s8, s30
	s_cselect_b32 s35, s25, s75
	s_cselect_b32 s34, s24, s74
	v_lshl_add_u64 v[148:149], s[28:29], 0, v[136:137]
	s_add_i32 m0, s42, 0xc000
	ds_read_b128 v[188:191], v155
	ds_read_b128 v[192:195], v155 offset:1024
	ds_read_b128 v[196:199], v155 offset:2048
	ds_read_b128 v[200:203], v155 offset:3072
	ds_read_b128 v[204:207], v155 offset:4096
	ds_read_b128 v[208:211], v155 offset:5120
	ds_read_b128 v[212:215], v155 offset:6144
	ds_read_b128 v[216:219], v155 offset:7168
	global_load_lds_dwordx4 v[148:149], off
	v_lshl_add_u64 v[148:149], s[28:29], 0, v[138:139]
	s_add_i32 m0, s42, 0xe000
	s_nop 0
	global_load_lds_dwordx4 v[148:149], off
	s_waitcnt vmcnt(8)
	s_waitcnt lgkmcnt(0)
	s_barrier
	s_setprio 1
	v_mfma_f32_16x16x32_bf16 v[124:127], v[144:147], v[188:191], v[124:127]
	v_mfma_f32_16x16x32_bf16 v[120:123], v[162:165], v[188:191], v[120:123]
	v_mfma_f32_16x16x32_bf16 v[108:111], v[144:147], v[196:199], v[108:111]
	v_mfma_f32_16x16x32_bf16 v[104:107], v[162:165], v[196:199], v[104:107]
	v_mfma_f32_16x16x32_bf16 v[92:95], v[144:147], v[204:207], v[92:95]
	v_mfma_f32_16x16x32_bf16 v[88:91], v[162:165], v[204:207], v[88:91]
	v_mfma_f32_16x16x32_bf16 v[76:79], v[144:147], v[212:215], v[76:79]
	v_mfma_f32_16x16x32_bf16 v[72:75], v[162:165], v[212:215], v[72:75]
	v_mfma_f32_16x16x32_bf16 v[124:127], v[158:161], v[192:195], v[124:127]
	v_mfma_f32_16x16x32_bf16 v[120:123], v[166:169], v[192:195], v[120:123]
	v_mfma_f32_16x16x32_bf16 v[108:111], v[158:161], v[200:203], v[108:111]
	v_mfma_f32_16x16x32_bf16 v[104:107], v[166:169], v[200:203], v[104:107]
	v_mfma_f32_16x16x32_bf16 v[92:95], v[158:161], v[208:211], v[92:95]
	v_mfma_f32_16x16x32_bf16 v[88:91], v[166:169], v[208:211], v[88:91]
	v_mfma_f32_16x16x32_bf16 v[76:79], v[158:161], v[216:219], v[76:79]
	v_mfma_f32_16x16x32_bf16 v[72:75], v[166:169], v[216:219], v[72:75]
	s_setprio 1
	v_mfma_f32_16x16x32_bf16 v[116:119], v[170:173], v[188:191], v[116:119]
	v_mfma_f32_16x16x32_bf16 v[112:115], v[178:181], v[188:191], v[112:115]
	v_mfma_f32_16x16x32_bf16 v[100:103], v[170:173], v[196:199], v[100:103]
	v_mfma_f32_16x16x32_bf16 v[96:99], v[178:181], v[196:199], v[96:99]
	v_mfma_f32_16x16x32_bf16 v[84:87], v[170:173], v[204:207], v[84:87]
	v_mfma_f32_16x16x32_bf16 v[80:83], v[178:181], v[204:207], v[80:83]
	v_mfma_f32_16x16x32_bf16 v[68:71], v[170:173], v[212:215], v[68:71]
	v_mfma_f32_16x16x32_bf16 v[64:67], v[178:181], v[212:215], v[64:67]
	v_mfma_f32_16x16x32_bf16 v[116:119], v[174:177], v[192:195], v[116:119]
	v_mfma_f32_16x16x32_bf16 v[112:115], v[182:185], v[192:195], v[112:115]
	v_mfma_f32_16x16x32_bf16 v[100:103], v[174:177], v[200:203], v[100:103]
	v_mfma_f32_16x16x32_bf16 v[96:99], v[182:185], v[200:203], v[96:99]
	v_mfma_f32_16x16x32_bf16 v[84:87], v[174:177], v[208:211], v[84:87]
	v_mfma_f32_16x16x32_bf16 v[80:83], v[182:185], v[208:211], v[80:83]
	v_mfma_f32_16x16x32_bf16 v[68:71], v[174:177], v[216:219], v[68:71]
	v_mfma_f32_16x16x32_bf16 v[64:67], v[182:185], v[216:219], v[64:67]
	s_barrier
	s_setprio 0
	s_add_i32 s28, s66, s40
	v_lshl_add_u64 v[148:149], s[34:35], 0, v[132:133]
	s_mov_b32 m0, s28
	ds_read_b128 v[188:191], v155 offset:16384
	ds_read_b128 v[192:195], v155 offset:17408
	ds_read_b128 v[196:199], v155 offset:18432
	ds_read_b128 v[200:203], v155 offset:19456
	ds_read_b128 v[204:207], v155 offset:20480
	ds_read_b128 v[208:211], v155 offset:21504
	ds_read_b128 v[212:215], v155 offset:22528
	ds_read_b128 v[216:219], v155 offset:23552
	global_load_lds_dwordx4 v[148:149], off
	s_add_i32 m0, s28, 0x2000
	s_add_u32 s28, s34, 0x18000
	v_lshl_add_u64 v[220:221], s[34:35], 0, v[128:129]
	s_addc_u32 s29, s35, 0
	s_add_i32 s58, s67, s40
	global_load_lds_dwordx4 v[220:221], off
	v_lshl_add_u64 v[222:223], s[28:29], 0, v[132:133]
	s_mov_b32 m0, s58
	v_lshl_add_u64 v[224:225], s[36:37], 0, v[130:131]
	global_load_lds_dwordx4 v[222:223], off
	v_lshl_add_u64 v[222:223], s[28:29], 0, v[128:129]
	s_add_i32 m0, s58, 0x2000
	s_nop 0
	global_load_lds_dwordx4 v[222:223], off
	v_lshl_add_u64 v[222:223], s[36:37], 0, v[134:135]
	s_mov_b32 m0, s42
	s_nop 0
	global_load_lds_dwordx4 v[222:223], off
	s_mov_b32 m0, s43
	s_nop 0
	global_load_lds_dwordx4 v[224:225], off
	s_waitcnt vmcnt(8)
	s_waitcnt lgkmcnt(0)
	s_barrier
; #define PG8_STAGE(bufoff, gbase, voff) do { _Pragma("unroll") for (int _i = 0; _i < 2; ++_i) \
;         __builtin_amdgcn_global_load_lds((const unsigned*)((const char*)(gbase) + (voff)[_i]), (PG8_LAS unsigned*)(lds + (bufoff) + ldsw + _i * 8192), 16, 0, 0); } while (0)
; #define PG8_LDA(dst, b, h) do { _Pragma("unroll") for (int m = 0; m < 4; ++m) _Pragma("unroll") for (int k = 0; k < 2; ++k) dst[m][k] = *(const PG8_LAS bf16x8*)(lds + PG8_SA(b, h) + aoff + m * 2048 + k * 1024); } while (0)
; #define PG8_LDB(dst, b, h) do { _Pragma("unroll") for (int n = 0; n < 2; ++n) _Pragma("unroll") for (int k = 0; k < 2; ++k) dst[n][k] = *(const PG8_LAS bf16x8*)(lds + PG8_SB(b, h) + boff + n * 2048 + k * 1024); } while (0)
; #define PG8_MMA(ai, bj, At, Bt) do { __builtin_amdgcn_s_setprio(1); _Pragma("unroll") for (int m = 0; m < 4; ++m) _Pragma("unroll") for (int n = 0; n < 2; ++n) _Pragma("unroll") for (int k = 0; k < 2; ++k) \
;         acc[ai][bj][m][n] = __builtin_amdgcn_mfma_f32_16x16x32_bf16(Bt[n][k], At[m][k], acc[ai][bj][m][n], 0, 0, 0); __builtin_amdgcn_s_setprio(0); } while (0)
; #define PG8_WAIT_V(n) asm volatile("s_waitcnt vmcnt(" #n ")" ::: "memory")
; #define PG8_WAIT_L(n) asm volatile("s_waitcnt lgkmcnt(" #n ")" ::: "memory")
; #define PG8_BAR __builtin_amdgcn_s_barrier()
; #define PG8_SCHED __builtin_amdgcn_sched_barrier(0)
; template <class Epi, class Sched, bool ALIGN_EPI = false, bool SP2 = false>
; __device__ __forceinline__ void gemm_phase(PG8_LAS unsigned char* lds, const Gemm g, const Sched& S, const Epi& E) {
;     ...
;             PG8_WAIT_V(8); PG8_WAIT_L(0); PG8_BAR; PG8_MMA(1, 0, At, B0); PG8_MMA(1, 1, At, B1); PG8_BAR; PG8_SCHED;
;             PG8_LDB(B0, 1, 0); PG8_LDB(B1, 1, 1); PG8_SCHED; PG8_LDA(At, 1, 0); PG8_STAGE(PG8_SA(0, 1), a2 + hstepA, voffA);
;             PG8_WAIT_V(8); PG8_WAIT_L(0); PG8_BAR; PG8_MMA(0, 0, At, B0); PG8_MMA(0, 1, At, B1); PG8_BAR; PG8_SCHED;
	s_setprio 1
	v_mfma_f32_16x16x32_bf16 v[60:63], v[144:147], v[188:191], v[60:63]
	v_mfma_f32_16x16x32_bf16 v[56:59], v[162:165], v[188:191], v[56:59]
	v_mfma_f32_16x16x32_bf16 v[44:47], v[144:147], v[196:199], v[44:47]
	v_mfma_f32_16x16x32_bf16 v[40:43], v[162:165], v[196:199], v[40:43]
	v_mfma_f32_16x16x32_bf16 v[28:31], v[144:147], v[204:207], v[28:31]
	v_mfma_f32_16x16x32_bf16 v[24:27], v[162:165], v[204:207], v[24:27]
	v_mfma_f32_16x16x32_bf16 v[12:15], v[144:147], v[212:215], v[12:15]
	v_mfma_f32_16x16x32_bf16 v[8:11], v[162:165], v[212:215], v[8:11]
	v_mfma_f32_16x16x32_bf16 v[60:63], v[158:161], v[192:195], v[60:63]
	v_mfma_f32_16x16x32_bf16 v[56:59], v[166:169], v[192:195], v[56:59]
	v_mfma_f32_16x16x32_bf16 v[44:47], v[158:161], v[200:203], v[44:47]
	v_mfma_f32_16x16x32_bf16 v[40:43], v[166:169], v[200:203], v[40:43]
	v_mfma_f32_16x16x32_bf16 v[28:31], v[158:161], v[208:211], v[28:31]
	v_mfma_f32_16x16x32_bf16 v[24:27], v[166:169], v[208:211], v[24:27]
	v_mfma_f32_16x16x32_bf16 v[12:15], v[158:161], v[216:219], v[12:15]
	v_mfma_f32_16x16x32_bf16 v[8:11], v[166:169], v[216:219], v[8:11]
	s_setprio 1
	v_mfma_f32_16x16x32_bf16 v[52:55], v[170:173], v[188:191], v[52:55]
	v_mfma_f32_16x16x32_bf16 v[48:51], v[178:181], v[188:191], v[48:51]
	v_mfma_f32_16x16x32_bf16 v[36:39], v[170:173], v[196:199], v[36:39]
	v_mfma_f32_16x16x32_bf16 v[32:35], v[178:181], v[196:199], v[32:35]
	v_mfma_f32_16x16x32_bf16 v[20:23], v[170:173], v[204:207], v[20:23]
	v_mfma_f32_16x16x32_bf16 v[16:19], v[178:181], v[204:207], v[16:19]
	v_mfma_f32_16x16x32_bf16 v[4:7], v[170:173], v[212:215], v[4:7]
	v_mfma_f32_16x16x32_bf16 v[0:3], v[178:181], v[212:215], v[0:3]
	v_mfma_f32_16x16x32_bf16 v[52:55], v[174:177], v[192:195], v[52:55]
	v_mfma_f32_16x16x32_bf16 v[48:51], v[182:185], v[192:195], v[48:51]
	v_mfma_f32_16x16x32_bf16 v[36:39], v[174:177], v[200:203], v[36:39]
	v_mfma_f32_16x16x32_bf16 v[32:35], v[182:185], v[200:203], v[32:35]
	v_mfma_f32_16x16x32_bf16 v[20:23], v[174:177], v[208:211], v[20:23]
	v_mfma_f32_16x16x32_bf16 v[16:19], v[182:185], v[208:211], v[16:19]
	v_mfma_f32_16x16x32_bf16 v[4:7], v[174:177], v[216:219], v[4:7]
	v_mfma_f32_16x16x32_bf16 v[0:3], v[182:185], v[216:219], v[0:3]
	s_barrier
	s_setprio 0
	s_add_i32 s58, 0, 0x18000
	v_add_u32_e32 v157, s58, v151
	s_add_i32 s59, 0, 0x1c000
	ds_read_b128 v[144:147], v157
	ds_read_b128 v[158:161], v157 offset:1024
	ds_read_b128 v[162:165], v157 offset:2048
	ds_read_b128 v[166:169], v157 offset:3072
	v_add_u32_e32 v157, s59, v151
	ds_read_b128 v[170:173], v157
	ds_read_b128 v[174:177], v157 offset:1024
	ds_read_b128 v[178:181], v157 offset:2048
	ds_read_b128 v[182:185], v157 offset:3072
	s_add_u32 s28, s36, 0x30000
	s_addc_u32 s29, s37, 0
	s_mov_b32 m0, s44
	v_lshl_add_u64 v[226:227], s[28:29], 0, v[134:135]
	ds_read_b128 v[188:191], v155 offset:32768
	ds_read_b128 v[192:195], v155 offset:33792
	ds_read_b128 v[196:199], v155 offset:34816
	ds_read_b128 v[200:203], v155 offset:35840
	ds_read_b128 v[204:207], v155 offset:36864
	ds_read_b128 v[208:211], v155 offset:37888
	ds_read_b128 v[212:215], v155 offset:38912
	ds_read_b128 v[216:219], v155 offset:39936
	global_load_lds_dwordx4 v[226:227], off
	v_lshl_add_u64 v[226:227], s[28:29], 0, v[130:131]
	s_mov_b32 m0, s45
	s_nop 0
	global_load_lds_dwordx4 v[226:227], off
	s_waitcnt vmcnt(8)
	s_waitcnt lgkmcnt(0)
	s_barrier
	s_setprio 1
	v_mfma_f32_16x16x32_bf16 v[124:127], v[144:147], v[188:191], v[124:127]
	v_mfma_f32_16x16x32_bf16 v[120:123], v[162:165], v[188:191], v[120:123]
	v_mfma_f32_16x16x32_bf16 v[108:111], v[144:147], v[196:199], v[108:111]
	v_mfma_f32_16x16x32_bf16 v[104:107], v[162:165], v[196:199], v[104:107]
	v_mfma_f32_16x16x32_bf16 v[92:95], v[144:147], v[204:207], v[92:95]
	v_mfma_f32_16x16x32_bf16 v[88:91], v[162:165], v[204:207], v[88:91]
	v_mfma_f32_16x16x32_bf16 v[76:79], v[144:147], v[212:215], v[76:79]
	v_mfma_f32_16x16x32_bf16 v[72:75], v[162:165], v[212:215], v[72:75]
	v_mfma_f32_16x16x32_bf16 v[124:127], v[158:161], v[192:195], v[124:127]
	v_mfma_f32_16x16x32_bf16 v[120:123], v[166:169], v[192:195], v[120:123]
	v_mfma_f32_16x16x32_bf16 v[108:111], v[158:161], v[200:203], v[108:111]
	v_mfma_f32_16x16x32_bf16 v[104:107], v[166:169], v[200:203], v[104:107]
	v_mfma_f32_16x16x32_bf16 v[92:95], v[158:161], v[208:211], v[92:95]
	v_mfma_f32_16x16x32_bf16 v[88:91], v[166:169], v[208:211], v[88:91]
	v_mfma_f32_16x16x32_bf16 v[76:79], v[158:161], v[216:219], v[76:79]
	v_mfma_f32_16x16x32_bf16 v[72:75], v[166:169], v[216:219], v[72:75]
	s_setprio 1
	v_mfma_f32_16x16x32_bf16 v[116:119], v[170:173], v[188:191], v[116:119]
	v_mfma_f32_16x16x32_bf16 v[112:115], v[178:181], v[188:191], v[112:115]
	v_mfma_f32_16x16x32_bf16 v[100:103], v[170:173], v[196:199], v[100:103]
	v_mfma_f32_16x16x32_bf16 v[96:99], v[178:181], v[196:199], v[96:99]
	v_mfma_f32_16x16x32_bf16 v[84:87], v[170:173], v[204:207], v[84:87]
	v_mfma_f32_16x16x32_bf16 v[80:83], v[178:181], v[204:207], v[80:83]
	v_mfma_f32_16x16x32_bf16 v[68:71], v[170:173], v[212:215], v[68:71]
	v_mfma_f32_16x16x32_bf16 v[64:67], v[178:181], v[212:215], v[64:67]
	v_mfma_f32_16x16x32_bf16 v[116:119], v[174:177], v[192:195], v[116:119]
	v_mfma_f32_16x16x32_bf16 v[112:115], v[182:185], v[192:195], v[112:115]
	v_mfma_f32_16x16x32_bf16 v[100:103], v[174:177], v[200:203], v[100:103]
	v_mfma_f32_16x16x32_bf16 v[96:99], v[182:185], v[200:203], v[96:99]
	v_mfma_f32_16x16x32_bf16 v[84:87], v[174:177], v[208:211], v[84:87]
	v_mfma_f32_16x16x32_bf16 v[80:83], v[182:185], v[208:211], v[80:83]
	v_mfma_f32_16x16x32_bf16 v[68:71], v[174:177], v[216:219], v[68:71]
	v_mfma_f32_16x16x32_bf16 v[64:67], v[182:185], v[216:219], v[64:67]
	s_barrier
; #define PG8_STAGE(bufoff, gbase, voff) do { _Pragma("unroll") for (int _i = 0; _i < 2; ++_i) \
;         __builtin_amdgcn_global_load_lds((const unsigned*)((const char*)(gbase) + (voff)[_i]), (PG8_LAS unsigned*)(lds + (bufoff) + ldsw + _i * 8192), 16, 0, 0); } while (0)
; #define PG8_LDA(dst, b, h) do { _Pragma("unroll") for (int m = 0; m < 4; ++m) _Pragma("unroll") for (int k = 0; k < 2; ++k) dst[m][k] = *(const PG8_LAS bf16x8*)(lds + PG8_SA(b, h) + aoff + m * 2048 + k * 1024); } while (0)
; #define PG8_MMA(ai, bj, At, Bt) do { __builtin_amdgcn_s_setprio(1); _Pragma("unroll") for (int m = 0; m < 4; ++m) _Pragma("unroll") for (int n = 0; n < 2; ++n) _Pragma("unroll") for (int k = 0; k < 2; ++k) \
;         acc[ai][bj][m][n] = __builtin_amdgcn_mfma_f32_16x16x32_bf16(Bt[n][k], At[m][k], acc[ai][bj][m][n], 0, 0, 0); __builtin_amdgcn_s_setprio(0); } while (0)
; #define PG8_WAIT_V(n) asm volatile("s_waitcnt vmcnt(" #n ")" ::: "memory")
; #define PG8_WAIT_L(n) asm volatile("s_waitcnt lgkmcnt(" #n ")" ::: "memory")
; #define PG8_BAR __builtin_amdgcn_s_barrier()
; #define PG8_SCHED __builtin_amdgcn_sched_barrier(0)
; template <class Epi, class Sched, bool ALIGN_EPI = false, bool SP2 = false>
; __device__ __forceinline__ void gemm_phase(PG8_LAS unsigned char* lds, const Gemm g, const Sched& S, const Epi& E) {
;     ...
;         for (int t = 0; t < nt; t += 2) {
;             const bool last = (t == nt - 2);
;     ...
;             PG8_LDA(At, 1, 1); PG8_STAGE(PG8_SB(1, 0), b3, voffB); PG8_STAGE(PG8_SB(1, 1), b3 + hstepB, voffB); PG8_STAGE(PG8_SA(1, 0), a3, voffA);
;             PG8_WAIT_V(8); PG8_WAIT_L(0); PG8_BAR; PG8_MMA(1, 0, At, B0); PG8_MMA(1, 1, At, B1); PG8_BAR; PG8_SCHED;
	s_setprio 0
	s_add_i32 s28, s58, s40
	v_lshl_add_u64 v[148:149], v[148:149], 0, s[12:13]
	s_mov_b32 m0, s28
	ds_read_b128 v[188:191], v155 offset:49152
	ds_read_b128 v[192:195], v155 offset:50176
	ds_read_b128 v[196:199], v155 offset:51200
	ds_read_b128 v[200:203], v155 offset:52224
	ds_read_b128 v[204:207], v155 offset:53248
	ds_read_b128 v[208:211], v155 offset:54272
	ds_read_b128 v[212:215], v155 offset:55296
	ds_read_b128 v[216:219], v155 offset:56320
	global_load_lds_dwordx4 v[148:149], off
	s_add_i32 m0, s28, 0x2000
	s_add_u32 s28, s34, 0x18080
	v_lshl_add_u64 v[148:149], v[220:221], 0, s[12:13]
	s_addc_u32 s29, s35, 0
	s_add_i32 s34, s59, s40
	global_load_lds_dwordx4 v[148:149], off
	v_lshl_add_u64 v[148:149], s[28:29], 0, v[132:133]
	s_mov_b32 m0, s34
	s_nop 0
	global_load_lds_dwordx4 v[148:149], off
	v_lshl_add_u64 v[148:149], s[28:29], 0, v[128:129]
	s_add_i32 m0, s34, 0x2000
	s_nop 0
	global_load_lds_dwordx4 v[148:149], off
	v_lshl_add_u64 v[148:149], v[222:223], 0, s[12:13]
	s_mov_b32 m0, s47
	s_nop 0
	global_load_lds_dwordx4 v[148:149], off
	v_lshl_add_u64 v[148:149], v[224:225], 0, s[12:13]
	s_mov_b32 m0, s48
	s_nop 0
	global_load_lds_dwordx4 v[148:149], off
	s_waitcnt vmcnt(8)
	s_waitcnt lgkmcnt(0)
	s_barrier
	s_setprio 1
	v_mfma_f32_16x16x32_bf16 v[60:63], v[144:147], v[188:191], v[60:63]
	v_mfma_f32_16x16x32_bf16 v[56:59], v[162:165], v[188:191], v[56:59]
	v_mfma_f32_16x16x32_bf16 v[44:47], v[144:147], v[196:199], v[44:47]
	v_mfma_f32_16x16x32_bf16 v[40:43], v[162:165], v[196:199], v[40:43]
	v_mfma_f32_16x16x32_bf16 v[28:31], v[144:147], v[204:207], v[28:31]
	v_mfma_f32_16x16x32_bf16 v[24:27], v[162:165], v[204:207], v[24:27]
	v_mfma_f32_16x16x32_bf16 v[12:15], v[144:147], v[212:215], v[12:15]
	v_mfma_f32_16x16x32_bf16 v[8:11], v[162:165], v[212:215], v[8:11]
	v_mfma_f32_16x16x32_bf16 v[60:63], v[158:161], v[192:195], v[60:63]
	v_mfma_f32_16x16x32_bf16 v[56:59], v[166:169], v[192:195], v[56:59]
	v_mfma_f32_16x16x32_bf16 v[44:47], v[158:161], v[200:203], v[44:47]
	v_mfma_f32_16x16x32_bf16 v[40:43], v[166:169], v[200:203], v[40:43]
	v_mfma_f32_16x16x32_bf16 v[28:31], v[158:161], v[208:211], v[28:31]
	v_mfma_f32_16x16x32_bf16 v[24:27], v[166:169], v[208:211], v[24:27]
	v_mfma_f32_16x16x32_bf16 v[12:15], v[158:161], v[216:219], v[12:15]
	v_mfma_f32_16x16x32_bf16 v[8:11], v[166:169], v[216:219], v[8:11]
	s_setprio 1
	v_mfma_f32_16x16x32_bf16 v[52:55], v[170:173], v[188:191], v[52:55]
	v_mfma_f32_16x16x32_bf16 v[48:51], v[178:181], v[188:191], v[48:51]
	v_mfma_f32_16x16x32_bf16 v[36:39], v[170:173], v[196:199], v[36:39]
	v_mfma_f32_16x16x32_bf16 v[32:35], v[178:181], v[196:199], v[32:35]
	v_mfma_f32_16x16x32_bf16 v[20:23], v[170:173], v[204:207], v[20:23]
	v_mfma_f32_16x16x32_bf16 v[16:19], v[178:181], v[204:207], v[16:19]
	v_mfma_f32_16x16x32_bf16 v[4:7], v[170:173], v[212:215], v[4:7]
	v_mfma_f32_16x16x32_bf16 v[0:3], v[178:181], v[212:215], v[0:3]
	v_mfma_f32_16x16x32_bf16 v[52:55], v[174:177], v[192:195], v[52:55]
	v_mfma_f32_16x16x32_bf16 v[48:51], v[182:185], v[192:195], v[48:51]
	v_mfma_f32_16x16x32_bf16 v[36:39], v[174:177], v[200:203], v[36:39]
	v_mfma_f32_16x16x32_bf16 v[32:35], v[182:185], v[200:203], v[32:35]
	v_mfma_f32_16x16x32_bf16 v[20:23], v[174:177], v[208:211], v[20:23]
	v_mfma_f32_16x16x32_bf16 v[16:19], v[182:185], v[208:211], v[16:19]
	v_mfma_f32_16x16x32_bf16 v[4:7], v[174:177], v[216:219], v[4:7]
	v_mfma_f32_16x16x32_bf16 v[0:3], v[182:185], v[216:219], v[0:3]
	s_barrier
	s_setprio 0
	s_add_i32 s76, s76, 2
	s_add_u32 s74, s74, 0x100
	s_addc_u32 s75, s75, 0
	s_cmp_gt_u32 s76, 3
	s_mov_b64 s[28:29], s[30:31]
	s_cbranch_scc0 .LBB0_524
	s_and_b64 vcc, exec, s[14:15]
	s_cbranch_vccz .LBB0_527
	s_barrier

; #define PG8_STAGE(bufoff, gbase, voff) do { _Pragma("unroll") for (int _i = 0; _i < 2; ++_i) \
;         __builtin_amdgcn_global_load_lds((const unsigned*)((const char*)(gbase) + (voff)[_i]), (PG8_LAS unsigned*)(lds + (bufoff) + ldsw + _i * 8192), 16, 0, 0); } while (0)
; #define PG8_LDA(dst, b, h) do { _Pragma("unroll") for (int m = 0; m < 4; ++m) _Pragma("unroll") for (int k = 0; k < 2; ++k) dst[m][k] = *(const PG8_LAS bf16x8*)(lds + PG8_SA(b, h) + aoff + m * 2048 + k * 1024); } while (0)
; #define PG8_LDB(dst, b, h) do { _Pragma("unroll") for (int n = 0; n < 2; ++n) _Pragma("unroll") for (int k = 0; k < 2; ++k) dst[n][k] = *(const PG8_LAS bf16x8*)(lds + PG8_SB(b, h) + boff + n * 2048 + k * 1024); } while (0)
; #define PG8_WAIT_V(n) asm volatile("s_waitcnt vmcnt(" #n ")" ::: "memory")
; #define PG8_WAIT_L(n) asm volatile("s_waitcnt lgkmcnt(" #n ")" ::: "memory")
; #define PG8_BAR __builtin_amdgcn_s_barrier()
; #define PG8_SCHED __builtin_amdgcn_sched_barrier(0)
; template <class Epi, class Sched, bool ALIGN_EPI = false, bool SP2 = false>
; __device__ __forceinline__ void gemm_phase(PG8_LAS unsigned char* lds, const Gemm g, const Sched& S, const Epi& E) {
;     ...
;         const bool has_next = S.next(ui + 1, nxt);
;         const char* nA = has_next ? (const char*)g.A + (size_t)nxt.pm * tstepA : cA; const char* nB = has_next ? (const char*)g.Bt + (size_t)nxt.pn * tstepB : cB;
;         for (int t = 0; t < nt; t += 2) {
;             const bool last = (t == nt - 2);
;             const char* a1 = cA + (size_t)(t + 1) * kstep;
;             const char* a2 = last ? nA : cA + (size_t)(t + 2) * kstep; const char* b2 = last ? nB : cB + (size_t)(t + 2) * kstep;
;             const char* a3 = a2 + kstep; const char* b3 = b2 + kstep;
;             if (last && has_next) S.a_ready(nxt);
;             if constexpr (SP2) {
;             PG8_LDB(B0, 0, 0); PG8_LDB(B1, 0, 1); PG8_SCHED; PG8_LDA(At, 0, 0); PG8_STAGE(PG8_SA(1, 1), a1 + hstepA, voffA);
;             PG8_WAIT_V(8); PG8_WAIT_L(0); PG8_BAR; PG8_MMA(0, 0, At, B0); PG8_MMA(0, 1, At, B1); PG8_BAR; PG8_SCHED;
;             PG8_LDA(At, 0, 1); PG8_STAGE(PG8_SB(0, 0), b2, voffB); PG8_STAGE(PG8_SB(0, 1), b2 + hstepB, voffB); PG8_STAGE(PG8_SA(0, 0), a2, voffA);
;             PG8_WAIT_V(8); PG8_WAIT_L(0); PG8_BAR; PG8_MMA(1, 0, At, B0); PG8_MMA(1, 1, At, B1); PG8_BAR; PG8_SCHED;
.LBB0_542:
	s_add_u32 s39, s34, s38
	s_addc_u32 s44, s35, 0
	s_add_u32 s42, s39, 0x100
	s_addc_u32 s43, s44, 0
	s_and_b64 s[40:41], s[36:37], exec
	s_cselect_b32 s41, s27, s43
	s_cselect_b32 s40, s26, s42
	s_add_u32 s38, s30, s38
	s_addc_u32 s42, s31, 0
	s_add_u32 s38, s38, 0x100
	s_addc_u32 s42, s42, 0
	s_and_b64 s[36:37], s[36:37], exec
	s_cselect_b32 s43, s25, s42
	s_cselect_b32 s42, s89, s38
	s_add_u32 s46, s39, 0x30080
	ds_read_b128 v[140:143], v149
	ds_read_b128 v[154:157], v149 offset:1024
	ds_read_b128 v[158:161], v149 offset:2048
	ds_read_b128 v[162:165], v149 offset:3072
	ds_read_b128 v[166:169], v150
	ds_read_b128 v[170:173], v150 offset:1024
	ds_read_b128 v[174:177], v150 offset:2048
	ds_read_b128 v[178:181], v150 offset:3072
	s_addc_u32 s47, s44, 0
	s_add_i32 vcc_hi, s78, s68
	s_add_i32 m0, s70, 0xc000
	s_add_i32 s58, s70, 0xe000
	s_add_i32 s96, vcc_hi, 0x2000
	s_add_u32 s44, s42, 0x10000
	s_addc_u32 s45, s43, 0
	s_add_i32 vcc_lo, s79, s68
	s_add_i32 s97, vcc_lo, 0x2000
	s_add_i32 s95, 0, 0x18000
	s_add_i32 s94, 0, 0x1c000
	s_add_u32 s38, s40, 0x30000
	s_addc_u32 s39, s41, 0
	s_add_i32 s93, s95, s68
	s_add_i32 s91, s93, 0x2000
	s_add_u32 s36, s42, 0x10080
	s_addc_u32 s37, s43, 0
	s_add_i32 s92, s94, s68
	s_add_i32 s90, s92, 0x2000
	v_lshl_add_u64 v[144:145], s[46:47], 0, v[134:135]
	ds_read_b128 v[182:185], v151
	ds_read_b128 v[188:191], v151 offset:1024
	ds_read_b128 v[192:195], v151 offset:2048
	ds_read_b128 v[196:199], v151 offset:3072
	ds_read_b128 v[200:203], v151 offset:4096
	ds_read_b128 v[204:207], v151 offset:5120
	ds_read_b128 v[208:211], v151 offset:6144
	ds_read_b128 v[212:215], v151 offset:7168
	global_load_lds_dwordx4 v[144:145], off
	v_lshl_add_u64 v[144:145], s[46:47], 0, v[130:131]
	s_mov_b32 m0, s58
	s_nop 0
	global_load_lds_dwordx4 v[144:145], off
	s_waitcnt vmcnt(8)
	s_waitcnt lgkmcnt(0)
	s_barrier
	s_setprio 1
	v_mfma_f32_16x16x32_bf16 v[124:127], v[140:143], v[182:185], v[124:127]
	v_mfma_f32_16x16x32_bf16 v[120:123], v[158:161], v[182:185], v[120:123]
	v_mfma_f32_16x16x32_bf16 v[108:111], v[140:143], v[192:195], v[108:111]
	v_mfma_f32_16x16x32_bf16 v[104:107], v[158:161], v[192:195], v[104:107]
	v_mfma_f32_16x16x32_bf16 v[92:95], v[140:143], v[200:203], v[92:95]
	v_mfma_f32_16x16x32_bf16 v[88:91], v[158:161], v[200:203], v[88:91]
	v_mfma_f32_16x16x32_bf16 v[76:79], v[140:143], v[208:211], v[76:79]
	v_mfma_f32_16x16x32_bf16 v[72:75], v[158:161], v[208:211], v[72:75]
	v_mfma_f32_16x16x32_bf16 v[124:127], v[154:157], v[188:191], v[124:127]
	v_mfma_f32_16x16x32_bf16 v[120:123], v[162:165], v[188:191], v[120:123]
	v_mfma_f32_16x16x32_bf16 v[108:111], v[154:157], v[196:199], v[108:111]
	v_mfma_f32_16x16x32_bf16 v[104:107], v[162:165], v[196:199], v[104:107]
	v_mfma_f32_16x16x32_bf16 v[92:95], v[154:157], v[204:207], v[92:95]
	v_mfma_f32_16x16x32_bf16 v[88:91], v[162:165], v[204:207], v[88:91]
	v_mfma_f32_16x16x32_bf16 v[76:79], v[154:157], v[212:215], v[76:79]
	v_mfma_f32_16x16x32_bf16 v[72:75], v[162:165], v[212:215], v[72:75]
	s_setprio 1
	v_mfma_f32_16x16x32_bf16 v[116:119], v[166:169], v[182:185], v[116:119]
	v_mfma_f32_16x16x32_bf16 v[112:115], v[174:177], v[182:185], v[112:115]
	v_mfma_f32_16x16x32_bf16 v[100:103], v[166:169], v[192:195], v[100:103]
	v_mfma_f32_16x16x32_bf16 v[96:99], v[174:177], v[192:195], v[96:99]
	v_mfma_f32_16x16x32_bf16 v[84:87], v[166:169], v[200:203], v[84:87]
	v_mfma_f32_16x16x32_bf16 v[80:83], v[174:177], v[200:203], v[80:83]
	v_mfma_f32_16x16x32_bf16 v[68:71], v[166:169], v[208:211], v[68:71]
	v_mfma_f32_16x16x32_bf16 v[64:67], v[174:177], v[208:211], v[64:67]
	v_mfma_f32_16x16x32_bf16 v[116:119], v[170:173], v[188:191], v[116:119]
	v_mfma_f32_16x16x32_bf16 v[112:115], v[178:181], v[188:191], v[112:115]
	v_mfma_f32_16x16x32_bf16 v[100:103], v[170:173], v[196:199], v[100:103]
	v_mfma_f32_16x16x32_bf16 v[96:99], v[178:181], v[196:199], v[96:99]
	v_mfma_f32_16x16x32_bf16 v[84:87], v[170:173], v[204:207], v[84:87]
	v_mfma_f32_16x16x32_bf16 v[80:83], v[178:181], v[204:207], v[80:83]
	v_mfma_f32_16x16x32_bf16 v[68:71], v[170:173], v[212:215], v[68:71]
	v_mfma_f32_16x16x32_bf16 v[64:67], v[178:181], v[212:215], v[64:67]
	s_barrier
	s_setprio 0
	s_mov_b32 m0, vcc_hi
	v_lshl_add_u64 v[144:145], s[42:43], 0, v[132:133]
	ds_read_b128 v[182:185], v151 offset:16384
	ds_read_b128 v[188:191], v151 offset:17408
	ds_read_b128 v[192:195], v151 offset:18432
	ds_read_b128 v[196:199], v151 offset:19456
	ds_read_b128 v[200:203], v151 offset:20480
	ds_read_b128 v[204:207], v151 offset:21504
	ds_read_b128 v[208:211], v151 offset:22528
	ds_read_b128 v[212:215], v151 offset:23552
	global_load_lds_dwordx4 v[144:145], off
	v_lshl_add_u64 v[216:217], s[42:43], 0, v[128:129]
	s_mov_b32 m0, s96
	v_lshl_add_u64 v[218:219], s[44:45], 0, v[132:133]
	global_load_lds_dwordx4 v[216:217], off
	s_mov_b32 m0, vcc_lo
	v_lshl_add_u64 v[220:221], s[40:41], 0, v[130:131]
	global_load_lds_dwordx4 v[218:219], off
	v_lshl_add_u64 v[218:219], s[44:45], 0, v[128:129]
	s_mov_b32 m0, s97
	s_nop 0
	global_load_lds_dwordx4 v[218:219], off
	v_lshl_add_u64 v[218:219], s[40:41], 0, v[134:135]
	s_mov_b32 m0, s70
	s_nop 0
	global_load_lds_dwordx4 v[218:219], off
	s_mov_b32 m0, s71
	s_nop 0
	global_load_lds_dwordx4 v[220:221], off
	s_waitcnt vmcnt(8)
	s_waitcnt lgkmcnt(0)
	s_barrier
; #define PG8_STAGE(bufoff, gbase, voff) do { _Pragma("unroll") for (int _i = 0; _i < 2; ++_i) \
;         __builtin_amdgcn_global_load_lds((const unsigned*)((const char*)(gbase) + (voff)[_i]), (PG8_LAS unsigned*)(lds + (bufoff) + ldsw + _i * 8192), 16, 0, 0); } while (0)
; #define PG8_LDA(dst, b, h) do { _Pragma("unroll") for (int m = 0; m < 4; ++m) _Pragma("unroll") for (int k = 0; k < 2; ++k) dst[m][k] = *(const PG8_LAS bf16x8*)(lds + PG8_SA(b, h) + aoff + m * 2048 + k * 1024); } while (0)
; #define PG8_LDB(dst, b, h) do { _Pragma("unroll") for (int n = 0; n < 2; ++n) _Pragma("unroll") for (int k = 0; k < 2; ++k) dst[n][k] = *(const PG8_LAS bf16x8*)(lds + PG8_SB(b, h) + boff + n * 2048 + k * 1024); } while (0)
; #define PG8_MMA(ai, bj, At, Bt) do { __builtin_amdgcn_s_setprio(1); _Pragma("unroll") for (int m = 0; m < 4; ++m) _Pragma("unroll") for (int n = 0; n < 2; ++n) _Pragma("unroll") for (int k = 0; k < 2; ++k) \
;         acc[ai][bj][m][n] = __builtin_amdgcn_mfma_f32_16x16x32_bf16(Bt[n][k], At[m][k], acc[ai][bj][m][n], 0, 0, 0); __builtin_amdgcn_s_setprio(0); } while (0)
; #define PG8_WAIT_V(n) asm volatile("s_waitcnt vmcnt(" #n ")" ::: "memory")
; #define PG8_WAIT_L(n) asm volatile("s_waitcnt lgkmcnt(" #n ")" ::: "memory")
; #define PG8_BAR __builtin_amdgcn_s_barrier()
; #define PG8_SCHED __builtin_amdgcn_sched_barrier(0)
; template <class Epi, class Sched, bool ALIGN_EPI = false, bool SP2 = false>
; __device__ __forceinline__ void gemm_phase(PG8_LAS unsigned char* lds, const Gemm g, const Sched& S, const Epi& E) {
;     ...
;             PG8_WAIT_V(8); PG8_WAIT_L(0); PG8_BAR; PG8_MMA(1, 0, At, B0); PG8_MMA(1, 1, At, B1); PG8_BAR; PG8_SCHED;
;             PG8_LDB(B0, 1, 0); PG8_LDB(B1, 1, 1); PG8_SCHED; PG8_LDA(At, 1, 0); PG8_STAGE(PG8_SA(0, 1), a2 + hstepA, voffA);
;             PG8_WAIT_V(8); PG8_WAIT_L(0); PG8_BAR; PG8_MMA(0, 0, At, B0); PG8_MMA(0, 1, At, B1); PG8_BAR; PG8_SCHED;
	s_setprio 1
	v_mfma_f32_16x16x32_bf16 v[60:63], v[140:143], v[182:185], v[60:63]
	v_mfma_f32_16x16x32_bf16 v[56:59], v[158:161], v[182:185], v[56:59]
	v_mfma_f32_16x16x32_bf16 v[44:47], v[140:143], v[192:195], v[44:47]
	v_mfma_f32_16x16x32_bf16 v[40:43], v[158:161], v[192:195], v[40:43]
	v_mfma_f32_16x16x32_bf16 v[28:31], v[140:143], v[200:203], v[28:31]
	v_mfma_f32_16x16x32_bf16 v[24:27], v[158:161], v[200:203], v[24:27]
	v_mfma_f32_16x16x32_bf16 v[12:15], v[140:143], v[208:211], v[12:15]
	v_mfma_f32_16x16x32_bf16 v[8:11], v[158:161], v[208:211], v[8:11]
	v_mfma_f32_16x16x32_bf16 v[60:63], v[154:157], v[188:191], v[60:63]
	v_mfma_f32_16x16x32_bf16 v[56:59], v[162:165], v[188:191], v[56:59]
	v_mfma_f32_16x16x32_bf16 v[44:47], v[154:157], v[196:199], v[44:47]
	v_mfma_f32_16x16x32_bf16 v[40:43], v[162:165], v[196:199], v[40:43]
	v_mfma_f32_16x16x32_bf16 v[28:31], v[154:157], v[204:207], v[28:31]
	v_mfma_f32_16x16x32_bf16 v[24:27], v[162:165], v[204:207], v[24:27]
	v_mfma_f32_16x16x32_bf16 v[12:15], v[154:157], v[212:215], v[12:15]
	v_mfma_f32_16x16x32_bf16 v[8:11], v[162:165], v[212:215], v[8:11]
	s_setprio 1
	v_mfma_f32_16x16x32_bf16 v[52:55], v[166:169], v[182:185], v[52:55]
	v_mfma_f32_16x16x32_bf16 v[48:51], v[174:177], v[182:185], v[48:51]
	v_mfma_f32_16x16x32_bf16 v[36:39], v[166:169], v[192:195], v[36:39]
	v_mfma_f32_16x16x32_bf16 v[32:35], v[174:177], v[192:195], v[32:35]
	v_mfma_f32_16x16x32_bf16 v[20:23], v[166:169], v[200:203], v[20:23]
	v_mfma_f32_16x16x32_bf16 v[16:19], v[174:177], v[200:203], v[16:19]
	v_mfma_f32_16x16x32_bf16 v[4:7], v[166:169], v[208:211], v[4:7]
	v_mfma_f32_16x16x32_bf16 v[0:3], v[174:177], v[208:211], v[0:3]
	v_mfma_f32_16x16x32_bf16 v[52:55], v[170:173], v[188:191], v[52:55]
	v_mfma_f32_16x16x32_bf16 v[48:51], v[178:181], v[188:191], v[48:51]
	v_mfma_f32_16x16x32_bf16 v[36:39], v[170:173], v[196:199], v[36:39]
	v_mfma_f32_16x16x32_bf16 v[32:35], v[178:181], v[196:199], v[32:35]
	v_mfma_f32_16x16x32_bf16 v[20:23], v[170:173], v[204:207], v[20:23]
	v_mfma_f32_16x16x32_bf16 v[16:19], v[178:181], v[204:207], v[16:19]
	v_mfma_f32_16x16x32_bf16 v[4:7], v[170:173], v[212:215], v[4:7]
	v_mfma_f32_16x16x32_bf16 v[0:3], v[178:181], v[212:215], v[0:3]
	s_barrier
	s_setprio 0
	v_add_u32_e32 v153, s95, v147
	ds_read_b128 v[140:143], v153
	ds_read_b128 v[154:157], v153 offset:1024
	ds_read_b128 v[158:161], v153 offset:2048
	ds_read_b128 v[162:165], v153 offset:3072
	v_add_u32_e32 v153, s94, v147
	ds_read_b128 v[166:169], v153
	ds_read_b128 v[170:173], v153 offset:1024
	ds_read_b128 v[174:177], v153 offset:2048
	ds_read_b128 v[178:181], v153 offset:3072
	s_mov_b32 m0, s72
	v_lshl_add_u64 v[222:223], s[38:39], 0, v[134:135]
	ds_read_b128 v[182:185], v151 offset:32768
	ds_read_b128 v[188:191], v151 offset:33792
	ds_read_b128 v[192:195], v151 offset:34816
	ds_read_b128 v[196:199], v151 offset:35840
	ds_read_b128 v[200:203], v151 offset:36864
	ds_read_b128 v[204:207], v151 offset:37888
	ds_read_b128 v[208:211], v151 offset:38912
	ds_read_b128 v[212:215], v151 offset:39936
	global_load_lds_dwordx4 v[222:223], off
	v_lshl_add_u64 v[222:223], s[38:39], 0, v[130:131]
	s_mov_b32 m0, s73
	s_nop 0
	global_load_lds_dwordx4 v[222:223], off
	s_waitcnt vmcnt(8)
	s_waitcnt lgkmcnt(0)
	s_barrier
	s_setprio 1
	v_mfma_f32_16x16x32_bf16 v[124:127], v[140:143], v[182:185], v[124:127]
	v_mfma_f32_16x16x32_bf16 v[120:123], v[158:161], v[182:185], v[120:123]
	v_mfma_f32_16x16x32_bf16 v[108:111], v[140:143], v[192:195], v[108:111]
	v_mfma_f32_16x16x32_bf16 v[104:107], v[158:161], v[192:195], v[104:107]
	v_mfma_f32_16x16x32_bf16 v[92:95], v[140:143], v[200:203], v[92:95]
	v_mfma_f32_16x16x32_bf16 v[88:91], v[158:161], v[200:203], v[88:91]
	v_mfma_f32_16x16x32_bf16 v[76:79], v[140:143], v[208:211], v[76:79]
	v_mfma_f32_16x16x32_bf16 v[72:75], v[158:161], v[208:211], v[72:75]
	v_mfma_f32_16x16x32_bf16 v[124:127], v[154:157], v[188:191], v[124:127]
	v_mfma_f32_16x16x32_bf16 v[120:123], v[162:165], v[188:191], v[120:123]
	v_mfma_f32_16x16x32_bf16 v[108:111], v[154:157], v[196:199], v[108:111]
	v_mfma_f32_16x16x32_bf16 v[104:107], v[162:165], v[196:199], v[104:107]
	v_mfma_f32_16x16x32_bf16 v[92:95], v[154:157], v[204:207], v[92:95]
	v_mfma_f32_16x16x32_bf16 v[88:91], v[162:165], v[204:207], v[88:91]
	v_mfma_f32_16x16x32_bf16 v[76:79], v[154:157], v[212:215], v[76:79]
	v_mfma_f32_16x16x32_bf16 v[72:75], v[162:165], v[212:215], v[72:75]
	s_setprio 1
	v_mfma_f32_16x16x32_bf16 v[116:119], v[166:169], v[182:185], v[116:119]
	v_mfma_f32_16x16x32_bf16 v[112:115], v[174:177], v[182:185], v[112:115]
	v_mfma_f32_16x16x32_bf16 v[100:103], v[166:169], v[192:195], v[100:103]
	v_mfma_f32_16x16x32_bf16 v[96:99], v[174:177], v[192:195], v[96:99]
	v_mfma_f32_16x16x32_bf16 v[84:87], v[166:169], v[200:203], v[84:87]
	v_mfma_f32_16x16x32_bf16 v[80:83], v[174:177], v[200:203], v[80:83]
	v_mfma_f32_16x16x32_bf16 v[68:71], v[166:169], v[208:211], v[68:71]
	v_mfma_f32_16x16x32_bf16 v[64:67], v[174:177], v[208:211], v[64:67]
	v_mfma_f32_16x16x32_bf16 v[116:119], v[170:173], v[188:191], v[116:119]
	v_mfma_f32_16x16x32_bf16 v[112:115], v[178:181], v[188:191], v[112:115]
	v_mfma_f32_16x16x32_bf16 v[100:103], v[170:173], v[196:199], v[100:103]
	v_mfma_f32_16x16x32_bf16 v[96:99], v[178:181], v[196:199], v[96:99]
	v_mfma_f32_16x16x32_bf16 v[84:87], v[170:173], v[204:207], v[84:87]
	v_mfma_f32_16x16x32_bf16 v[80:83], v[178:181], v[204:207], v[80:83]
	v_mfma_f32_16x16x32_bf16 v[68:71], v[170:173], v[212:215], v[68:71]
	v_mfma_f32_16x16x32_bf16 v[64:67], v[178:181], v[212:215], v[64:67]
	s_barrier
; #define PG8_STAGE(bufoff, gbase, voff) do { _Pragma("unroll") for (int _i = 0; _i < 2; ++_i) \
;         __builtin_amdgcn_global_load_lds((const unsigned*)((const char*)(gbase) + (voff)[_i]), (PG8_LAS unsigned*)(lds + (bufoff) + ldsw + _i * 8192), 16, 0, 0); } while (0)
; #define PG8_LDA(dst, b, h) do { _Pragma("unroll") for (int m = 0; m < 4; ++m) _Pragma("unroll") for (int k = 0; k < 2; ++k) dst[m][k] = *(const PG8_LAS bf16x8*)(lds + PG8_SA(b, h) + aoff + m * 2048 + k * 1024); } while (0)
; #define PG8_MMA(ai, bj, At, Bt) do { __builtin_amdgcn_s_setprio(1); _Pragma("unroll") for (int m = 0; m < 4; ++m) _Pragma("unroll") for (int n = 0; n < 2; ++n) _Pragma("unroll") for (int k = 0; k < 2; ++k) \
;         acc[ai][bj][m][n] = __builtin_amdgcn_mfma_f32_16x16x32_bf16(Bt[n][k], At[m][k], acc[ai][bj][m][n], 0, 0, 0); __builtin_amdgcn_s_setprio(0); } while (0)
; #define PG8_WAIT_V(n) asm volatile("s_waitcnt vmcnt(" #n ")" ::: "memory")
; #define PG8_WAIT_L(n) asm volatile("s_waitcnt lgkmcnt(" #n ")" ::: "memory")
; #define PG8_BAR __builtin_amdgcn_s_barrier()
; #define PG8_SCHED __builtin_amdgcn_sched_barrier(0)
; template <class Epi, class Sched, bool ALIGN_EPI = false, bool SP2 = false>
; __device__ __forceinline__ void gemm_phase(PG8_LAS unsigned char* lds, const Gemm g, const Sched& S, const Epi& E) {
;     ...
;         for (int t = 0; t < nt; t += 2) {
;             const bool last = (t == nt - 2);
;     ...
;             PG8_LDA(At, 1, 1); PG8_STAGE(PG8_SB(1, 0), b3, voffB); PG8_STAGE(PG8_SB(1, 1), b3 + hstepB, voffB); PG8_STAGE(PG8_SA(1, 0), a3, voffA);
;             PG8_WAIT_V(8); PG8_WAIT_L(0); PG8_BAR; PG8_MMA(1, 0, At, B0); PG8_MMA(1, 1, At, B1); PG8_BAR; PG8_SCHED;
	s_setprio 0
	s_mov_b32 m0, s93
	v_lshl_add_u64 v[144:145], v[144:145], 0, s[12:13]
	ds_read_b128 v[182:185], v151 offset:49152
	ds_read_b128 v[188:191], v151 offset:50176
	ds_read_b128 v[192:195], v151 offset:51200
	ds_read_b128 v[196:199], v151 offset:52224
	ds_read_b128 v[200:203], v151 offset:53248
	ds_read_b128 v[204:207], v151 offset:54272
	ds_read_b128 v[208:211], v151 offset:55296
	ds_read_b128 v[212:215], v151 offset:56320
	global_load_lds_dwordx4 v[144:145], off
	v_lshl_add_u64 v[144:145], v[216:217], 0, s[12:13]
	s_mov_b32 m0, s91
	s_nop 0
	global_load_lds_dwordx4 v[144:145], off
	v_lshl_add_u64 v[144:145], s[36:37], 0, v[132:133]
	s_mov_b32 m0, s92
	s_nop 0
	global_load_lds_dwordx4 v[144:145], off
	v_lshl_add_u64 v[144:145], s[36:37], 0, v[128:129]
	s_mov_b32 m0, s90
	s_nop 0
	global_load_lds_dwordx4 v[144:145], off
	v_lshl_add_u64 v[144:145], v[218:219], 0, s[12:13]
	s_mov_b32 m0, s75
	s_nop 0
	global_load_lds_dwordx4 v[144:145], off
	v_lshl_add_u64 v[144:145], v[220:221], 0, s[12:13]
	s_mov_b32 m0, s76
	s_nop 0
	global_load_lds_dwordx4 v[144:145], off
	s_waitcnt vmcnt(8)
	s_waitcnt lgkmcnt(0)
	s_barrier
	s_setprio 1
	v_mfma_f32_16x16x32_bf16 v[60:63], v[140:143], v[182:185], v[60:63]
	v_mfma_f32_16x16x32_bf16 v[56:59], v[158:161], v[182:185], v[56:59]
	v_mfma_f32_16x16x32_bf16 v[44:47], v[140:143], v[192:195], v[44:47]
	v_mfma_f32_16x16x32_bf16 v[40:43], v[158:161], v[192:195], v[40:43]
	v_mfma_f32_16x16x32_bf16 v[28:31], v[140:143], v[200:203], v[28:31]
	v_mfma_f32_16x16x32_bf16 v[24:27], v[158:161], v[200:203], v[24:27]
	v_mfma_f32_16x16x32_bf16 v[12:15], v[140:143], v[208:211], v[12:15]
	v_mfma_f32_16x16x32_bf16 v[8:11], v[158:161], v[208:211], v[8:11]
	v_mfma_f32_16x16x32_bf16 v[60:63], v[154:157], v[188:191], v[60:63]
	v_mfma_f32_16x16x32_bf16 v[56:59], v[162:165], v[188:191], v[56:59]
	v_mfma_f32_16x16x32_bf16 v[44:47], v[154:157], v[196:199], v[44:47]
	v_mfma_f32_16x16x32_bf16 v[40:43], v[162:165], v[196:199], v[40:43]
	v_mfma_f32_16x16x32_bf16 v[28:31], v[154:157], v[204:207], v[28:31]
	v_mfma_f32_16x16x32_bf16 v[24:27], v[162:165], v[204:207], v[24:27]
	v_mfma_f32_16x16x32_bf16 v[12:15], v[154:157], v[212:215], v[12:15]
	v_mfma_f32_16x16x32_bf16 v[8:11], v[162:165], v[212:215], v[8:11]
	s_setprio 1
	v_mfma_f32_16x16x32_bf16 v[52:55], v[166:169], v[182:185], v[52:55]
	v_mfma_f32_16x16x32_bf16 v[48:51], v[174:177], v[182:185], v[48:51]
	v_mfma_f32_16x16x32_bf16 v[36:39], v[166:169], v[192:195], v[36:39]
	v_mfma_f32_16x16x32_bf16 v[32:35], v[174:177], v[192:195], v[32:35]
	v_mfma_f32_16x16x32_bf16 v[20:23], v[166:169], v[200:203], v[20:23]
	v_mfma_f32_16x16x32_bf16 v[16:19], v[174:177], v[200:203], v[16:19]
	v_mfma_f32_16x16x32_bf16 v[4:7], v[166:169], v[208:211], v[4:7]
	v_mfma_f32_16x16x32_bf16 v[0:3], v[174:177], v[208:211], v[0:3]
	v_mfma_f32_16x16x32_bf16 v[52:55], v[170:173], v[188:191], v[52:55]
	v_mfma_f32_16x16x32_bf16 v[48:51], v[178:181], v[188:191], v[48:51]
	v_mfma_f32_16x16x32_bf16 v[36:39], v[170:173], v[196:199], v[36:39]
	v_mfma_f32_16x16x32_bf16 v[32:35], v[178:181], v[196:199], v[32:35]
	v_mfma_f32_16x16x32_bf16 v[20:23], v[170:173], v[204:207], v[20:23]
	v_mfma_f32_16x16x32_bf16 v[16:19], v[178:181], v[204:207], v[16:19]
	v_mfma_f32_16x16x32_bf16 v[4:7], v[170:173], v[212:215], v[4:7]
	v_mfma_f32_16x16x32_bf16 v[0:3], v[178:181], v[212:215], v[0:3]
	s_barrier
	s_setprio 0
	s_movk_i32 s38, 0x100
	s_andn2_b64 vcc, exec, s[8:9]
	s_mov_b64 s[36:37], -1
	s_mov_b64 s[8:9], 0
	s_cbranch_vccz .LBB0_542
	s_and_b64 vcc, exec, s[14:15]
	s_cbranch_vccz .LBB0_545
	s_barrier

; #define PG8_STAGE(bufoff, gbase, voff) do { _Pragma("unroll") for (int _i = 0; _i < 2; ++_i) \
;         __builtin_amdgcn_global_load_lds((const unsigned*)((const char*)(gbase) + (voff)[_i]), (PG8_LAS unsigned*)(lds + (bufoff) + ldsw + _i * 8192), 16, 0, 0); } while (0)
; #define PG8_LDA(dst, b, h) do { _Pragma("unroll") for (int m = 0; m < 4; ++m) _Pragma("unroll") for (int k = 0; k < 2; ++k) dst[m][k] = *(const PG8_LAS bf16x8*)(lds + PG8_SA(b, h) + aoff + m * 2048 + k * 1024); } while (0)
; #define PG8_LDB(dst, b, h) do { _Pragma("unroll") for (int n = 0; n < 2; ++n) _Pragma("unroll") for (int k = 0; k < 2; ++k) dst[n][k] = *(const PG8_LAS bf16x8*)(lds + PG8_SB(b, h) + boff + n * 2048 + k * 1024); } while (0)
; #define PG8_MMA(ai, bj, At, Bt) do { __builtin_amdgcn_s_setprio(1); _Pragma("unroll") for (int m = 0; m < 4; ++m) _Pragma("unroll") for (int n = 0; n < 2; ++n) _Pragma("unroll") for (int k = 0; k < 2; ++k) \
;         acc[ai][bj][m][n] = __builtin_amdgcn_mfma_f32_16x16x32_bf16(Bt[n][k], At[m][k], acc[ai][bj][m][n], 0, 0, 0); __builtin_amdgcn_s_setprio(0); } while (0)
; #define PG8_WAIT_V(n) asm volatile("s_waitcnt vmcnt(" #n ")" ::: "memory")
; #define PG8_WAIT_L(n) asm volatile("s_waitcnt lgkmcnt(" #n ")" ::: "memory")
; #define PG8_BAR __builtin_amdgcn_s_barrier()
; template <class Epi, class Sched, bool ALIGN_EPI = false, bool SP2 = false>
; __device__ __forceinline__ void gemm_phase(PG8_LAS unsigned char* lds, const Gemm g, const Sched& S, const Epi& E) {
;     ...
;             const char* a1 = cA + (size_t)(t + 1) * kstep;
;             const char* a2 = last ? nA : cA + (size_t)(t + 2) * kstep; const char* b2 = last ? nB : cB + (size_t)(t + 2) * kstep;
;             const char* a3 = a2 + kstep; const char* b3 = b2 + kstep;
;             if (last && has_next) S.a_ready(nxt);
;             if constexpr (SP2) {
;             PG8_LDB(B0, 0, 0); PG8_LDB(B1, 0, 1); PG8_SCHED; PG8_LDA(At, 0, 0); PG8_STAGE(PG8_SA(1, 1), a1 + hstepA, voffA);
;             PG8_WAIT_V(8); PG8_WAIT_L(0); PG8_BAR; PG8_MMA(0, 0, At, B0); PG8_MMA(0, 1, At, B1); PG8_BAR; PG8_SCHED;
;             PG8_LDA(At, 0, 1); PG8_STAGE(PG8_SB(0, 0), b2, voffB); PG8_STAGE(PG8_SB(0, 1), b2 + hstepB, voffB); PG8_STAGE(PG8_SA(0, 0), a2, voffA);
;             PG8_WAIT_V(8); PG8_WAIT_L(0); PG8_BAR; PG8_MMA(1, 0, At, B0); PG8_MMA(1, 1, At, B1); PG8_BAR; PG8_SCHED;
.LBB0_971:
	ds_read_b128 v[128:131], v191
	ds_read_b128 v[132:135], v191 offset:1024
	ds_read_b128 v[136:139], v191 offset:2048
	ds_read_b128 v[140:143], v191 offset:3072
	ds_read_b128 v[144:147], v192
	ds_read_b128 v[148:151], v192 offset:1024
	ds_read_b128 v[168:171], v192 offset:2048
	ds_read_b128 v[172:175], v192 offset:3072
	s_add_u32 s34, s30, 0xfffc0080
	s_addc_u32 s35, s31, -1
	s_cmp_eq_u32 s74, 12
	s_cselect_b32 s37, s21, s35
	s_cselect_b32 s36, s27, s34
	s_cselect_b32 s35, s19, s73
	s_cselect_b32 s34, s68, s69
	v_lshl_add_u64 v[184:185], s[30:31], 0, v[160:161]
	s_add_i32 m0, s29, 0xc000
	ds_read_b128 v[176:179], v193
	ds_read_b128 v[180:183], v193 offset:1024
	ds_read_b128 v[196:199], v193 offset:2048
	ds_read_b128 v[200:203], v193 offset:3072
	ds_read_b128 v[204:207], v193 offset:4096
	ds_read_b128 v[208:211], v193 offset:5120
	ds_read_b128 v[212:215], v193 offset:6144
	ds_read_b128 v[216:219], v193 offset:7168
	global_load_lds_dwordx4 v[184:185], off
	v_lshl_add_u64 v[184:185], s[30:31], 0, v[162:163]
	s_add_i32 m0, s29, 0xe000
	s_nop 0
	global_load_lds_dwordx4 v[184:185], off
	s_waitcnt vmcnt(8)
	s_waitcnt lgkmcnt(0)
	s_barrier
	s_setprio 1
	v_mfma_f32_16x16x32_bf16 v[124:127], v[128:131], v[176:179], v[124:127]
	v_mfma_f32_16x16x32_bf16 v[120:123], v[136:139], v[176:179], v[120:123]
	v_mfma_f32_16x16x32_bf16 v[108:111], v[128:131], v[196:199], v[108:111]
	v_mfma_f32_16x16x32_bf16 v[104:107], v[136:139], v[196:199], v[104:107]
	v_mfma_f32_16x16x32_bf16 v[92:95], v[128:131], v[204:207], v[92:95]
	v_mfma_f32_16x16x32_bf16 v[88:91], v[136:139], v[204:207], v[88:91]
	v_mfma_f32_16x16x32_bf16 v[76:79], v[128:131], v[212:215], v[76:79]
	v_mfma_f32_16x16x32_bf16 v[72:75], v[136:139], v[212:215], v[72:75]
	v_mfma_f32_16x16x32_bf16 v[124:127], v[132:135], v[180:183], v[124:127]
	v_mfma_f32_16x16x32_bf16 v[120:123], v[140:143], v[180:183], v[120:123]
	v_mfma_f32_16x16x32_bf16 v[108:111], v[132:135], v[200:203], v[108:111]
	v_mfma_f32_16x16x32_bf16 v[104:107], v[140:143], v[200:203], v[104:107]
	v_mfma_f32_16x16x32_bf16 v[92:95], v[132:135], v[208:211], v[92:95]
	v_mfma_f32_16x16x32_bf16 v[88:91], v[140:143], v[208:211], v[88:91]
	v_mfma_f32_16x16x32_bf16 v[76:79], v[132:135], v[216:219], v[76:79]
	v_mfma_f32_16x16x32_bf16 v[72:75], v[140:143], v[216:219], v[72:75]
	s_setprio 1
	v_mfma_f32_16x16x32_bf16 v[116:119], v[144:147], v[176:179], v[116:119]
	v_mfma_f32_16x16x32_bf16 v[112:115], v[168:171], v[176:179], v[112:115]
	v_mfma_f32_16x16x32_bf16 v[100:103], v[144:147], v[196:199], v[100:103]
	v_mfma_f32_16x16x32_bf16 v[96:99], v[168:171], v[196:199], v[96:99]
	v_mfma_f32_16x16x32_bf16 v[84:87], v[144:147], v[204:207], v[84:87]
	v_mfma_f32_16x16x32_bf16 v[80:83], v[168:171], v[204:207], v[80:83]
	v_mfma_f32_16x16x32_bf16 v[68:71], v[144:147], v[212:215], v[68:71]
	v_mfma_f32_16x16x32_bf16 v[64:67], v[168:171], v[212:215], v[64:67]
	v_mfma_f32_16x16x32_bf16 v[116:119], v[148:151], v[180:183], v[116:119]
	v_mfma_f32_16x16x32_bf16 v[112:115], v[172:175], v[180:183], v[112:115]
	v_mfma_f32_16x16x32_bf16 v[100:103], v[148:151], v[200:203], v[100:103]
	v_mfma_f32_16x16x32_bf16 v[96:99], v[172:175], v[200:203], v[96:99]
	v_mfma_f32_16x16x32_bf16 v[84:87], v[148:151], v[208:211], v[84:87]
	v_mfma_f32_16x16x32_bf16 v[80:83], v[172:175], v[208:211], v[80:83]
	v_mfma_f32_16x16x32_bf16 v[68:71], v[148:151], v[216:219], v[68:71]
	v_mfma_f32_16x16x32_bf16 v[64:67], v[172:175], v[216:219], v[64:67]
	s_barrier
	s_setprio 0
	s_add_i32 s58, s49, s39
	v_lshl_add_u64 v[184:185], s[34:35], 0, v[154:155]
	s_mov_b32 m0, s58
	ds_read_b128 v[176:179], v193 offset:16384
	ds_read_b128 v[180:183], v193 offset:17408
	ds_read_b128 v[196:199], v193 offset:18432
	ds_read_b128 v[200:203], v193 offset:19456
	ds_read_b128 v[204:207], v193 offset:20480
	ds_read_b128 v[208:211], v193 offset:21504
	ds_read_b128 v[212:215], v193 offset:22528
	ds_read_b128 v[216:219], v193 offset:23552
	global_load_lds_dwordx4 v[184:185], off
	s_add_i32 m0, s58, 0x2000
	s_add_u32 s58, s34, 0x40000
	v_lshl_add_u64 v[220:221], s[34:35], 0, v[158:159]
	s_addc_u32 s59, s35, 0
	s_add_i32 s75, s66, s39
	global_load_lds_dwordx4 v[220:221], off
	v_lshl_add_u64 v[222:223], s[58:59], 0, v[154:155]
	s_mov_b32 m0, s75
	v_lshl_add_u64 v[224:225], s[36:37], 0, v[156:157]
	global_load_lds_dwordx4 v[222:223], off
	v_lshl_add_u64 v[222:223], s[58:59], 0, v[158:159]
	s_add_i32 m0, s75, 0x2000
	s_nop 0
	global_load_lds_dwordx4 v[222:223], off
	v_lshl_add_u64 v[222:223], s[36:37], 0, v[152:153]
	s_mov_b32 m0, s29
	s_nop 0
	global_load_lds_dwordx4 v[222:223], off
	s_mov_b32 m0, s40
	s_nop 0
	global_load_lds_dwordx4 v[224:225], off
	s_waitcnt vmcnt(8)
	s_waitcnt lgkmcnt(0)
	s_barrier
; #define PG8_STAGE(bufoff, gbase, voff) do { _Pragma("unroll") for (int _i = 0; _i < 2; ++_i) \
;         __builtin_amdgcn_global_load_lds((const unsigned*)((const char*)(gbase) + (voff)[_i]), (PG8_LAS unsigned*)(lds + (bufoff) + ldsw + _i * 8192), 16, 0, 0); } while (0)
; #define PG8_LDA(dst, b, h) do { _Pragma("unroll") for (int m = 0; m < 4; ++m) _Pragma("unroll") for (int k = 0; k < 2; ++k) dst[m][k] = *(const PG8_LAS bf16x8*)(lds + PG8_SA(b, h) + aoff + m * 2048 + k * 1024); } while (0)
; #define PG8_LDB(dst, b, h) do { _Pragma("unroll") for (int n = 0; n < 2; ++n) _Pragma("unroll") for (int k = 0; k < 2; ++k) dst[n][k] = *(const PG8_LAS bf16x8*)(lds + PG8_SB(b, h) + boff + n * 2048 + k * 1024); } while (0)
; #define PG8_MMA(ai, bj, At, Bt) do { __builtin_amdgcn_s_setprio(1); _Pragma("unroll") for (int m = 0; m < 4; ++m) _Pragma("unroll") for (int n = 0; n < 2; ++n) _Pragma("unroll") for (int k = 0; k < 2; ++k) \
;         acc[ai][bj][m][n] = __builtin_amdgcn_mfma_f32_16x16x32_bf16(Bt[n][k], At[m][k], acc[ai][bj][m][n], 0, 0, 0); __builtin_amdgcn_s_setprio(0); } while (0)
; #define PG8_WAIT_V(n) asm volatile("s_waitcnt vmcnt(" #n ")" ::: "memory")
; #define PG8_WAIT_L(n) asm volatile("s_waitcnt lgkmcnt(" #n ")" ::: "memory")
; #define PG8_BAR __builtin_amdgcn_s_barrier()
; #define PG8_SCHED __builtin_amdgcn_sched_barrier(0)
; template <class Epi, class Sched, bool ALIGN_EPI = false, bool SP2 = false>
; __device__ __forceinline__ void gemm_phase(PG8_LAS unsigned char* lds, const Gemm g, const Sched& S, const Epi& E) {
;     ...
;             PG8_WAIT_V(8); PG8_WAIT_L(0); PG8_BAR; PG8_MMA(1, 0, At, B0); PG8_MMA(1, 1, At, B1); PG8_BAR; PG8_SCHED;
;             PG8_LDB(B0, 1, 0); PG8_LDB(B1, 1, 1); PG8_SCHED; PG8_LDA(At, 1, 0); PG8_STAGE(PG8_SA(0, 1), a2 + hstepA, voffA);
;             PG8_WAIT_V(8); PG8_WAIT_L(0); PG8_BAR; PG8_MMA(0, 0, At, B0); PG8_MMA(0, 1, At, B1); PG8_BAR; PG8_SCHED;
	s_setprio 1
	v_mfma_f32_16x16x32_bf16 v[60:63], v[128:131], v[176:179], v[60:63]
	v_mfma_f32_16x16x32_bf16 v[56:59], v[136:139], v[176:179], v[56:59]
	v_mfma_f32_16x16x32_bf16 v[44:47], v[128:131], v[196:199], v[44:47]
	v_mfma_f32_16x16x32_bf16 v[40:43], v[136:139], v[196:199], v[40:43]
	v_mfma_f32_16x16x32_bf16 v[28:31], v[128:131], v[204:207], v[28:31]
	v_mfma_f32_16x16x32_bf16 v[24:27], v[136:139], v[204:207], v[24:27]
	v_mfma_f32_16x16x32_bf16 v[12:15], v[128:131], v[212:215], v[12:15]
	v_mfma_f32_16x16x32_bf16 v[8:11], v[136:139], v[212:215], v[8:11]
	v_mfma_f32_16x16x32_bf16 v[60:63], v[132:135], v[180:183], v[60:63]
	v_mfma_f32_16x16x32_bf16 v[56:59], v[140:143], v[180:183], v[56:59]
	v_mfma_f32_16x16x32_bf16 v[44:47], v[132:135], v[200:203], v[44:47]
	v_mfma_f32_16x16x32_bf16 v[40:43], v[140:143], v[200:203], v[40:43]
	v_mfma_f32_16x16x32_bf16 v[28:31], v[132:135], v[208:211], v[28:31]
	v_mfma_f32_16x16x32_bf16 v[24:27], v[140:143], v[208:211], v[24:27]
	v_mfma_f32_16x16x32_bf16 v[12:15], v[132:135], v[216:219], v[12:15]
	v_mfma_f32_16x16x32_bf16 v[8:11], v[140:143], v[216:219], v[8:11]
	s_setprio 1
	v_mfma_f32_16x16x32_bf16 v[52:55], v[144:147], v[176:179], v[52:55]
	v_mfma_f32_16x16x32_bf16 v[48:51], v[168:171], v[176:179], v[48:51]
	v_mfma_f32_16x16x32_bf16 v[36:39], v[144:147], v[196:199], v[36:39]
	v_mfma_f32_16x16x32_bf16 v[32:35], v[168:171], v[196:199], v[32:35]
	v_mfma_f32_16x16x32_bf16 v[20:23], v[144:147], v[204:207], v[20:23]
	v_mfma_f32_16x16x32_bf16 v[16:19], v[168:171], v[204:207], v[16:19]
	v_mfma_f32_16x16x32_bf16 v[4:7], v[144:147], v[212:215], v[4:7]
	v_mfma_f32_16x16x32_bf16 v[0:3], v[168:171], v[212:215], v[0:3]
	v_mfma_f32_16x16x32_bf16 v[52:55], v[148:151], v[180:183], v[52:55]
	v_mfma_f32_16x16x32_bf16 v[48:51], v[172:175], v[180:183], v[48:51]
	v_mfma_f32_16x16x32_bf16 v[36:39], v[148:151], v[200:203], v[36:39]
	v_mfma_f32_16x16x32_bf16 v[32:35], v[172:175], v[200:203], v[32:35]
	v_mfma_f32_16x16x32_bf16 v[20:23], v[148:151], v[208:211], v[20:23]
	v_mfma_f32_16x16x32_bf16 v[16:19], v[172:175], v[208:211], v[16:19]
	v_mfma_f32_16x16x32_bf16 v[4:7], v[148:151], v[216:219], v[4:7]
	v_mfma_f32_16x16x32_bf16 v[0:3], v[172:175], v[216:219], v[0:3]
	s_barrier
	s_setprio 0
	s_add_i32 s58, 0, 0x18000
	s_add_i32 s59, 0, 0x1c000
	v_add_u32_e32 v140, s58, v189
	v_add_u32_e32 v172, s59, v189
	ds_read_b128 v[128:131], v140
	ds_read_b128 v[132:135], v140 offset:1024
	ds_read_b128 v[136:139], v140 offset:2048
	ds_read_b128 v[140:143], v140 offset:3072
	ds_read_b128 v[144:147], v172
	ds_read_b128 v[148:151], v172 offset:1024
	ds_read_b128 v[168:171], v172 offset:2048
	ds_read_b128 v[172:175], v172 offset:3072
	s_add_u32 s36, s36, 0x40000
	s_addc_u32 s37, s37, 0
	s_mov_b32 m0, s41
	v_lshl_add_u64 v[226:227], s[36:37], 0, v[152:153]
	ds_read_b128 v[176:179], v193 offset:32768
	ds_read_b128 v[180:183], v193 offset:33792
	ds_read_b128 v[196:199], v193 offset:34816
	ds_read_b128 v[200:203], v193 offset:35840
	ds_read_b128 v[204:207], v193 offset:36864
	ds_read_b128 v[208:211], v193 offset:37888
	ds_read_b128 v[212:215], v193 offset:38912
	ds_read_b128 v[216:219], v193 offset:39936
	global_load_lds_dwordx4 v[226:227], off
	v_lshl_add_u64 v[226:227], s[36:37], 0, v[156:157]
	s_mov_b32 m0, s42
	s_nop 0
	global_load_lds_dwordx4 v[226:227], off
	s_waitcnt vmcnt(8)
	s_waitcnt lgkmcnt(0)
	s_barrier
	s_setprio 1
	v_mfma_f32_16x16x32_bf16 v[124:127], v[128:131], v[176:179], v[124:127]
	v_mfma_f32_16x16x32_bf16 v[120:123], v[136:139], v[176:179], v[120:123]
	v_mfma_f32_16x16x32_bf16 v[108:111], v[128:131], v[196:199], v[108:111]
	v_mfma_f32_16x16x32_bf16 v[104:107], v[136:139], v[196:199], v[104:107]
	v_mfma_f32_16x16x32_bf16 v[92:95], v[128:131], v[204:207], v[92:95]
	v_mfma_f32_16x16x32_bf16 v[88:91], v[136:139], v[204:207], v[88:91]
	v_mfma_f32_16x16x32_bf16 v[76:79], v[128:131], v[212:215], v[76:79]
	v_mfma_f32_16x16x32_bf16 v[72:75], v[136:139], v[212:215], v[72:75]
	v_mfma_f32_16x16x32_bf16 v[124:127], v[132:135], v[180:183], v[124:127]
	v_mfma_f32_16x16x32_bf16 v[120:123], v[140:143], v[180:183], v[120:123]
	v_mfma_f32_16x16x32_bf16 v[108:111], v[132:135], v[200:203], v[108:111]
	v_mfma_f32_16x16x32_bf16 v[104:107], v[140:143], v[200:203], v[104:107]
	v_mfma_f32_16x16x32_bf16 v[92:95], v[132:135], v[208:211], v[92:95]
	v_mfma_f32_16x16x32_bf16 v[88:91], v[140:143], v[208:211], v[88:91]
	v_mfma_f32_16x16x32_bf16 v[76:79], v[132:135], v[216:219], v[76:79]
	v_mfma_f32_16x16x32_bf16 v[72:75], v[140:143], v[216:219], v[72:75]
	s_setprio 1
	v_mfma_f32_16x16x32_bf16 v[116:119], v[144:147], v[176:179], v[116:119]
	v_mfma_f32_16x16x32_bf16 v[112:115], v[168:171], v[176:179], v[112:115]
	v_mfma_f32_16x16x32_bf16 v[100:103], v[144:147], v[196:199], v[100:103]
	v_mfma_f32_16x16x32_bf16 v[96:99], v[168:171], v[196:199], v[96:99]
	v_mfma_f32_16x16x32_bf16 v[84:87], v[144:147], v[204:207], v[84:87]
	v_mfma_f32_16x16x32_bf16 v[80:83], v[168:171], v[204:207], v[80:83]
	v_mfma_f32_16x16x32_bf16 v[68:71], v[144:147], v[212:215], v[68:71]
	v_mfma_f32_16x16x32_bf16 v[64:67], v[168:171], v[212:215], v[64:67]
	v_mfma_f32_16x16x32_bf16 v[116:119], v[148:151], v[180:183], v[116:119]
	v_mfma_f32_16x16x32_bf16 v[112:115], v[172:175], v[180:183], v[112:115]
	v_mfma_f32_16x16x32_bf16 v[100:103], v[148:151], v[200:203], v[100:103]
	v_mfma_f32_16x16x32_bf16 v[96:99], v[172:175], v[200:203], v[96:99]
	v_mfma_f32_16x16x32_bf16 v[84:87], v[148:151], v[208:211], v[84:87]
	v_mfma_f32_16x16x32_bf16 v[80:83], v[172:175], v[208:211], v[80:83]
	v_mfma_f32_16x16x32_bf16 v[68:71], v[148:151], v[216:219], v[68:71]
	v_mfma_f32_16x16x32_bf16 v[64:67], v[172:175], v[216:219], v[64:67]
	s_barrier
; #define PG8_STAGE(bufoff, gbase, voff) do { _Pragma("unroll") for (int _i = 0; _i < 2; ++_i) \
;         __builtin_amdgcn_global_load_lds((const unsigned*)((const char*)(gbase) + (voff)[_i]), (PG8_LAS unsigned*)(lds + (bufoff) + ldsw + _i * 8192), 16, 0, 0); } while (0)
; #define PG8_LDA(dst, b, h) do { _Pragma("unroll") for (int m = 0; m < 4; ++m) _Pragma("unroll") for (int k = 0; k < 2; ++k) dst[m][k] = *(const PG8_LAS bf16x8*)(lds + PG8_SA(b, h) + aoff + m * 2048 + k * 1024); } while (0)
; #define PG8_MMA(ai, bj, At, Bt) do { __builtin_amdgcn_s_setprio(1); _Pragma("unroll") for (int m = 0; m < 4; ++m) _Pragma("unroll") for (int n = 0; n < 2; ++n) _Pragma("unroll") for (int k = 0; k < 2; ++k) \
;         acc[ai][bj][m][n] = __builtin_amdgcn_mfma_f32_16x16x32_bf16(Bt[n][k], At[m][k], acc[ai][bj][m][n], 0, 0, 0); __builtin_amdgcn_s_setprio(0); } while (0)
; #define PG8_WAIT_V(n) asm volatile("s_waitcnt vmcnt(" #n ")" ::: "memory")
; #define PG8_WAIT_L(n) asm volatile("s_waitcnt lgkmcnt(" #n ")" ::: "memory")
; #define PG8_BAR __builtin_amdgcn_s_barrier()
; #define PG8_SCHED __builtin_amdgcn_sched_barrier(0)
; template <class Epi, class Sched, bool ALIGN_EPI = false, bool SP2 = false>
; __device__ __forceinline__ void gemm_phase(PG8_LAS unsigned char* lds, const Gemm g, const Sched& S, const Epi& E) {
;     ...
;         for (int t = 0; t < nt; t += 2) {
;             const bool last = (t == nt - 2);
;     ...
;             PG8_LDA(At, 1, 1); PG8_STAGE(PG8_SB(1, 0), b3, voffB); PG8_STAGE(PG8_SB(1, 1), b3 + hstepB, voffB); PG8_STAGE(PG8_SA(1, 0), a3, voffA);
;             PG8_WAIT_V(8); PG8_WAIT_L(0); PG8_BAR; PG8_MMA(1, 0, At, B0); PG8_MMA(1, 1, At, B1); PG8_BAR; PG8_SCHED;
	s_setprio 0
	s_add_i32 s36, s58, s39
	v_lshl_add_u64 v[184:185], v[184:185], 0, s[14:15]
	s_mov_b32 m0, s36
	ds_read_b128 v[176:179], v193 offset:49152
	ds_read_b128 v[180:183], v193 offset:50176
	ds_read_b128 v[196:199], v193 offset:51200
	ds_read_b128 v[200:203], v193 offset:52224
	ds_read_b128 v[204:207], v193 offset:53248
	ds_read_b128 v[208:211], v193 offset:54272
	ds_read_b128 v[212:215], v193 offset:55296
	ds_read_b128 v[216:219], v193 offset:56320
	global_load_lds_dwordx4 v[184:185], off
	s_add_i32 m0, s36, 0x2000
	s_add_u32 s34, s34, 0x40080
	v_lshl_add_u64 v[184:185], v[220:221], 0, s[14:15]
	s_addc_u32 s35, s35, 0
	s_add_i32 s36, s59, s39
	global_load_lds_dwordx4 v[184:185], off
	v_lshl_add_u64 v[184:185], s[34:35], 0, v[154:155]
	s_mov_b32 m0, s36
	s_nop 0
	global_load_lds_dwordx4 v[184:185], off
	v_lshl_add_u64 v[184:185], s[34:35], 0, v[158:159]
	s_add_i32 m0, s36, 0x2000
	s_nop 0
	global_load_lds_dwordx4 v[184:185], off
	v_lshl_add_u64 v[184:185], v[222:223], 0, s[14:15]
	s_mov_b32 m0, s44
	s_nop 0
	global_load_lds_dwordx4 v[184:185], off
	v_lshl_add_u64 v[184:185], v[224:225], 0, s[14:15]
	s_mov_b32 m0, s45
	s_nop 0
	global_load_lds_dwordx4 v[184:185], off
	s_waitcnt vmcnt(8)
	s_waitcnt lgkmcnt(0)
	s_barrier
	s_setprio 1
	v_mfma_f32_16x16x32_bf16 v[60:63], v[128:131], v[176:179], v[60:63]
	v_mfma_f32_16x16x32_bf16 v[56:59], v[136:139], v[176:179], v[56:59]
	v_mfma_f32_16x16x32_bf16 v[44:47], v[128:131], v[196:199], v[44:47]
	v_mfma_f32_16x16x32_bf16 v[40:43], v[136:139], v[196:199], v[40:43]
	v_mfma_f32_16x16x32_bf16 v[28:31], v[128:131], v[204:207], v[28:31]
	v_mfma_f32_16x16x32_bf16 v[24:27], v[136:139], v[204:207], v[24:27]
	v_mfma_f32_16x16x32_bf16 v[12:15], v[128:131], v[212:215], v[12:15]
	v_mfma_f32_16x16x32_bf16 v[8:11], v[136:139], v[212:215], v[8:11]
	v_mfma_f32_16x16x32_bf16 v[60:63], v[132:135], v[180:183], v[60:63]
	v_mfma_f32_16x16x32_bf16 v[56:59], v[140:143], v[180:183], v[56:59]
	v_mfma_f32_16x16x32_bf16 v[44:47], v[132:135], v[200:203], v[44:47]
	v_mfma_f32_16x16x32_bf16 v[40:43], v[140:143], v[200:203], v[40:43]
	v_mfma_f32_16x16x32_bf16 v[28:31], v[132:135], v[208:211], v[28:31]
	v_mfma_f32_16x16x32_bf16 v[24:27], v[140:143], v[208:211], v[24:27]
	v_mfma_f32_16x16x32_bf16 v[12:15], v[132:135], v[216:219], v[12:15]
	v_mfma_f32_16x16x32_bf16 v[8:11], v[140:143], v[216:219], v[8:11]
	s_setprio 1
	v_mfma_f32_16x16x32_bf16 v[52:55], v[144:147], v[176:179], v[52:55]
	v_mfma_f32_16x16x32_bf16 v[48:51], v[168:171], v[176:179], v[48:51]
	v_mfma_f32_16x16x32_bf16 v[36:39], v[144:147], v[196:199], v[36:39]
	v_mfma_f32_16x16x32_bf16 v[32:35], v[168:171], v[196:199], v[32:35]
	v_mfma_f32_16x16x32_bf16 v[20:23], v[144:147], v[204:207], v[20:23]
	v_mfma_f32_16x16x32_bf16 v[16:19], v[168:171], v[204:207], v[16:19]
	v_mfma_f32_16x16x32_bf16 v[4:7], v[144:147], v[212:215], v[4:7]
	v_mfma_f32_16x16x32_bf16 v[0:3], v[168:171], v[212:215], v[0:3]
	v_mfma_f32_16x16x32_bf16 v[52:55], v[148:151], v[180:183], v[52:55]
	v_mfma_f32_16x16x32_bf16 v[48:51], v[172:175], v[180:183], v[48:51]
	v_mfma_f32_16x16x32_bf16 v[36:39], v[148:151], v[200:203], v[36:39]
	v_mfma_f32_16x16x32_bf16 v[32:35], v[172:175], v[200:203], v[32:35]
	v_mfma_f32_16x16x32_bf16 v[20:23], v[148:151], v[208:211], v[20:23]
	v_mfma_f32_16x16x32_bf16 v[16:19], v[172:175], v[208:211], v[16:19]
	v_mfma_f32_16x16x32_bf16 v[4:7], v[148:151], v[216:219], v[4:7]
	v_mfma_f32_16x16x32_bf16 v[0:3], v[172:175], v[216:219], v[0:3]
	s_barrier
	s_setprio 0
	s_add_i32 s74, s74, 2
	s_add_u32 s30, s30, 0x100
	s_addc_u32 s31, s31, 0
	s_add_u32 s69, s69, 0x100
	s_addc_u32 s73, s73, 0
	s_cmp_gt_u32 s74, 13
	s_cbranch_scc0 .LBB0_971
	s_and_b64 vcc, exec, s[16:17]
	s_cbranch_vccz .LBB0_974
	s_barrier

; #define PG8_STAGE(bufoff, gbase, voff) do { _Pragma("unroll") for (int _i = 0; _i < 2; ++_i) \
;         __builtin_amdgcn_global_load_lds((const unsigned*)((const char*)(gbase) + (voff)[_i]), (PG8_LAS unsigned*)(lds + (bufoff) + ldsw + _i * 8192), 16, 0, 0); } while (0)
; #define PG8_LDA(dst, b, h) do { _Pragma("unroll") for (int m = 0; m < 4; ++m) _Pragma("unroll") for (int k = 0; k < 2; ++k) dst[m][k] = *(const PG8_LAS bf16x8*)(lds + PG8_SA(b, h) + aoff + m * 2048 + k * 1024); } while (0)
; #define PG8_LDB(dst, b, h) do { _Pragma("unroll") for (int n = 0; n < 2; ++n) _Pragma("unroll") for (int k = 0; k < 2; ++k) dst[n][k] = *(const PG8_LAS bf16x8*)(lds + PG8_SB(b, h) + boff + n * 2048 + k * 1024); } while (0)
; #define PG8_MMA(ai, bj, At, Bt) do { __builtin_amdgcn_s_setprio(1); _Pragma("unroll") for (int m = 0; m < 4; ++m) _Pragma("unroll") for (int n = 0; n < 2; ++n) _Pragma("unroll") for (int k = 0; k < 2; ++k) \
;         acc[ai][bj][m][n] = __builtin_amdgcn_mfma_f32_16x16x32_bf16(Bt[n][k], At[m][k], acc[ai][bj][m][n], 0, 0, 0); __builtin_amdgcn_s_setprio(0); } while (0)
; #define PG8_WAIT_V(n) asm volatile("s_waitcnt vmcnt(" #n ")" ::: "memory")
; #define PG8_WAIT_L(n) asm volatile("s_waitcnt lgkmcnt(" #n ")" ::: "memory")
; #define PG8_BAR __builtin_amdgcn_s_barrier()
; template <class Epi, class Sched, bool ALIGN_EPI = false, bool SP2 = false>
; __device__ __forceinline__ void gemm_phase(PG8_LAS unsigned char* lds, const Gemm g, const Sched& S, const Epi& E) {
;     ...
;             const char* a1 = cA + (size_t)(t + 1) * kstep;
;             const char* a2 = last ? nA : cA + (size_t)(t + 2) * kstep; const char* b2 = last ? nB : cB + (size_t)(t + 2) * kstep;
;             const char* a3 = a2 + kstep; const char* b3 = b2 + kstep;
;             if (last && has_next) S.a_ready(nxt);
;             if constexpr (SP2) {
;             PG8_LDB(B0, 0, 0); PG8_LDB(B1, 0, 1); PG8_SCHED; PG8_LDA(At, 0, 0); PG8_STAGE(PG8_SA(1, 1), a1 + hstepA, voffA);
;             PG8_WAIT_V(8); PG8_WAIT_L(0); PG8_BAR; PG8_MMA(0, 0, At, B0); PG8_MMA(0, 1, At, B1); PG8_BAR; PG8_SCHED;
;             PG8_LDA(At, 0, 1); PG8_STAGE(PG8_SB(0, 0), b2, voffB); PG8_STAGE(PG8_SB(0, 1), b2 + hstepB, voffB); PG8_STAGE(PG8_SA(0, 0), a2, voffA);
;             PG8_WAIT_V(8); PG8_WAIT_L(0); PG8_BAR; PG8_MMA(1, 0, At, B0); PG8_MMA(1, 1, At, B1); PG8_BAR; PG8_SCHED;
.LBB0_1055:
	ds_read_b128 v[144:147], v153
	ds_read_b128 v[158:161], v153 offset:1024
	ds_read_b128 v[162:165], v153 offset:2048
	ds_read_b128 v[166:169], v153 offset:3072
	ds_read_b128 v[170:173], v154
	ds_read_b128 v[174:177], v154 offset:1024
	ds_read_b128 v[178:181], v154 offset:2048
	ds_read_b128 v[182:185], v154 offset:3072
	s_add_u32 s28, s26, 0xfffc0080
	s_addc_u32 s29, s27, -1
	s_cmp_eq_u32 s69, 12
	s_cselect_b32 s31, s19, s29
	s_cselect_b32 s30, s49, s28
	s_cselect_b32 s29, s17, s68
	s_cselect_b32 s28, s66, s67
	v_lshl_add_u64 v[148:149], s[26:27], 0, v[136:137]
	s_add_i32 m0, s25, 0xc000
	ds_read_b128 v[188:191], v155
	ds_read_b128 v[192:195], v155 offset:1024
	ds_read_b128 v[196:199], v155 offset:2048
	ds_read_b128 v[200:203], v155 offset:3072
	ds_read_b128 v[204:207], v155 offset:4096
	ds_read_b128 v[208:211], v155 offset:5120
	ds_read_b128 v[212:215], v155 offset:6144
	ds_read_b128 v[216:219], v155 offset:7168
	global_load_lds_dwordx4 v[148:149], off
	v_lshl_add_u64 v[148:149], s[26:27], 0, v[138:139]
	s_add_i32 m0, s25, 0xe000
	s_nop 0
	global_load_lds_dwordx4 v[148:149], off
	s_waitcnt vmcnt(8)
	s_waitcnt lgkmcnt(0)
	s_barrier
	s_setprio 1
	v_mfma_f32_16x16x32_bf16 v[116:119], v[144:147], v[188:191], v[116:119]
	v_mfma_f32_16x16x32_bf16 v[112:115], v[162:165], v[188:191], v[112:115]
	v_mfma_f32_16x16x32_bf16 v[108:111], v[144:147], v[196:199], v[108:111]
	v_mfma_f32_16x16x32_bf16 v[100:103], v[162:165], v[196:199], v[100:103]
	v_mfma_f32_16x16x32_bf16 v[92:95], v[144:147], v[204:207], v[92:95]
	v_mfma_f32_16x16x32_bf16 v[84:87], v[162:165], v[204:207], v[84:87]
	v_mfma_f32_16x16x32_bf16 v[76:79], v[144:147], v[212:215], v[76:79]
	v_mfma_f32_16x16x32_bf16 v[68:71], v[162:165], v[212:215], v[68:71]
	v_mfma_f32_16x16x32_bf16 v[116:119], v[158:161], v[192:195], v[116:119]
	v_mfma_f32_16x16x32_bf16 v[112:115], v[166:169], v[192:195], v[112:115]
	v_mfma_f32_16x16x32_bf16 v[108:111], v[158:161], v[200:203], v[108:111]
	v_mfma_f32_16x16x32_bf16 v[100:103], v[166:169], v[200:203], v[100:103]
	v_mfma_f32_16x16x32_bf16 v[92:95], v[158:161], v[208:211], v[92:95]
	v_mfma_f32_16x16x32_bf16 v[84:87], v[166:169], v[208:211], v[84:87]
	v_mfma_f32_16x16x32_bf16 v[76:79], v[158:161], v[216:219], v[76:79]
	v_mfma_f32_16x16x32_bf16 v[68:71], v[166:169], v[216:219], v[68:71]
	s_setprio 1
	v_mfma_f32_16x16x32_bf16 v[124:127], v[170:173], v[188:191], v[124:127]
	v_mfma_f32_16x16x32_bf16 v[120:123], v[178:181], v[188:191], v[120:123]
	v_mfma_f32_16x16x32_bf16 v[104:107], v[170:173], v[196:199], v[104:107]
	v_mfma_f32_16x16x32_bf16 v[96:99], v[178:181], v[196:199], v[96:99]
	v_mfma_f32_16x16x32_bf16 v[88:91], v[170:173], v[204:207], v[88:91]
	v_mfma_f32_16x16x32_bf16 v[80:83], v[178:181], v[204:207], v[80:83]
	v_mfma_f32_16x16x32_bf16 v[72:75], v[170:173], v[212:215], v[72:75]
	v_mfma_f32_16x16x32_bf16 v[64:67], v[178:181], v[212:215], v[64:67]
	v_mfma_f32_16x16x32_bf16 v[124:127], v[174:177], v[192:195], v[124:127]
	v_mfma_f32_16x16x32_bf16 v[120:123], v[182:185], v[192:195], v[120:123]
	v_mfma_f32_16x16x32_bf16 v[104:107], v[174:177], v[200:203], v[104:107]
	v_mfma_f32_16x16x32_bf16 v[96:99], v[182:185], v[200:203], v[96:99]
	v_mfma_f32_16x16x32_bf16 v[88:91], v[174:177], v[208:211], v[88:91]
	v_mfma_f32_16x16x32_bf16 v[80:83], v[182:185], v[208:211], v[80:83]
	v_mfma_f32_16x16x32_bf16 v[72:75], v[174:177], v[216:219], v[72:75]
	v_mfma_f32_16x16x32_bf16 v[64:67], v[182:185], v[216:219], v[64:67]
	s_barrier
	s_setprio 0
	s_add_i32 s58, s45, s35
	v_lshl_add_u64 v[148:149], s[28:29], 0, v[132:133]
	s_mov_b32 m0, s58
	ds_read_b128 v[188:191], v155 offset:16384
	ds_read_b128 v[192:195], v155 offset:17408
	ds_read_b128 v[196:199], v155 offset:18432
	ds_read_b128 v[200:203], v155 offset:19456
	ds_read_b128 v[204:207], v155 offset:20480
	ds_read_b128 v[208:211], v155 offset:21504
	ds_read_b128 v[212:215], v155 offset:22528
	ds_read_b128 v[216:219], v155 offset:23552
	global_load_lds_dwordx4 v[148:149], off
	s_add_i32 m0, s58, 0x2000
	s_add_u32 s58, s28, 0x40000
	v_lshl_add_u64 v[220:221], s[28:29], 0, v[128:129]
	s_addc_u32 s59, s29, 0
	s_add_i32 s73, s46, s35
	global_load_lds_dwordx4 v[220:221], off
	v_lshl_add_u64 v[222:223], s[58:59], 0, v[132:133]
	s_mov_b32 m0, s73
	v_lshl_add_u64 v[224:225], s[30:31], 0, v[130:131]
	global_load_lds_dwordx4 v[222:223], off
	v_lshl_add_u64 v[222:223], s[58:59], 0, v[128:129]
	s_add_i32 m0, s73, 0x2000
	s_nop 0
	global_load_lds_dwordx4 v[222:223], off
	v_lshl_add_u64 v[222:223], s[30:31], 0, v[134:135]
	s_mov_b32 m0, s25
	s_nop 0
	global_load_lds_dwordx4 v[222:223], off
	s_mov_b32 m0, s38
	s_nop 0
	global_load_lds_dwordx4 v[224:225], off
	s_waitcnt vmcnt(8)
	s_waitcnt lgkmcnt(0)
	s_barrier
; #define PG8_STAGE(bufoff, gbase, voff) do { _Pragma("unroll") for (int _i = 0; _i < 2; ++_i) \
;         __builtin_amdgcn_global_load_lds((const unsigned*)((const char*)(gbase) + (voff)[_i]), (PG8_LAS unsigned*)(lds + (bufoff) + ldsw + _i * 8192), 16, 0, 0); } while (0)
; #define PG8_LDA(dst, b, h) do { _Pragma("unroll") for (int m = 0; m < 4; ++m) _Pragma("unroll") for (int k = 0; k < 2; ++k) dst[m][k] = *(const PG8_LAS bf16x8*)(lds + PG8_SA(b, h) + aoff + m * 2048 + k * 1024); } while (0)
; #define PG8_LDB(dst, b, h) do { _Pragma("unroll") for (int n = 0; n < 2; ++n) _Pragma("unroll") for (int k = 0; k < 2; ++k) dst[n][k] = *(const PG8_LAS bf16x8*)(lds + PG8_SB(b, h) + boff + n * 2048 + k * 1024); } while (0)
; #define PG8_MMA(ai, bj, At, Bt) do { __builtin_amdgcn_s_setprio(1); _Pragma("unroll") for (int m = 0; m < 4; ++m) _Pragma("unroll") for (int n = 0; n < 2; ++n) _Pragma("unroll") for (int k = 0; k < 2; ++k) \
;         acc[ai][bj][m][n] = __builtin_amdgcn_mfma_f32_16x16x32_bf16(Bt[n][k], At[m][k], acc[ai][bj][m][n], 0, 0, 0); __builtin_amdgcn_s_setprio(0); } while (0)
; #define PG8_WAIT_V(n) asm volatile("s_waitcnt vmcnt(" #n ")" ::: "memory")
; #define PG8_WAIT_L(n) asm volatile("s_waitcnt lgkmcnt(" #n ")" ::: "memory")
; #define PG8_BAR __builtin_amdgcn_s_barrier()
; #define PG8_SCHED __builtin_amdgcn_sched_barrier(0)
; template <class Epi, class Sched, bool ALIGN_EPI = false, bool SP2 = false>
; __device__ __forceinline__ void gemm_phase(PG8_LAS unsigned char* lds, const Gemm g, const Sched& S, const Epi& E) {
;     ...
;             PG8_WAIT_V(8); PG8_WAIT_L(0); PG8_BAR; PG8_MMA(1, 0, At, B0); PG8_MMA(1, 1, At, B1); PG8_BAR; PG8_SCHED;
;             PG8_LDB(B0, 1, 0); PG8_LDB(B1, 1, 1); PG8_SCHED; PG8_LDA(At, 1, 0); PG8_STAGE(PG8_SA(0, 1), a2 + hstepA, voffA);
;             PG8_WAIT_V(8); PG8_WAIT_L(0); PG8_BAR; PG8_MMA(0, 0, At, B0); PG8_MMA(0, 1, At, B1); PG8_BAR; PG8_SCHED;
	s_setprio 1
	v_mfma_f32_16x16x32_bf16 v[60:63], v[144:147], v[188:191], v[60:63]
	v_mfma_f32_16x16x32_bf16 v[52:55], v[162:165], v[188:191], v[52:55]
	v_mfma_f32_16x16x32_bf16 v[44:47], v[144:147], v[196:199], v[44:47]
	v_mfma_f32_16x16x32_bf16 v[36:39], v[162:165], v[196:199], v[36:39]
	v_mfma_f32_16x16x32_bf16 v[28:31], v[144:147], v[204:207], v[28:31]
	v_mfma_f32_16x16x32_bf16 v[20:23], v[162:165], v[204:207], v[20:23]
	v_mfma_f32_16x16x32_bf16 v[12:15], v[144:147], v[212:215], v[12:15]
	v_mfma_f32_16x16x32_bf16 v[4:7], v[162:165], v[212:215], v[4:7]
	v_mfma_f32_16x16x32_bf16 v[60:63], v[158:161], v[192:195], v[60:63]
	v_mfma_f32_16x16x32_bf16 v[52:55], v[166:169], v[192:195], v[52:55]
	v_mfma_f32_16x16x32_bf16 v[44:47], v[158:161], v[200:203], v[44:47]
	v_mfma_f32_16x16x32_bf16 v[36:39], v[166:169], v[200:203], v[36:39]
	v_mfma_f32_16x16x32_bf16 v[28:31], v[158:161], v[208:211], v[28:31]
	v_mfma_f32_16x16x32_bf16 v[20:23], v[166:169], v[208:211], v[20:23]
	v_mfma_f32_16x16x32_bf16 v[12:15], v[158:161], v[216:219], v[12:15]
	v_mfma_f32_16x16x32_bf16 v[4:7], v[166:169], v[216:219], v[4:7]
	s_setprio 1
	v_mfma_f32_16x16x32_bf16 v[56:59], v[170:173], v[188:191], v[56:59]
	v_mfma_f32_16x16x32_bf16 v[48:51], v[178:181], v[188:191], v[48:51]
	v_mfma_f32_16x16x32_bf16 v[40:43], v[170:173], v[196:199], v[40:43]
	v_mfma_f32_16x16x32_bf16 v[32:35], v[178:181], v[196:199], v[32:35]
	v_mfma_f32_16x16x32_bf16 v[24:27], v[170:173], v[204:207], v[24:27]
	v_mfma_f32_16x16x32_bf16 v[16:19], v[178:181], v[204:207], v[16:19]
	v_mfma_f32_16x16x32_bf16 v[8:11], v[170:173], v[212:215], v[8:11]
	v_mfma_f32_16x16x32_bf16 v[0:3], v[178:181], v[212:215], v[0:3]
	v_mfma_f32_16x16x32_bf16 v[56:59], v[174:177], v[192:195], v[56:59]
	v_mfma_f32_16x16x32_bf16 v[48:51], v[182:185], v[192:195], v[48:51]
	v_mfma_f32_16x16x32_bf16 v[40:43], v[174:177], v[200:203], v[40:43]
	v_mfma_f32_16x16x32_bf16 v[32:35], v[182:185], v[200:203], v[32:35]
	v_mfma_f32_16x16x32_bf16 v[24:27], v[174:177], v[208:211], v[24:27]
	v_mfma_f32_16x16x32_bf16 v[16:19], v[182:185], v[208:211], v[16:19]
	v_mfma_f32_16x16x32_bf16 v[8:11], v[174:177], v[216:219], v[8:11]
	v_mfma_f32_16x16x32_bf16 v[0:3], v[182:185], v[216:219], v[0:3]
	s_barrier
	s_setprio 0
	s_add_i32 s58, 0, 0x18000
	v_add_u32_e32 v157, s58, v151
	s_add_i32 s59, 0, 0x1c000
	ds_read_b128 v[144:147], v157
	ds_read_b128 v[158:161], v157 offset:1024
	ds_read_b128 v[162:165], v157 offset:2048
	ds_read_b128 v[166:169], v157 offset:3072
	v_add_u32_e32 v157, s59, v151
	ds_read_b128 v[170:173], v157
	ds_read_b128 v[174:177], v157 offset:1024
	ds_read_b128 v[178:181], v157 offset:2048
	ds_read_b128 v[182:185], v157 offset:3072
	s_add_u32 s30, s30, 0x40000
	s_addc_u32 s31, s31, 0
	s_mov_b32 m0, s39
	v_lshl_add_u64 v[226:227], s[30:31], 0, v[134:135]
	ds_read_b128 v[188:191], v155 offset:32768
	ds_read_b128 v[192:195], v155 offset:33792
	ds_read_b128 v[196:199], v155 offset:34816
	ds_read_b128 v[200:203], v155 offset:35840
	ds_read_b128 v[204:207], v155 offset:36864
	ds_read_b128 v[208:211], v155 offset:37888
	ds_read_b128 v[212:215], v155 offset:38912
	ds_read_b128 v[216:219], v155 offset:39936
	global_load_lds_dwordx4 v[226:227], off
	v_lshl_add_u64 v[226:227], s[30:31], 0, v[130:131]
	s_mov_b32 m0, s40
	s_nop 0
	global_load_lds_dwordx4 v[226:227], off
	s_waitcnt vmcnt(8)
	s_waitcnt lgkmcnt(0)
	s_barrier
	s_setprio 1
	v_mfma_f32_16x16x32_bf16 v[116:119], v[144:147], v[188:191], v[116:119]
	v_mfma_f32_16x16x32_bf16 v[112:115], v[162:165], v[188:191], v[112:115]
	v_mfma_f32_16x16x32_bf16 v[108:111], v[144:147], v[196:199], v[108:111]
	v_mfma_f32_16x16x32_bf16 v[100:103], v[162:165], v[196:199], v[100:103]
	v_mfma_f32_16x16x32_bf16 v[92:95], v[144:147], v[204:207], v[92:95]
	v_mfma_f32_16x16x32_bf16 v[84:87], v[162:165], v[204:207], v[84:87]
	v_mfma_f32_16x16x32_bf16 v[76:79], v[144:147], v[212:215], v[76:79]
	v_mfma_f32_16x16x32_bf16 v[68:71], v[162:165], v[212:215], v[68:71]
	v_mfma_f32_16x16x32_bf16 v[116:119], v[158:161], v[192:195], v[116:119]
	v_mfma_f32_16x16x32_bf16 v[112:115], v[166:169], v[192:195], v[112:115]
	v_mfma_f32_16x16x32_bf16 v[108:111], v[158:161], v[200:203], v[108:111]
	v_mfma_f32_16x16x32_bf16 v[100:103], v[166:169], v[200:203], v[100:103]
	v_mfma_f32_16x16x32_bf16 v[92:95], v[158:161], v[208:211], v[92:95]
	v_mfma_f32_16x16x32_bf16 v[84:87], v[166:169], v[208:211], v[84:87]
	v_mfma_f32_16x16x32_bf16 v[76:79], v[158:161], v[216:219], v[76:79]
	v_mfma_f32_16x16x32_bf16 v[68:71], v[166:169], v[216:219], v[68:71]
	s_setprio 1
	v_mfma_f32_16x16x32_bf16 v[124:127], v[170:173], v[188:191], v[124:127]
	v_mfma_f32_16x16x32_bf16 v[120:123], v[178:181], v[188:191], v[120:123]
	v_mfma_f32_16x16x32_bf16 v[104:107], v[170:173], v[196:199], v[104:107]
	v_mfma_f32_16x16x32_bf16 v[96:99], v[178:181], v[196:199], v[96:99]
	v_mfma_f32_16x16x32_bf16 v[88:91], v[170:173], v[204:207], v[88:91]
	v_mfma_f32_16x16x32_bf16 v[80:83], v[178:181], v[204:207], v[80:83]
	v_mfma_f32_16x16x32_bf16 v[72:75], v[170:173], v[212:215], v[72:75]
	v_mfma_f32_16x16x32_bf16 v[64:67], v[178:181], v[212:215], v[64:67]
	v_mfma_f32_16x16x32_bf16 v[124:127], v[174:177], v[192:195], v[124:127]
	v_mfma_f32_16x16x32_bf16 v[120:123], v[182:185], v[192:195], v[120:123]
	v_mfma_f32_16x16x32_bf16 v[104:107], v[174:177], v[200:203], v[104:107]
	v_mfma_f32_16x16x32_bf16 v[96:99], v[182:185], v[200:203], v[96:99]
	v_mfma_f32_16x16x32_bf16 v[88:91], v[174:177], v[208:211], v[88:91]
	v_mfma_f32_16x16x32_bf16 v[80:83], v[182:185], v[208:211], v[80:83]
	v_mfma_f32_16x16x32_bf16 v[72:75], v[174:177], v[216:219], v[72:75]
	v_mfma_f32_16x16x32_bf16 v[64:67], v[182:185], v[216:219], v[64:67]
	s_barrier
; #define PG8_STAGE(bufoff, gbase, voff) do { _Pragma("unroll") for (int _i = 0; _i < 2; ++_i) \
;         __builtin_amdgcn_global_load_lds((const unsigned*)((const char*)(gbase) + (voff)[_i]), (PG8_LAS unsigned*)(lds + (bufoff) + ldsw + _i * 8192), 16, 0, 0); } while (0)
; #define PG8_LDA(dst, b, h) do { _Pragma("unroll") for (int m = 0; m < 4; ++m) _Pragma("unroll") for (int k = 0; k < 2; ++k) dst[m][k] = *(const PG8_LAS bf16x8*)(lds + PG8_SA(b, h) + aoff + m * 2048 + k * 1024); } while (0)
; #define PG8_MMA(ai, bj, At, Bt) do { __builtin_amdgcn_s_setprio(1); _Pragma("unroll") for (int m = 0; m < 4; ++m) _Pragma("unroll") for (int n = 0; n < 2; ++n) _Pragma("unroll") for (int k = 0; k < 2; ++k) \
;         acc[ai][bj][m][n] = __builtin_amdgcn_mfma_f32_16x16x32_bf16(Bt[n][k], At[m][k], acc[ai][bj][m][n], 0, 0, 0); __builtin_amdgcn_s_setprio(0); } while (0)
; #define PG8_WAIT_V(n) asm volatile("s_waitcnt vmcnt(" #n ")" ::: "memory")
; #define PG8_WAIT_L(n) asm volatile("s_waitcnt lgkmcnt(" #n ")" ::: "memory")
; #define PG8_BAR __builtin_amdgcn_s_barrier()
; #define PG8_SCHED __builtin_amdgcn_sched_barrier(0)
; template <class Epi, class Sched, bool ALIGN_EPI = false, bool SP2 = false>
; __device__ __forceinline__ void gemm_phase(PG8_LAS unsigned char* lds, const Gemm g, const Sched& S, const Epi& E) {
;     ...
;         for (int t = 0; t < nt; t += 2) {
;             const bool last = (t == nt - 2);
;     ...
;             PG8_LDA(At, 1, 1); PG8_STAGE(PG8_SB(1, 0), b3, voffB); PG8_STAGE(PG8_SB(1, 1), b3 + hstepB, voffB); PG8_STAGE(PG8_SA(1, 0), a3, voffA);
;             PG8_WAIT_V(8); PG8_WAIT_L(0); PG8_BAR; PG8_MMA(1, 0, At, B0); PG8_MMA(1, 1, At, B1); PG8_BAR; PG8_SCHED;
	s_setprio 0
	s_add_i32 s30, s58, s35
	v_lshl_add_u64 v[148:149], v[148:149], 0, s[12:13]
	s_mov_b32 m0, s30
	ds_read_b128 v[188:191], v155 offset:49152
	ds_read_b128 v[192:195], v155 offset:50176
	ds_read_b128 v[196:199], v155 offset:51200
	ds_read_b128 v[200:203], v155 offset:52224
	ds_read_b128 v[204:207], v155 offset:53248
	ds_read_b128 v[208:211], v155 offset:54272
	ds_read_b128 v[212:215], v155 offset:55296
	ds_read_b128 v[216:219], v155 offset:56320
	global_load_lds_dwordx4 v[148:149], off
	s_add_i32 m0, s30, 0x2000
	s_add_u32 s28, s28, 0x40080
	v_lshl_add_u64 v[148:149], v[220:221], 0, s[12:13]
	s_addc_u32 s29, s29, 0
	s_add_i32 s30, s59, s35
	global_load_lds_dwordx4 v[148:149], off
	v_lshl_add_u64 v[148:149], s[28:29], 0, v[132:133]
	s_mov_b32 m0, s30
	s_nop 0
	global_load_lds_dwordx4 v[148:149], off
	v_lshl_add_u64 v[148:149], s[28:29], 0, v[128:129]
	s_add_i32 m0, s30, 0x2000
	s_nop 0
	global_load_lds_dwordx4 v[148:149], off
	v_lshl_add_u64 v[148:149], v[222:223], 0, s[12:13]
	s_mov_b32 m0, s42
	s_nop 0
	global_load_lds_dwordx4 v[148:149], off
	v_lshl_add_u64 v[148:149], v[224:225], 0, s[12:13]
	s_mov_b32 m0, s43
	s_nop 0
	global_load_lds_dwordx4 v[148:149], off
	s_waitcnt vmcnt(8)
	s_waitcnt lgkmcnt(0)
	s_barrier
	s_setprio 1
	v_mfma_f32_16x16x32_bf16 v[60:63], v[144:147], v[188:191], v[60:63]
	v_mfma_f32_16x16x32_bf16 v[52:55], v[162:165], v[188:191], v[52:55]
	v_mfma_f32_16x16x32_bf16 v[44:47], v[144:147], v[196:199], v[44:47]
	v_mfma_f32_16x16x32_bf16 v[36:39], v[162:165], v[196:199], v[36:39]
	v_mfma_f32_16x16x32_bf16 v[28:31], v[144:147], v[204:207], v[28:31]
	v_mfma_f32_16x16x32_bf16 v[20:23], v[162:165], v[204:207], v[20:23]
	v_mfma_f32_16x16x32_bf16 v[12:15], v[144:147], v[212:215], v[12:15]
	v_mfma_f32_16x16x32_bf16 v[4:7], v[162:165], v[212:215], v[4:7]
	v_mfma_f32_16x16x32_bf16 v[60:63], v[158:161], v[192:195], v[60:63]
	v_mfma_f32_16x16x32_bf16 v[52:55], v[166:169], v[192:195], v[52:55]
	v_mfma_f32_16x16x32_bf16 v[44:47], v[158:161], v[200:203], v[44:47]
	v_mfma_f32_16x16x32_bf16 v[36:39], v[166:169], v[200:203], v[36:39]
	v_mfma_f32_16x16x32_bf16 v[28:31], v[158:161], v[208:211], v[28:31]
	v_mfma_f32_16x16x32_bf16 v[20:23], v[166:169], v[208:211], v[20:23]
	v_mfma_f32_16x16x32_bf16 v[12:15], v[158:161], v[216:219], v[12:15]
	v_mfma_f32_16x16x32_bf16 v[4:7], v[166:169], v[216:219], v[4:7]
	s_setprio 1
	v_mfma_f32_16x16x32_bf16 v[56:59], v[170:173], v[188:191], v[56:59]
	v_mfma_f32_16x16x32_bf16 v[48:51], v[178:181], v[188:191], v[48:51]
	v_mfma_f32_16x16x32_bf16 v[40:43], v[170:173], v[196:199], v[40:43]
	v_mfma_f32_16x16x32_bf16 v[32:35], v[178:181], v[196:199], v[32:35]
	v_mfma_f32_16x16x32_bf16 v[24:27], v[170:173], v[204:207], v[24:27]
	v_mfma_f32_16x16x32_bf16 v[16:19], v[178:181], v[204:207], v[16:19]
	v_mfma_f32_16x16x32_bf16 v[8:11], v[170:173], v[212:215], v[8:11]
	v_mfma_f32_16x16x32_bf16 v[0:3], v[178:181], v[212:215], v[0:3]
	v_mfma_f32_16x16x32_bf16 v[56:59], v[174:177], v[192:195], v[56:59]
	v_mfma_f32_16x16x32_bf16 v[48:51], v[182:185], v[192:195], v[48:51]
	v_mfma_f32_16x16x32_bf16 v[40:43], v[174:177], v[200:203], v[40:43]
	v_mfma_f32_16x16x32_bf16 v[32:35], v[182:185], v[200:203], v[32:35]
	v_mfma_f32_16x16x32_bf16 v[24:27], v[174:177], v[208:211], v[24:27]
	v_mfma_f32_16x16x32_bf16 v[16:19], v[182:185], v[208:211], v[16:19]
	v_mfma_f32_16x16x32_bf16 v[8:11], v[174:177], v[216:219], v[8:11]
	v_mfma_f32_16x16x32_bf16 v[0:3], v[182:185], v[216:219], v[0:3]
	s_barrier
	s_setprio 0
	s_add_i32 s69, s69, 2
	s_add_u32 s26, s26, 0x100
	s_addc_u32 s27, s27, 0
	s_add_u32 s67, s67, 0x100
	s_addc_u32 s68, s68, 0
	s_cmp_gt_u32 s69, 13
	s_cbranch_scc0 .LBB0_1055
	s_and_b64 vcc, exec, s[14:15]
	s_cbranch_vccz .LBB0_1058
	s_barrier

; #define PG8_STAGE(bufoff, gbase, voff) do { _Pragma("unroll") for (int _i = 0; _i < 2; ++_i) \
;         __builtin_amdgcn_global_load_lds((const unsigned*)((const char*)(gbase) + (voff)[_i]), (PG8_LAS unsigned*)(lds + (bufoff) + ldsw + _i * 8192), 16, 0, 0); } while (0)
; #define PG8_LDA(dst, b, h) do { _Pragma("unroll") for (int m = 0; m < 4; ++m) _Pragma("unroll") for (int k = 0; k < 2; ++k) dst[m][k] = *(const PG8_LAS bf16x8*)(lds + PG8_SA(b, h) + aoff + m * 2048 + k * 1024); } while (0)
; #define PG8_LDB(dst, b, h) do { _Pragma("unroll") for (int n = 0; n < 2; ++n) _Pragma("unroll") for (int k = 0; k < 2; ++k) dst[n][k] = *(const PG8_LAS bf16x8*)(lds + PG8_SB(b, h) + boff + n * 2048 + k * 1024); } while (0)
; #define PG8_MMA(ai, bj, At, Bt) do { __builtin_amdgcn_s_setprio(1); _Pragma("unroll") for (int m = 0; m < 4; ++m) _Pragma("unroll") for (int n = 0; n < 2; ++n) _Pragma("unroll") for (int k = 0; k < 2; ++k) \
;         acc[ai][bj][m][n] = __builtin_amdgcn_mfma_f32_16x16x32_bf16(Bt[n][k], At[m][k], acc[ai][bj][m][n], 0, 0, 0); __builtin_amdgcn_s_setprio(0); } while (0)
; #define PG8_WAIT_V(n) asm volatile("s_waitcnt vmcnt(" #n ")" ::: "memory")
; #define PG8_WAIT_L(n) asm volatile("s_waitcnt lgkmcnt(" #n ")" ::: "memory")
; #define PG8_BAR __builtin_amdgcn_s_barrier()
; template <class Epi, class Sched, bool ALIGN_EPI = false, bool SP2 = false>
; __device__ __forceinline__ void gemm_phase(PG8_LAS unsigned char* lds, const Gemm g, const Sched& S, const Epi& E) {
;     ...
;             const char* a1 = cA + (size_t)(t + 1) * kstep;
;             const char* a2 = last ? nA : cA + (size_t)(t + 2) * kstep; const char* b2 = last ? nB : cB + (size_t)(t + 2) * kstep;
;             const char* a3 = a2 + kstep; const char* b3 = b2 + kstep;
;             if (last && has_next) S.a_ready(nxt);
;             if constexpr (SP2) {
;             PG8_LDB(B0, 0, 0); PG8_LDB(B1, 0, 1); PG8_SCHED; PG8_LDA(At, 0, 0); PG8_STAGE(PG8_SA(1, 1), a1 + hstepA, voffA);
;             PG8_WAIT_V(8); PG8_WAIT_L(0); PG8_BAR; PG8_MMA(0, 0, At, B0); PG8_MMA(0, 1, At, B1); PG8_BAR; PG8_SCHED;
;             PG8_LDA(At, 0, 1); PG8_STAGE(PG8_SB(0, 0), b2, voffB); PG8_STAGE(PG8_SB(0, 1), b2 + hstepB, voffB); PG8_STAGE(PG8_SA(0, 0), a2, voffA);
;             PG8_WAIT_V(8); PG8_WAIT_L(0); PG8_BAR; PG8_MMA(1, 0, At, B0); PG8_MMA(1, 1, At, B1); PG8_BAR; PG8_SCHED;
.LBB0_1129:
	ds_read_b128 v[128:131], v191
	ds_read_b128 v[132:135], v191 offset:1024
	ds_read_b128 v[136:139], v191 offset:2048
	ds_read_b128 v[140:143], v191 offset:3072
	ds_read_b128 v[144:147], v192
	ds_read_b128 v[148:151], v192 offset:1024
	ds_read_b128 v[168:171], v192 offset:2048
	ds_read_b128 v[172:175], v192 offset:3072
	s_add_u32 s24, s22, 0x100
	s_addc_u32 s25, s23, 0
	s_cmp_eq_u32 s69, 40
	s_cselect_b32 s29, s11, s25
	s_cselect_b32 s28, s10, s24
	s_cselect_b32 s27, s21, s68
	s_cselect_b32 s26, s20, s67
	v_lshl_add_u64 v[184:185], s[22:23], 0, v[160:161]
	s_add_i32 m0, s34, 0xc000
	ds_read_b128 v[176:179], v193
	ds_read_b128 v[180:183], v193 offset:1024
	ds_read_b128 v[196:199], v193 offset:2048
	ds_read_b128 v[200:203], v193 offset:3072
	ds_read_b128 v[204:207], v193 offset:4096
	ds_read_b128 v[208:211], v193 offset:5120
	ds_read_b128 v[212:215], v193 offset:6144
	ds_read_b128 v[216:219], v193 offset:7168
	global_load_lds_dwordx4 v[184:185], off
	v_lshl_add_u64 v[184:185], s[22:23], 0, v[162:163]
	s_add_i32 m0, s34, 0xe000
	s_nop 0
	global_load_lds_dwordx4 v[184:185], off
	s_waitcnt vmcnt(8)
	s_waitcnt lgkmcnt(0)
	s_barrier
	s_setprio 1
	v_mfma_f32_16x16x32_bf16 v[124:127], v[128:131], v[176:179], v[124:127]
	v_mfma_f32_16x16x32_bf16 v[120:123], v[136:139], v[176:179], v[120:123]
	v_mfma_f32_16x16x32_bf16 v[108:111], v[128:131], v[196:199], v[108:111]
	v_mfma_f32_16x16x32_bf16 v[104:107], v[136:139], v[196:199], v[104:107]
	v_mfma_f32_16x16x32_bf16 v[92:95], v[128:131], v[204:207], v[92:95]
	v_mfma_f32_16x16x32_bf16 v[88:91], v[136:139], v[204:207], v[88:91]
	v_mfma_f32_16x16x32_bf16 v[76:79], v[128:131], v[212:215], v[76:79]
	v_mfma_f32_16x16x32_bf16 v[72:75], v[136:139], v[212:215], v[72:75]
	v_mfma_f32_16x16x32_bf16 v[124:127], v[132:135], v[180:183], v[124:127]
	v_mfma_f32_16x16x32_bf16 v[120:123], v[140:143], v[180:183], v[120:123]
	v_mfma_f32_16x16x32_bf16 v[108:111], v[132:135], v[200:203], v[108:111]
	v_mfma_f32_16x16x32_bf16 v[104:107], v[140:143], v[200:203], v[104:107]
	v_mfma_f32_16x16x32_bf16 v[92:95], v[132:135], v[208:211], v[92:95]
	v_mfma_f32_16x16x32_bf16 v[88:91], v[140:143], v[208:211], v[88:91]
	v_mfma_f32_16x16x32_bf16 v[76:79], v[132:135], v[216:219], v[76:79]
	v_mfma_f32_16x16x32_bf16 v[72:75], v[140:143], v[216:219], v[72:75]
	s_setprio 1
	v_mfma_f32_16x16x32_bf16 v[116:119], v[144:147], v[176:179], v[116:119]
	v_mfma_f32_16x16x32_bf16 v[112:115], v[168:171], v[176:179], v[112:115]
	v_mfma_f32_16x16x32_bf16 v[100:103], v[144:147], v[196:199], v[100:103]
	v_mfma_f32_16x16x32_bf16 v[96:99], v[168:171], v[196:199], v[96:99]
	v_mfma_f32_16x16x32_bf16 v[84:87], v[144:147], v[204:207], v[84:87]
	v_mfma_f32_16x16x32_bf16 v[80:83], v[168:171], v[204:207], v[80:83]
	v_mfma_f32_16x16x32_bf16 v[68:71], v[144:147], v[212:215], v[68:71]
	v_mfma_f32_16x16x32_bf16 v[64:67], v[168:171], v[212:215], v[64:67]
	v_mfma_f32_16x16x32_bf16 v[116:119], v[148:151], v[180:183], v[116:119]
	v_mfma_f32_16x16x32_bf16 v[112:115], v[172:175], v[180:183], v[112:115]
	v_mfma_f32_16x16x32_bf16 v[100:103], v[148:151], v[200:203], v[100:103]
	v_mfma_f32_16x16x32_bf16 v[96:99], v[172:175], v[200:203], v[96:99]
	v_mfma_f32_16x16x32_bf16 v[84:87], v[148:151], v[208:211], v[84:87]
	v_mfma_f32_16x16x32_bf16 v[80:83], v[172:175], v[208:211], v[80:83]
	v_mfma_f32_16x16x32_bf16 v[68:71], v[148:151], v[216:219], v[68:71]
	v_mfma_f32_16x16x32_bf16 v[64:67], v[172:175], v[216:219], v[64:67]
	s_barrier
	s_setprio 0
	s_add_i32 s22, s44, s31
	v_lshl_add_u64 v[184:185], s[26:27], 0, v[154:155]
	s_mov_b32 m0, s22
	ds_read_b128 v[176:179], v193 offset:16384
	ds_read_b128 v[180:183], v193 offset:17408
	ds_read_b128 v[196:199], v193 offset:18432
	ds_read_b128 v[200:203], v193 offset:19456
	ds_read_b128 v[204:207], v193 offset:20480
	ds_read_b128 v[208:211], v193 offset:21504
	ds_read_b128 v[212:215], v193 offset:22528
	ds_read_b128 v[216:219], v193 offset:23552
	global_load_lds_dwordx4 v[184:185], off
	s_add_i32 m0, s22, 0x2000
	s_add_u32 s22, s26, 0xb0000
	v_lshl_add_u64 v[220:221], s[26:27], 0, v[158:159]
	s_addc_u32 s23, s27, 0
	s_add_i32 s58, s45, s31
	global_load_lds_dwordx4 v[220:221], off
	v_lshl_add_u64 v[222:223], s[22:23], 0, v[154:155]
	s_mov_b32 m0, s58
	v_lshl_add_u64 v[224:225], s[28:29], 0, v[156:157]
	global_load_lds_dwordx4 v[222:223], off
	v_lshl_add_u64 v[222:223], s[22:23], 0, v[158:159]
	s_add_i32 m0, s58, 0x2000
	s_nop 0
	global_load_lds_dwordx4 v[222:223], off
	v_lshl_add_u64 v[222:223], s[28:29], 0, v[152:153]
	s_mov_b32 m0, s34
	s_nop 0
	global_load_lds_dwordx4 v[222:223], off
	s_mov_b32 m0, s35
	s_nop 0
	global_load_lds_dwordx4 v[224:225], off
	s_waitcnt vmcnt(8)
	s_waitcnt lgkmcnt(0)
	s_barrier
; #define PG8_STAGE(bufoff, gbase, voff) do { _Pragma("unroll") for (int _i = 0; _i < 2; ++_i) \
;         __builtin_amdgcn_global_load_lds((const unsigned*)((const char*)(gbase) + (voff)[_i]), (PG8_LAS unsigned*)(lds + (bufoff) + ldsw + _i * 8192), 16, 0, 0); } while (0)
; #define PG8_LDA(dst, b, h) do { _Pragma("unroll") for (int m = 0; m < 4; ++m) _Pragma("unroll") for (int k = 0; k < 2; ++k) dst[m][k] = *(const PG8_LAS bf16x8*)(lds + PG8_SA(b, h) + aoff + m * 2048 + k * 1024); } while (0)
; #define PG8_LDB(dst, b, h) do { _Pragma("unroll") for (int n = 0; n < 2; ++n) _Pragma("unroll") for (int k = 0; k < 2; ++k) dst[n][k] = *(const PG8_LAS bf16x8*)(lds + PG8_SB(b, h) + boff + n * 2048 + k * 1024); } while (0)
; #define PG8_MMA(ai, bj, At, Bt) do { __builtin_amdgcn_s_setprio(1); _Pragma("unroll") for (int m = 0; m < 4; ++m) _Pragma("unroll") for (int n = 0; n < 2; ++n) _Pragma("unroll") for (int k = 0; k < 2; ++k) \
;         acc[ai][bj][m][n] = __builtin_amdgcn_mfma_f32_16x16x32_bf16(Bt[n][k], At[m][k], acc[ai][bj][m][n], 0, 0, 0); __builtin_amdgcn_s_setprio(0); } while (0)
; #define PG8_WAIT_V(n) asm volatile("s_waitcnt vmcnt(" #n ")" ::: "memory")
; #define PG8_WAIT_L(n) asm volatile("s_waitcnt lgkmcnt(" #n ")" ::: "memory")
; #define PG8_BAR __builtin_amdgcn_s_barrier()
; #define PG8_SCHED __builtin_amdgcn_sched_barrier(0)
; template <class Epi, class Sched, bool ALIGN_EPI = false, bool SP2 = false>
; __device__ __forceinline__ void gemm_phase(PG8_LAS unsigned char* lds, const Gemm g, const Sched& S, const Epi& E) {
;     ...
;             PG8_WAIT_V(8); PG8_WAIT_L(0); PG8_BAR; PG8_MMA(1, 0, At, B0); PG8_MMA(1, 1, At, B1); PG8_BAR; PG8_SCHED;
;             PG8_LDB(B0, 1, 0); PG8_LDB(B1, 1, 1); PG8_SCHED; PG8_LDA(At, 1, 0); PG8_STAGE(PG8_SA(0, 1), a2 + hstepA, voffA);
;             PG8_WAIT_V(8); PG8_WAIT_L(0); PG8_BAR; PG8_MMA(0, 0, At, B0); PG8_MMA(0, 1, At, B1); PG8_BAR; PG8_SCHED;
	s_setprio 1
	v_mfma_f32_16x16x32_bf16 v[60:63], v[128:131], v[176:179], v[60:63]
	v_mfma_f32_16x16x32_bf16 v[56:59], v[136:139], v[176:179], v[56:59]
	v_mfma_f32_16x16x32_bf16 v[44:47], v[128:131], v[196:199], v[44:47]
	v_mfma_f32_16x16x32_bf16 v[40:43], v[136:139], v[196:199], v[40:43]
	v_mfma_f32_16x16x32_bf16 v[28:31], v[128:131], v[204:207], v[28:31]
	v_mfma_f32_16x16x32_bf16 v[24:27], v[136:139], v[204:207], v[24:27]
	v_mfma_f32_16x16x32_bf16 v[12:15], v[128:131], v[212:215], v[12:15]
	v_mfma_f32_16x16x32_bf16 v[8:11], v[136:139], v[212:215], v[8:11]
	v_mfma_f32_16x16x32_bf16 v[60:63], v[132:135], v[180:183], v[60:63]
	v_mfma_f32_16x16x32_bf16 v[56:59], v[140:143], v[180:183], v[56:59]
	v_mfma_f32_16x16x32_bf16 v[44:47], v[132:135], v[200:203], v[44:47]
	v_mfma_f32_16x16x32_bf16 v[40:43], v[140:143], v[200:203], v[40:43]
	v_mfma_f32_16x16x32_bf16 v[28:31], v[132:135], v[208:211], v[28:31]
	v_mfma_f32_16x16x32_bf16 v[24:27], v[140:143], v[208:211], v[24:27]
	v_mfma_f32_16x16x32_bf16 v[12:15], v[132:135], v[216:219], v[12:15]
	v_mfma_f32_16x16x32_bf16 v[8:11], v[140:143], v[216:219], v[8:11]
	s_setprio 1
	v_mfma_f32_16x16x32_bf16 v[52:55], v[144:147], v[176:179], v[52:55]
	v_mfma_f32_16x16x32_bf16 v[48:51], v[168:171], v[176:179], v[48:51]
	v_mfma_f32_16x16x32_bf16 v[36:39], v[144:147], v[196:199], v[36:39]
	v_mfma_f32_16x16x32_bf16 v[32:35], v[168:171], v[196:199], v[32:35]
	v_mfma_f32_16x16x32_bf16 v[20:23], v[144:147], v[204:207], v[20:23]
	v_mfma_f32_16x16x32_bf16 v[16:19], v[168:171], v[204:207], v[16:19]
	v_mfma_f32_16x16x32_bf16 v[4:7], v[144:147], v[212:215], v[4:7]
	v_mfma_f32_16x16x32_bf16 v[0:3], v[168:171], v[212:215], v[0:3]
	v_mfma_f32_16x16x32_bf16 v[52:55], v[148:151], v[180:183], v[52:55]
	v_mfma_f32_16x16x32_bf16 v[48:51], v[172:175], v[180:183], v[48:51]
	v_mfma_f32_16x16x32_bf16 v[36:39], v[148:151], v[200:203], v[36:39]
	v_mfma_f32_16x16x32_bf16 v[32:35], v[172:175], v[200:203], v[32:35]
	v_mfma_f32_16x16x32_bf16 v[20:23], v[148:151], v[208:211], v[20:23]
	v_mfma_f32_16x16x32_bf16 v[16:19], v[172:175], v[208:211], v[16:19]
	v_mfma_f32_16x16x32_bf16 v[4:7], v[148:151], v[216:219], v[4:7]
	v_mfma_f32_16x16x32_bf16 v[0:3], v[172:175], v[216:219], v[0:3]
	s_barrier
	s_setprio 0
	s_add_i32 s58, 0, 0x18000
	s_add_i32 s59, 0, 0x1c000
	v_add_u32_e32 v140, s58, v189
	v_add_u32_e32 v172, s59, v189
	ds_read_b128 v[128:131], v140
	ds_read_b128 v[132:135], v140 offset:1024
	ds_read_b128 v[136:139], v140 offset:2048
	ds_read_b128 v[140:143], v140 offset:3072
	ds_read_b128 v[144:147], v172
	ds_read_b128 v[148:151], v172 offset:1024
	ds_read_b128 v[168:171], v172 offset:2048
	ds_read_b128 v[172:175], v172 offset:3072
	s_add_u32 s22, s28, 0xb0000
	s_addc_u32 s23, s29, 0
	s_mov_b32 m0, s36
	v_lshl_add_u64 v[226:227], s[22:23], 0, v[152:153]
	ds_read_b128 v[176:179], v193 offset:32768
	ds_read_b128 v[180:183], v193 offset:33792
	ds_read_b128 v[196:199], v193 offset:34816
	ds_read_b128 v[200:203], v193 offset:35840
	ds_read_b128 v[204:207], v193 offset:36864
	ds_read_b128 v[208:211], v193 offset:37888
	ds_read_b128 v[212:215], v193 offset:38912
	ds_read_b128 v[216:219], v193 offset:39936
	global_load_lds_dwordx4 v[226:227], off
	v_lshl_add_u64 v[226:227], s[22:23], 0, v[156:157]
	s_mov_b32 m0, s37
	s_nop 0
	global_load_lds_dwordx4 v[226:227], off
	s_waitcnt vmcnt(8)
	s_waitcnt lgkmcnt(0)
	s_barrier
	s_setprio 1
	v_mfma_f32_16x16x32_bf16 v[124:127], v[128:131], v[176:179], v[124:127]
	v_mfma_f32_16x16x32_bf16 v[120:123], v[136:139], v[176:179], v[120:123]
	v_mfma_f32_16x16x32_bf16 v[108:111], v[128:131], v[196:199], v[108:111]
	v_mfma_f32_16x16x32_bf16 v[104:107], v[136:139], v[196:199], v[104:107]
	v_mfma_f32_16x16x32_bf16 v[92:95], v[128:131], v[204:207], v[92:95]
	v_mfma_f32_16x16x32_bf16 v[88:91], v[136:139], v[204:207], v[88:91]
	v_mfma_f32_16x16x32_bf16 v[76:79], v[128:131], v[212:215], v[76:79]
	v_mfma_f32_16x16x32_bf16 v[72:75], v[136:139], v[212:215], v[72:75]
	v_mfma_f32_16x16x32_bf16 v[124:127], v[132:135], v[180:183], v[124:127]
	v_mfma_f32_16x16x32_bf16 v[120:123], v[140:143], v[180:183], v[120:123]
	v_mfma_f32_16x16x32_bf16 v[108:111], v[132:135], v[200:203], v[108:111]
	v_mfma_f32_16x16x32_bf16 v[104:107], v[140:143], v[200:203], v[104:107]
	v_mfma_f32_16x16x32_bf16 v[92:95], v[132:135], v[208:211], v[92:95]
	v_mfma_f32_16x16x32_bf16 v[88:91], v[140:143], v[208:211], v[88:91]
	v_mfma_f32_16x16x32_bf16 v[76:79], v[132:135], v[216:219], v[76:79]
	v_mfma_f32_16x16x32_bf16 v[72:75], v[140:143], v[216:219], v[72:75]
	s_setprio 1
	v_mfma_f32_16x16x32_bf16 v[116:119], v[144:147], v[176:179], v[116:119]
	v_mfma_f32_16x16x32_bf16 v[112:115], v[168:171], v[176:179], v[112:115]
	v_mfma_f32_16x16x32_bf16 v[100:103], v[144:147], v[196:199], v[100:103]
	v_mfma_f32_16x16x32_bf16 v[96:99], v[168:171], v[196:199], v[96:99]
	v_mfma_f32_16x16x32_bf16 v[84:87], v[144:147], v[204:207], v[84:87]
	v_mfma_f32_16x16x32_bf16 v[80:83], v[168:171], v[204:207], v[80:83]
	v_mfma_f32_16x16x32_bf16 v[68:71], v[144:147], v[212:215], v[68:71]
	v_mfma_f32_16x16x32_bf16 v[64:67], v[168:171], v[212:215], v[64:67]
	v_mfma_f32_16x16x32_bf16 v[116:119], v[148:151], v[180:183], v[116:119]
	v_mfma_f32_16x16x32_bf16 v[112:115], v[172:175], v[180:183], v[112:115]
	v_mfma_f32_16x16x32_bf16 v[100:103], v[148:151], v[200:203], v[100:103]
	v_mfma_f32_16x16x32_bf16 v[96:99], v[172:175], v[200:203], v[96:99]
	v_mfma_f32_16x16x32_bf16 v[84:87], v[148:151], v[208:211], v[84:87]
	v_mfma_f32_16x16x32_bf16 v[80:83], v[172:175], v[208:211], v[80:83]
	v_mfma_f32_16x16x32_bf16 v[68:71], v[148:151], v[216:219], v[68:71]
	v_mfma_f32_16x16x32_bf16 v[64:67], v[172:175], v[216:219], v[64:67]
	s_barrier
; #define PG8_STAGE(bufoff, gbase, voff) do { _Pragma("unroll") for (int _i = 0; _i < 2; ++_i) \
;         __builtin_amdgcn_global_load_lds((const unsigned*)((const char*)(gbase) + (voff)[_i]), (PG8_LAS unsigned*)(lds + (bufoff) + ldsw + _i * 8192), 16, 0, 0); } while (0)
; #define PG8_LDA(dst, b, h) do { _Pragma("unroll") for (int m = 0; m < 4; ++m) _Pragma("unroll") for (int k = 0; k < 2; ++k) dst[m][k] = *(const PG8_LAS bf16x8*)(lds + PG8_SA(b, h) + aoff + m * 2048 + k * 1024); } while (0)
; #define PG8_MMA(ai, bj, At, Bt) do { __builtin_amdgcn_s_setprio(1); _Pragma("unroll") for (int m = 0; m < 4; ++m) _Pragma("unroll") for (int n = 0; n < 2; ++n) _Pragma("unroll") for (int k = 0; k < 2; ++k) \
;         acc[ai][bj][m][n] = __builtin_amdgcn_mfma_f32_16x16x32_bf16(Bt[n][k], At[m][k], acc[ai][bj][m][n], 0, 0, 0); __builtin_amdgcn_s_setprio(0); } while (0)
; #define PG8_WAIT_V(n) asm volatile("s_waitcnt vmcnt(" #n ")" ::: "memory")
; #define PG8_WAIT_L(n) asm volatile("s_waitcnt lgkmcnt(" #n ")" ::: "memory")
; #define PG8_BAR __builtin_amdgcn_s_barrier()
; #define PG8_SCHED __builtin_amdgcn_sched_barrier(0)
; template <class Epi, class Sched, bool ALIGN_EPI = false, bool SP2 = false>
; __device__ __forceinline__ void gemm_phase(PG8_LAS unsigned char* lds, const Gemm g, const Sched& S, const Epi& E) {
;     ...
;         for (int t = 0; t < nt; t += 2) {
;             const bool last = (t == nt - 2);
;     ...
;             PG8_LDA(At, 1, 1); PG8_STAGE(PG8_SB(1, 0), b3, voffB); PG8_STAGE(PG8_SB(1, 1), b3 + hstepB, voffB); PG8_STAGE(PG8_SA(1, 0), a3, voffA);
;             PG8_WAIT_V(8); PG8_WAIT_L(0); PG8_BAR; PG8_MMA(1, 0, At, B0); PG8_MMA(1, 1, At, B1); PG8_BAR; PG8_SCHED;
	s_setprio 0
	s_add_i32 s22, s58, s31
	v_lshl_add_u64 v[184:185], v[184:185], 0, s[16:17]
	s_mov_b32 m0, s22
	ds_read_b128 v[176:179], v193 offset:49152
	ds_read_b128 v[180:183], v193 offset:50176
	ds_read_b128 v[196:199], v193 offset:51200
	ds_read_b128 v[200:203], v193 offset:52224
	ds_read_b128 v[204:207], v193 offset:53248
	ds_read_b128 v[208:211], v193 offset:54272
	ds_read_b128 v[212:215], v193 offset:55296
	ds_read_b128 v[216:219], v193 offset:56320
	global_load_lds_dwordx4 v[184:185], off
	s_add_i32 m0, s22, 0x2000
	s_add_u32 s22, s26, 0xb0080
	v_lshl_add_u64 v[184:185], v[220:221], 0, s[16:17]
	s_addc_u32 s23, s27, 0
	s_add_i32 s26, s59, s31
	global_load_lds_dwordx4 v[184:185], off
	v_lshl_add_u64 v[184:185], s[22:23], 0, v[154:155]
	s_mov_b32 m0, s26
	s_nop 0
	global_load_lds_dwordx4 v[184:185], off
	v_lshl_add_u64 v[184:185], s[22:23], 0, v[158:159]
	s_add_i32 m0, s26, 0x2000
	s_nop 0
	global_load_lds_dwordx4 v[184:185], off
	v_lshl_add_u64 v[184:185], v[222:223], 0, s[16:17]
	s_mov_b32 m0, s39
	s_nop 0
	global_load_lds_dwordx4 v[184:185], off
	v_lshl_add_u64 v[184:185], v[224:225], 0, s[16:17]
	s_mov_b32 m0, s40
	s_nop 0
	global_load_lds_dwordx4 v[184:185], off
	s_waitcnt vmcnt(8)
	s_waitcnt lgkmcnt(0)
	s_barrier
	s_setprio 1
	v_mfma_f32_16x16x32_bf16 v[60:63], v[128:131], v[176:179], v[60:63]
	v_mfma_f32_16x16x32_bf16 v[56:59], v[136:139], v[176:179], v[56:59]
	v_mfma_f32_16x16x32_bf16 v[44:47], v[128:131], v[196:199], v[44:47]
	v_mfma_f32_16x16x32_bf16 v[40:43], v[136:139], v[196:199], v[40:43]
	v_mfma_f32_16x16x32_bf16 v[28:31], v[128:131], v[204:207], v[28:31]
	v_mfma_f32_16x16x32_bf16 v[24:27], v[136:139], v[204:207], v[24:27]
	v_mfma_f32_16x16x32_bf16 v[12:15], v[128:131], v[212:215], v[12:15]
	v_mfma_f32_16x16x32_bf16 v[8:11], v[136:139], v[212:215], v[8:11]
	v_mfma_f32_16x16x32_bf16 v[60:63], v[132:135], v[180:183], v[60:63]
	v_mfma_f32_16x16x32_bf16 v[56:59], v[140:143], v[180:183], v[56:59]
	v_mfma_f32_16x16x32_bf16 v[44:47], v[132:135], v[200:203], v[44:47]
	v_mfma_f32_16x16x32_bf16 v[40:43], v[140:143], v[200:203], v[40:43]
	v_mfma_f32_16x16x32_bf16 v[28:31], v[132:135], v[208:211], v[28:31]
	v_mfma_f32_16x16x32_bf16 v[24:27], v[140:143], v[208:211], v[24:27]
	v_mfma_f32_16x16x32_bf16 v[12:15], v[132:135], v[216:219], v[12:15]
	v_mfma_f32_16x16x32_bf16 v[8:11], v[140:143], v[216:219], v[8:11]
	s_setprio 1
	v_mfma_f32_16x16x32_bf16 v[52:55], v[144:147], v[176:179], v[52:55]
	v_mfma_f32_16x16x32_bf16 v[48:51], v[168:171], v[176:179], v[48:51]
	v_mfma_f32_16x16x32_bf16 v[36:39], v[144:147], v[196:199], v[36:39]
	v_mfma_f32_16x16x32_bf16 v[32:35], v[168:171], v[196:199], v[32:35]
	v_mfma_f32_16x16x32_bf16 v[20:23], v[144:147], v[204:207], v[20:23]
	v_mfma_f32_16x16x32_bf16 v[16:19], v[168:171], v[204:207], v[16:19]
	v_mfma_f32_16x16x32_bf16 v[4:7], v[144:147], v[212:215], v[4:7]
	v_mfma_f32_16x16x32_bf16 v[0:3], v[168:171], v[212:215], v[0:3]
	v_mfma_f32_16x16x32_bf16 v[52:55], v[148:151], v[180:183], v[52:55]
	v_mfma_f32_16x16x32_bf16 v[48:51], v[172:175], v[180:183], v[48:51]
	v_mfma_f32_16x16x32_bf16 v[36:39], v[148:151], v[200:203], v[36:39]
	v_mfma_f32_16x16x32_bf16 v[32:35], v[172:175], v[200:203], v[32:35]
	v_mfma_f32_16x16x32_bf16 v[20:23], v[148:151], v[208:211], v[20:23]
	v_mfma_f32_16x16x32_bf16 v[16:19], v[172:175], v[208:211], v[16:19]
	v_mfma_f32_16x16x32_bf16 v[4:7], v[148:151], v[216:219], v[4:7]
	v_mfma_f32_16x16x32_bf16 v[0:3], v[172:175], v[216:219], v[0:3]
	s_barrier
	s_setprio 0
	s_add_i32 s69, s69, 2
	s_add_u32 s67, s67, 0x100
	s_addc_u32 s68, s68, 0
	s_cmp_gt_u32 s69, 41
	s_mov_b64 s[22:23], s[24:25]
	s_cbranch_scc0 .LBB0_1129
	s_and_b64 vcc, exec, s[18:19]
	s_cbranch_vccz .LBB0_1132
	s_barrier

; #define PG8_STAGE(bufoff, gbase, voff) do { _Pragma("unroll") for (int _i = 0; _i < 2; ++_i) \
;         __builtin_amdgcn_global_load_lds((const unsigned*)((const char*)(gbase) + (voff)[_i]), (PG8_LAS unsigned*)(lds + (bufoff) + ldsw + _i * 8192), 16, 0, 0); } while (0)
; #define PG8_LDA(dst, b, h) do { _Pragma("unroll") for (int m = 0; m < 4; ++m) _Pragma("unroll") for (int k = 0; k < 2; ++k) dst[m][k] = *(const PG8_LAS bf16x8*)(lds + PG8_SA(b, h) + aoff + m * 2048 + k * 1024); } while (0)
; #define PG8_LDB(dst, b, h) do { _Pragma("unroll") for (int n = 0; n < 2; ++n) _Pragma("unroll") for (int k = 0; k < 2; ++k) dst[n][k] = *(const PG8_LAS bf16x8*)(lds + PG8_SB(b, h) + boff + n * 2048 + k * 1024); } while (0)
; #define PG8_WAIT_V(n) asm volatile("s_waitcnt vmcnt(" #n ")" ::: "memory")
; #define PG8_WAIT_L(n) asm volatile("s_waitcnt lgkmcnt(" #n ")" ::: "memory")
; #define PG8_BAR __builtin_amdgcn_s_barrier()
; #define PG8_SCHED __builtin_amdgcn_sched_barrier(0)
; template <class Epi, class Sched, bool ALIGN_EPI = false, bool SP2 = false>
; __device__ __forceinline__ void gemm_phase(PG8_LAS unsigned char* lds, const Gemm g, const Sched& S, const Epi& E) {
;     ...
;         const bool has_next = S.next(ui + 1, nxt);
;         const char* nA = has_next ? (const char*)g.A + (size_t)nxt.pm * tstepA : cA; const char* nB = has_next ? (const char*)g.Bt + (size_t)nxt.pn * tstepB : cB;
;         for (int t = 0; t < nt; t += 2) {
;             const bool last = (t == nt - 2);
;             const char* a1 = cA + (size_t)(t + 1) * kstep;
;             const char* a2 = last ? nA : cA + (size_t)(t + 2) * kstep; const char* b2 = last ? nB : cB + (size_t)(t + 2) * kstep;
;             const char* a3 = a2 + kstep; const char* b3 = b2 + kstep;
;             if (last && has_next) S.a_ready(nxt);
;             if constexpr (SP2) {
;             PG8_LDB(B0, 0, 0); PG8_LDB(B1, 0, 1); PG8_SCHED; PG8_LDA(At, 0, 0); PG8_STAGE(PG8_SA(1, 1), a1 + hstepA, voffA);
;             PG8_WAIT_V(8); PG8_WAIT_L(0); PG8_BAR; PG8_MMA(0, 0, At, B0); PG8_MMA(0, 1, At, B1); PG8_BAR; PG8_SCHED;
;             PG8_LDA(At, 0, 1); PG8_STAGE(PG8_SB(0, 0), b2, voffB); PG8_STAGE(PG8_SB(0, 1), b2 + hstepB, voffB); PG8_STAGE(PG8_SA(0, 0), a2, voffA);
;             PG8_WAIT_V(8); PG8_WAIT_L(0); PG8_BAR; PG8_MMA(1, 0, At, B0); PG8_MMA(1, 1, At, B1); PG8_BAR; PG8_SCHED;
.LBB0_1161:
	s_add_u32 s43, s36, s42
	s_addc_u32 s48, s37, 0
	s_add_u32 s46, s43, 0x100
	s_addc_u32 s47, s48, 0
	s_and_b64 s[44:45], s[40:41], exec
	s_cselect_b32 s45, s25, s47
	s_cselect_b32 s44, s89, s46
	s_add_u32 s42, s34, s42
	s_addc_u32 s46, s35, 0
	s_add_u32 s42, s42, 0x100
	s_addc_u32 s46, s46, 0
	s_and_b64 s[40:41], s[40:41], exec
	s_cselect_b32 s47, s23, s46
	s_cselect_b32 s46, s90, s42
	s_add_u32 s64, s43, 0x10080
	ds_read_b128 v[146:149], v143
	ds_read_b128 v[150:153], v143 offset:1024
	ds_read_b128 v[154:157], v143 offset:2048
	ds_read_b128 v[158:161], v143 offset:3072
	ds_read_b128 v[162:165], v144
	ds_read_b128 v[166:169], v144 offset:1024
	ds_read_b128 v[170:173], v144 offset:2048
	ds_read_b128 v[174:177], v144 offset:3072
	s_addc_u32 s65, s48, 0
	s_add_i32 s97, s82, s67
	s_add_i32 m0, s31, 0xc000
	s_add_i32 s59, s31, 0xe000
	s_add_i32 s58, s97, 0x2000
	s_add_u32 s48, s46, 0x10000
	s_addc_u32 s49, s47, 0
	s_add_i32 vcc_hi, s83, s67
	s_add_i32 vcc_lo, vcc_hi, 0x2000
	s_add_i32 s96, 0, 0x18000
	s_add_i32 s95, 0, 0x1c000
	s_add_u32 s42, s44, 0x10000
	s_addc_u32 s43, s45, 0
	s_add_i32 s94, s96, s67
	s_add_i32 s92, s94, 0x2000
	s_add_u32 s40, s46, 0x10080
	s_addc_u32 s41, s47, 0
	s_add_i32 s93, s95, s67
	s_add_i32 s91, s93, 0x2000
	v_lshl_add_u64 v[212:213], s[64:65], 0, v[134:135]
	ds_read_b128 v[178:181], v145
	ds_read_b128 v[182:185], v145 offset:1024
	ds_read_b128 v[188:191], v145 offset:2048
	ds_read_b128 v[192:195], v145 offset:3072
	ds_read_b128 v[196:199], v145 offset:4096
	ds_read_b128 v[200:203], v145 offset:5120
	ds_read_b128 v[204:207], v145 offset:6144
	ds_read_b128 v[208:211], v145 offset:7168
	global_load_lds_dwordx4 v[212:213], off
	v_lshl_add_u64 v[212:213], s[64:65], 0, v[130:131]
	s_mov_b32 m0, s59
	s_nop 0
	global_load_lds_dwordx4 v[212:213], off
	s_waitcnt vmcnt(8)
	s_waitcnt lgkmcnt(0)
	s_barrier
	s_setprio 1
	v_mfma_f32_16x16x32_bf16 v[124:127], v[146:149], v[178:181], v[124:127]
	v_mfma_f32_16x16x32_bf16 v[120:123], v[154:157], v[178:181], v[120:123]
	v_mfma_f32_16x16x32_bf16 v[116:119], v[146:149], v[188:191], v[116:119]
	v_mfma_f32_16x16x32_bf16 v[108:111], v[154:157], v[188:191], v[108:111]
	v_mfma_f32_16x16x32_bf16 v[100:103], v[146:149], v[196:199], v[100:103]
	v_mfma_f32_16x16x32_bf16 v[92:95], v[154:157], v[196:199], v[92:95]
	v_mfma_f32_16x16x32_bf16 v[84:87], v[146:149], v[204:207], v[84:87]
	v_mfma_f32_16x16x32_bf16 v[76:79], v[154:157], v[204:207], v[76:79]
	v_mfma_f32_16x16x32_bf16 v[124:127], v[150:153], v[182:185], v[124:127]
	v_mfma_f32_16x16x32_bf16 v[120:123], v[158:161], v[182:185], v[120:123]
	v_mfma_f32_16x16x32_bf16 v[116:119], v[150:153], v[192:195], v[116:119]
	v_mfma_f32_16x16x32_bf16 v[108:111], v[158:161], v[192:195], v[108:111]
	v_mfma_f32_16x16x32_bf16 v[100:103], v[150:153], v[200:203], v[100:103]
	v_mfma_f32_16x16x32_bf16 v[92:95], v[158:161], v[200:203], v[92:95]
	v_mfma_f32_16x16x32_bf16 v[84:87], v[150:153], v[208:211], v[84:87]
	v_mfma_f32_16x16x32_bf16 v[76:79], v[158:161], v[208:211], v[76:79]
	s_setprio 1
	v_mfma_f32_16x16x32_bf16 v[112:115], v[162:165], v[178:181], v[112:115]
	v_mfma_f32_16x16x32_bf16 v[104:107], v[170:173], v[178:181], v[104:107]
	v_mfma_f32_16x16x32_bf16 v[96:99], v[162:165], v[188:191], v[96:99]
	v_mfma_f32_16x16x32_bf16 v[88:91], v[170:173], v[188:191], v[88:91]
	v_mfma_f32_16x16x32_bf16 v[80:83], v[162:165], v[196:199], v[80:83]
	v_mfma_f32_16x16x32_bf16 v[72:75], v[170:173], v[196:199], v[72:75]
	v_mfma_f32_16x16x32_bf16 v[68:71], v[162:165], v[204:207], v[68:71]
	v_mfma_f32_16x16x32_bf16 v[64:67], v[170:173], v[204:207], v[64:67]
	v_mfma_f32_16x16x32_bf16 v[112:115], v[166:169], v[182:185], v[112:115]
	v_mfma_f32_16x16x32_bf16 v[104:107], v[174:177], v[182:185], v[104:107]
	v_mfma_f32_16x16x32_bf16 v[96:99], v[166:169], v[192:195], v[96:99]
	v_mfma_f32_16x16x32_bf16 v[88:91], v[174:177], v[192:195], v[88:91]
	v_mfma_f32_16x16x32_bf16 v[80:83], v[166:169], v[200:203], v[80:83]
	v_mfma_f32_16x16x32_bf16 v[72:75], v[174:177], v[200:203], v[72:75]
	v_mfma_f32_16x16x32_bf16 v[68:71], v[166:169], v[208:211], v[68:71]
	v_mfma_f32_16x16x32_bf16 v[64:67], v[174:177], v[208:211], v[64:67]
	s_barrier
	s_setprio 0
	s_mov_b32 m0, s97
	v_lshl_add_u64 v[212:213], s[46:47], 0, v[132:133]
	ds_read_b128 v[178:181], v145 offset:16384
	ds_read_b128 v[182:185], v145 offset:17408
	ds_read_b128 v[188:191], v145 offset:18432
	ds_read_b128 v[192:195], v145 offset:19456
	ds_read_b128 v[196:199], v145 offset:20480
	ds_read_b128 v[200:203], v145 offset:21504
	ds_read_b128 v[204:207], v145 offset:22528
	ds_read_b128 v[208:211], v145 offset:23552
	global_load_lds_dwordx4 v[212:213], off
	v_lshl_add_u64 v[214:215], s[46:47], 0, v[128:129]
	s_mov_b32 m0, s58
	v_lshl_add_u64 v[216:217], s[48:49], 0, v[132:133]
	global_load_lds_dwordx4 v[214:215], off
	s_mov_b32 m0, vcc_hi
	v_lshl_add_u64 v[218:219], s[44:45], 0, v[130:131]
	global_load_lds_dwordx4 v[216:217], off
	v_lshl_add_u64 v[216:217], s[48:49], 0, v[128:129]
	s_mov_b32 m0, vcc_lo
	s_nop 0
	global_load_lds_dwordx4 v[216:217], off
	v_lshl_add_u64 v[216:217], s[44:45], 0, v[134:135]
	s_mov_b32 m0, s31
	s_nop 0
	global_load_lds_dwordx4 v[216:217], off
	s_mov_b32 m0, s74
	s_nop 0
	global_load_lds_dwordx4 v[218:219], off
	s_waitcnt vmcnt(8)
	s_waitcnt lgkmcnt(0)
	s_barrier
; #define PG8_STAGE(bufoff, gbase, voff) do { _Pragma("unroll") for (int _i = 0; _i < 2; ++_i) \
;         __builtin_amdgcn_global_load_lds((const unsigned*)((const char*)(gbase) + (voff)[_i]), (PG8_LAS unsigned*)(lds + (bufoff) + ldsw + _i * 8192), 16, 0, 0); } while (0)
; #define PG8_LDA(dst, b, h) do { _Pragma("unroll") for (int m = 0; m < 4; ++m) _Pragma("unroll") for (int k = 0; k < 2; ++k) dst[m][k] = *(const PG8_LAS bf16x8*)(lds + PG8_SA(b, h) + aoff + m * 2048 + k * 1024); } while (0)
; #define PG8_LDB(dst, b, h) do { _Pragma("unroll") for (int n = 0; n < 2; ++n) _Pragma("unroll") for (int k = 0; k < 2; ++k) dst[n][k] = *(const PG8_LAS bf16x8*)(lds + PG8_SB(b, h) + boff + n * 2048 + k * 1024); } while (0)
; #define PG8_MMA(ai, bj, At, Bt) do { __builtin_amdgcn_s_setprio(1); _Pragma("unroll") for (int m = 0; m < 4; ++m) _Pragma("unroll") for (int n = 0; n < 2; ++n) _Pragma("unroll") for (int k = 0; k < 2; ++k) \
;         acc[ai][bj][m][n] = __builtin_amdgcn_mfma_f32_16x16x32_bf16(Bt[n][k], At[m][k], acc[ai][bj][m][n], 0, 0, 0); __builtin_amdgcn_s_setprio(0); } while (0)
; #define PG8_WAIT_V(n) asm volatile("s_waitcnt vmcnt(" #n ")" ::: "memory")
; #define PG8_WAIT_L(n) asm volatile("s_waitcnt lgkmcnt(" #n ")" ::: "memory")
; #define PG8_BAR __builtin_amdgcn_s_barrier()
; #define PG8_SCHED __builtin_amdgcn_sched_barrier(0)
; template <class Epi, class Sched, bool ALIGN_EPI = false, bool SP2 = false>
; __device__ __forceinline__ void gemm_phase(PG8_LAS unsigned char* lds, const Gemm g, const Sched& S, const Epi& E) {
;     ...
;             PG8_WAIT_V(8); PG8_WAIT_L(0); PG8_BAR; PG8_MMA(1, 0, At, B0); PG8_MMA(1, 1, At, B1); PG8_BAR; PG8_SCHED;
;             PG8_LDB(B0, 1, 0); PG8_LDB(B1, 1, 1); PG8_SCHED; PG8_LDA(At, 1, 0); PG8_STAGE(PG8_SA(0, 1), a2 + hstepA, voffA);
;             PG8_WAIT_V(8); PG8_WAIT_L(0); PG8_BAR; PG8_MMA(0, 0, At, B0); PG8_MMA(0, 1, At, B1); PG8_BAR; PG8_SCHED;
	s_setprio 1
	v_mfma_f32_16x16x32_bf16 v[60:63], v[146:149], v[178:181], v[60:63]
	v_mfma_f32_16x16x32_bf16 v[56:59], v[154:157], v[178:181], v[56:59]
	v_mfma_f32_16x16x32_bf16 v[52:55], v[146:149], v[188:191], v[52:55]
	v_mfma_f32_16x16x32_bf16 v[44:47], v[154:157], v[188:191], v[44:47]
	v_mfma_f32_16x16x32_bf16 v[36:39], v[146:149], v[196:199], v[36:39]
	v_mfma_f32_16x16x32_bf16 v[28:31], v[154:157], v[196:199], v[28:31]
	v_mfma_f32_16x16x32_bf16 v[20:23], v[146:149], v[204:207], v[20:23]
	v_mfma_f32_16x16x32_bf16 v[12:15], v[154:157], v[204:207], v[12:15]
	v_mfma_f32_16x16x32_bf16 v[60:63], v[150:153], v[182:185], v[60:63]
	v_mfma_f32_16x16x32_bf16 v[56:59], v[158:161], v[182:185], v[56:59]
	v_mfma_f32_16x16x32_bf16 v[52:55], v[150:153], v[192:195], v[52:55]
	v_mfma_f32_16x16x32_bf16 v[44:47], v[158:161], v[192:195], v[44:47]
	v_mfma_f32_16x16x32_bf16 v[36:39], v[150:153], v[200:203], v[36:39]
	v_mfma_f32_16x16x32_bf16 v[28:31], v[158:161], v[200:203], v[28:31]
	v_mfma_f32_16x16x32_bf16 v[20:23], v[150:153], v[208:211], v[20:23]
	v_mfma_f32_16x16x32_bf16 v[12:15], v[158:161], v[208:211], v[12:15]
	s_setprio 1
	v_mfma_f32_16x16x32_bf16 v[48:51], v[162:165], v[178:181], v[48:51]
	v_mfma_f32_16x16x32_bf16 v[40:43], v[170:173], v[178:181], v[40:43]
	v_mfma_f32_16x16x32_bf16 v[32:35], v[162:165], v[188:191], v[32:35]
	v_mfma_f32_16x16x32_bf16 v[24:27], v[170:173], v[188:191], v[24:27]
	v_mfma_f32_16x16x32_bf16 v[16:19], v[162:165], v[196:199], v[16:19]
	v_mfma_f32_16x16x32_bf16 v[8:11], v[170:173], v[196:199], v[8:11]
	v_mfma_f32_16x16x32_bf16 v[4:7], v[162:165], v[204:207], v[4:7]
	v_mfma_f32_16x16x32_bf16 v[0:3], v[170:173], v[204:207], v[0:3]
	v_mfma_f32_16x16x32_bf16 v[48:51], v[166:169], v[182:185], v[48:51]
	v_mfma_f32_16x16x32_bf16 v[40:43], v[174:177], v[182:185], v[40:43]
	v_mfma_f32_16x16x32_bf16 v[32:35], v[166:169], v[192:195], v[32:35]
	v_mfma_f32_16x16x32_bf16 v[24:27], v[174:177], v[192:195], v[24:27]
	v_mfma_f32_16x16x32_bf16 v[16:19], v[166:169], v[200:203], v[16:19]
	v_mfma_f32_16x16x32_bf16 v[8:11], v[174:177], v[200:203], v[8:11]
	v_mfma_f32_16x16x32_bf16 v[4:7], v[166:169], v[208:211], v[4:7]
	v_mfma_f32_16x16x32_bf16 v[0:3], v[174:177], v[208:211], v[0:3]
	s_barrier
	s_setprio 0
	v_add_u32_e32 v158, s96, v141
	v_add_u32_e32 v174, s95, v141
	ds_read_b128 v[146:149], v158
	ds_read_b128 v[150:153], v158 offset:1024
	ds_read_b128 v[154:157], v158 offset:2048
	ds_read_b128 v[158:161], v158 offset:3072
	ds_read_b128 v[162:165], v174
	ds_read_b128 v[166:169], v174 offset:1024
	ds_read_b128 v[170:173], v174 offset:2048
	ds_read_b128 v[174:177], v174 offset:3072
	s_mov_b32 m0, s75
	v_lshl_add_u64 v[220:221], s[42:43], 0, v[134:135]
	ds_read_b128 v[178:181], v145 offset:32768
	ds_read_b128 v[182:185], v145 offset:33792
	ds_read_b128 v[188:191], v145 offset:34816
	ds_read_b128 v[192:195], v145 offset:35840
	ds_read_b128 v[196:199], v145 offset:36864
	ds_read_b128 v[200:203], v145 offset:37888
	ds_read_b128 v[204:207], v145 offset:38912
	ds_read_b128 v[208:211], v145 offset:39936
	global_load_lds_dwordx4 v[220:221], off
	v_lshl_add_u64 v[220:221], s[42:43], 0, v[130:131]
	s_mov_b32 m0, s76
	s_nop 0
	global_load_lds_dwordx4 v[220:221], off
	s_waitcnt vmcnt(8)
	s_waitcnt lgkmcnt(0)
	s_barrier
	s_setprio 1
	v_mfma_f32_16x16x32_bf16 v[124:127], v[146:149], v[178:181], v[124:127]
	v_mfma_f32_16x16x32_bf16 v[120:123], v[154:157], v[178:181], v[120:123]
	v_mfma_f32_16x16x32_bf16 v[116:119], v[146:149], v[188:191], v[116:119]
	v_mfma_f32_16x16x32_bf16 v[108:111], v[154:157], v[188:191], v[108:111]
	v_mfma_f32_16x16x32_bf16 v[100:103], v[146:149], v[196:199], v[100:103]
	v_mfma_f32_16x16x32_bf16 v[92:95], v[154:157], v[196:199], v[92:95]
	v_mfma_f32_16x16x32_bf16 v[84:87], v[146:149], v[204:207], v[84:87]
	v_mfma_f32_16x16x32_bf16 v[76:79], v[154:157], v[204:207], v[76:79]
	v_mfma_f32_16x16x32_bf16 v[124:127], v[150:153], v[182:185], v[124:127]
	v_mfma_f32_16x16x32_bf16 v[120:123], v[158:161], v[182:185], v[120:123]
	v_mfma_f32_16x16x32_bf16 v[116:119], v[150:153], v[192:195], v[116:119]
	v_mfma_f32_16x16x32_bf16 v[108:111], v[158:161], v[192:195], v[108:111]
	v_mfma_f32_16x16x32_bf16 v[100:103], v[150:153], v[200:203], v[100:103]
	v_mfma_f32_16x16x32_bf16 v[92:95], v[158:161], v[200:203], v[92:95]
	v_mfma_f32_16x16x32_bf16 v[84:87], v[150:153], v[208:211], v[84:87]
	v_mfma_f32_16x16x32_bf16 v[76:79], v[158:161], v[208:211], v[76:79]
	s_setprio 1
	v_mfma_f32_16x16x32_bf16 v[112:115], v[162:165], v[178:181], v[112:115]
	v_mfma_f32_16x16x32_bf16 v[104:107], v[170:173], v[178:181], v[104:107]
	v_mfma_f32_16x16x32_bf16 v[96:99], v[162:165], v[188:191], v[96:99]
	v_mfma_f32_16x16x32_bf16 v[88:91], v[170:173], v[188:191], v[88:91]
	v_mfma_f32_16x16x32_bf16 v[80:83], v[162:165], v[196:199], v[80:83]
	v_mfma_f32_16x16x32_bf16 v[72:75], v[170:173], v[196:199], v[72:75]
	v_mfma_f32_16x16x32_bf16 v[68:71], v[162:165], v[204:207], v[68:71]
	v_mfma_f32_16x16x32_bf16 v[64:67], v[170:173], v[204:207], v[64:67]
	v_mfma_f32_16x16x32_bf16 v[112:115], v[166:169], v[182:185], v[112:115]
	v_mfma_f32_16x16x32_bf16 v[104:107], v[174:177], v[182:185], v[104:107]
	v_mfma_f32_16x16x32_bf16 v[96:99], v[166:169], v[192:195], v[96:99]
	v_mfma_f32_16x16x32_bf16 v[88:91], v[174:177], v[192:195], v[88:91]
	v_mfma_f32_16x16x32_bf16 v[80:83], v[166:169], v[200:203], v[80:83]
	v_mfma_f32_16x16x32_bf16 v[72:75], v[174:177], v[200:203], v[72:75]
	v_mfma_f32_16x16x32_bf16 v[68:71], v[166:169], v[208:211], v[68:71]
	v_mfma_f32_16x16x32_bf16 v[64:67], v[174:177], v[208:211], v[64:67]
	s_barrier
; #define PG8_STAGE(bufoff, gbase, voff) do { _Pragma("unroll") for (int _i = 0; _i < 2; ++_i) \
;         __builtin_amdgcn_global_load_lds((const unsigned*)((const char*)(gbase) + (voff)[_i]), (PG8_LAS unsigned*)(lds + (bufoff) + ldsw + _i * 8192), 16, 0, 0); } while (0)
; #define PG8_LDA(dst, b, h) do { _Pragma("unroll") for (int m = 0; m < 4; ++m) _Pragma("unroll") for (int k = 0; k < 2; ++k) dst[m][k] = *(const PG8_LAS bf16x8*)(lds + PG8_SA(b, h) + aoff + m * 2048 + k * 1024); } while (0)
; #define PG8_MMA(ai, bj, At, Bt) do { __builtin_amdgcn_s_setprio(1); _Pragma("unroll") for (int m = 0; m < 4; ++m) _Pragma("unroll") for (int n = 0; n < 2; ++n) _Pragma("unroll") for (int k = 0; k < 2; ++k) \
;         acc[ai][bj][m][n] = __builtin_amdgcn_mfma_f32_16x16x32_bf16(Bt[n][k], At[m][k], acc[ai][bj][m][n], 0, 0, 0); __builtin_amdgcn_s_setprio(0); } while (0)
; #define PG8_WAIT_V(n) asm volatile("s_waitcnt vmcnt(" #n ")" ::: "memory")
; #define PG8_WAIT_L(n) asm volatile("s_waitcnt lgkmcnt(" #n ")" ::: "memory")
; #define PG8_BAR __builtin_amdgcn_s_barrier()
; #define PG8_SCHED __builtin_amdgcn_sched_barrier(0)
; template <class Epi, class Sched, bool ALIGN_EPI = false, bool SP2 = false>
; __device__ __forceinline__ void gemm_phase(PG8_LAS unsigned char* lds, const Gemm g, const Sched& S, const Epi& E) {
;     ...
;         for (int t = 0; t < nt; t += 2) {
;             const bool last = (t == nt - 2);
;     ...
;             PG8_LDA(At, 1, 1); PG8_STAGE(PG8_SB(1, 0), b3, voffB); PG8_STAGE(PG8_SB(1, 1), b3 + hstepB, voffB); PG8_STAGE(PG8_SA(1, 0), a3, voffA);
;             PG8_WAIT_V(8); PG8_WAIT_L(0); PG8_BAR; PG8_MMA(1, 0, At, B0); PG8_MMA(1, 1, At, B1); PG8_BAR; PG8_SCHED;
	s_setprio 0
	s_mov_b32 m0, s94
	v_lshl_add_u64 v[212:213], v[212:213], 0, s[10:11]
	ds_read_b128 v[178:181], v145 offset:49152
	ds_read_b128 v[182:185], v145 offset:50176
	ds_read_b128 v[188:191], v145 offset:51200
	ds_read_b128 v[192:195], v145 offset:52224
	ds_read_b128 v[196:199], v145 offset:53248
	ds_read_b128 v[200:203], v145 offset:54272
	ds_read_b128 v[204:207], v145 offset:55296
	ds_read_b128 v[208:211], v145 offset:56320
	global_load_lds_dwordx4 v[212:213], off
	v_lshl_add_u64 v[212:213], v[214:215], 0, s[10:11]
	s_mov_b32 m0, s92
	s_nop 0
	global_load_lds_dwordx4 v[212:213], off
	v_lshl_add_u64 v[212:213], s[40:41], 0, v[132:133]
	s_mov_b32 m0, s93
	s_nop 0
	global_load_lds_dwordx4 v[212:213], off
	v_lshl_add_u64 v[212:213], s[40:41], 0, v[128:129]
	s_mov_b32 m0, s91
	s_nop 0
	global_load_lds_dwordx4 v[212:213], off
	v_lshl_add_u64 v[212:213], v[216:217], 0, s[10:11]
	s_mov_b32 m0, s78
	s_nop 0
	global_load_lds_dwordx4 v[212:213], off
	v_lshl_add_u64 v[212:213], v[218:219], 0, s[10:11]
	s_mov_b32 m0, s79
	s_nop 0
	global_load_lds_dwordx4 v[212:213], off
	s_waitcnt vmcnt(8)
	s_waitcnt lgkmcnt(0)
	s_barrier
	s_setprio 1
	v_mfma_f32_16x16x32_bf16 v[60:63], v[146:149], v[178:181], v[60:63]
	v_mfma_f32_16x16x32_bf16 v[56:59], v[154:157], v[178:181], v[56:59]
	v_mfma_f32_16x16x32_bf16 v[52:55], v[146:149], v[188:191], v[52:55]
	v_mfma_f32_16x16x32_bf16 v[44:47], v[154:157], v[188:191], v[44:47]
	v_mfma_f32_16x16x32_bf16 v[36:39], v[146:149], v[196:199], v[36:39]
	v_mfma_f32_16x16x32_bf16 v[28:31], v[154:157], v[196:199], v[28:31]
	v_mfma_f32_16x16x32_bf16 v[20:23], v[146:149], v[204:207], v[20:23]
	v_mfma_f32_16x16x32_bf16 v[12:15], v[154:157], v[204:207], v[12:15]
	v_mfma_f32_16x16x32_bf16 v[60:63], v[150:153], v[182:185], v[60:63]
	v_mfma_f32_16x16x32_bf16 v[56:59], v[158:161], v[182:185], v[56:59]
	v_mfma_f32_16x16x32_bf16 v[52:55], v[150:153], v[192:195], v[52:55]
	v_mfma_f32_16x16x32_bf16 v[44:47], v[158:161], v[192:195], v[44:47]
	v_mfma_f32_16x16x32_bf16 v[36:39], v[150:153], v[200:203], v[36:39]
	v_mfma_f32_16x16x32_bf16 v[28:31], v[158:161], v[200:203], v[28:31]
	v_mfma_f32_16x16x32_bf16 v[20:23], v[150:153], v[208:211], v[20:23]
	v_mfma_f32_16x16x32_bf16 v[12:15], v[158:161], v[208:211], v[12:15]
	s_setprio 1
	v_mfma_f32_16x16x32_bf16 v[48:51], v[162:165], v[178:181], v[48:51]
	v_mfma_f32_16x16x32_bf16 v[40:43], v[170:173], v[178:181], v[40:43]
	v_mfma_f32_16x16x32_bf16 v[32:35], v[162:165], v[188:191], v[32:35]
	v_mfma_f32_16x16x32_bf16 v[24:27], v[170:173], v[188:191], v[24:27]
	v_mfma_f32_16x16x32_bf16 v[16:19], v[162:165], v[196:199], v[16:19]
	v_mfma_f32_16x16x32_bf16 v[8:11], v[170:173], v[196:199], v[8:11]
	v_mfma_f32_16x16x32_bf16 v[4:7], v[162:165], v[204:207], v[4:7]
	v_mfma_f32_16x16x32_bf16 v[0:3], v[170:173], v[204:207], v[0:3]
	v_mfma_f32_16x16x32_bf16 v[48:51], v[166:169], v[182:185], v[48:51]
	v_mfma_f32_16x16x32_bf16 v[40:43], v[174:177], v[182:185], v[40:43]
	v_mfma_f32_16x16x32_bf16 v[32:35], v[166:169], v[192:195], v[32:35]
	v_mfma_f32_16x16x32_bf16 v[24:27], v[174:177], v[192:195], v[24:27]
	v_mfma_f32_16x16x32_bf16 v[16:19], v[166:169], v[200:203], v[16:19]
	v_mfma_f32_16x16x32_bf16 v[8:11], v[174:177], v[200:203], v[8:11]
	v_mfma_f32_16x16x32_bf16 v[4:7], v[166:169], v[208:211], v[4:7]
	v_mfma_f32_16x16x32_bf16 v[0:3], v[174:177], v[208:211], v[0:3]
	s_barrier
	s_setprio 0
	s_movk_i32 s42, 0x100
	s_andn2_b64 vcc, exec, s[38:39]
	s_mov_b64 s[40:41], -1
	s_mov_b64 s[38:39], 0
	s_cbranch_vccz .LBB0_1161
	s_and_b64 vcc, exec, s[14:15]
	s_cbranch_vccz .LBB0_1164
	s_barrier

; #define PG8_STAGE(bufoff, gbase, voff) do { _Pragma("unroll") for (int _i = 0; _i < 2; ++_i) \
;         __builtin_amdgcn_global_load_lds((const unsigned*)((const char*)(gbase) + (voff)[_i]), (PG8_LAS unsigned*)(lds + (bufoff) + ldsw + _i * 8192), 16, 0, 0); } while (0)
; #define PG8_LDA(dst, b, h) do { _Pragma("unroll") for (int m = 0; m < 4; ++m) _Pragma("unroll") for (int k = 0; k < 2; ++k) dst[m][k] = *(const PG8_LAS bf16x8*)(lds + PG8_SA(b, h) + aoff + m * 2048 + k * 1024); } while (0)
; #define PG8_LDB(dst, b, h) do { _Pragma("unroll") for (int n = 0; n < 2; ++n) _Pragma("unroll") for (int k = 0; k < 2; ++k) dst[n][k] = *(const PG8_LAS bf16x8*)(lds + PG8_SB(b, h) + boff + n * 2048 + k * 1024); } while (0)
; #define PG8_MMA(ai, bj, At, Bt) do { __builtin_amdgcn_s_setprio(1); _Pragma("unroll") for (int m = 0; m < 4; ++m) _Pragma("unroll") for (int n = 0; n < 2; ++n) _Pragma("unroll") for (int k = 0; k < 2; ++k) \
;         acc[ai][bj][m][n] = __builtin_amdgcn_mfma_f32_16x16x32_bf16(Bt[n][k], At[m][k], acc[ai][bj][m][n], 0, 0, 0); __builtin_amdgcn_s_setprio(0); } while (0)
; #define PG8_WAIT_V(n) asm volatile("s_waitcnt vmcnt(" #n ")" ::: "memory")
; #define PG8_WAIT_L(n) asm volatile("s_waitcnt lgkmcnt(" #n ")" ::: "memory")
; #define PG8_BAR __builtin_amdgcn_s_barrier()
; template <class Epi, class Sched, bool ALIGN_EPI = false, bool SP2 = false>
; __device__ __forceinline__ void gemm_phase(PG8_LAS unsigned char* lds, const Gemm g, const Sched& S, const Epi& E) {
;     ...
;             const char* a1 = cA + (size_t)(t + 1) * kstep;
;             const char* a2 = last ? nA : cA + (size_t)(t + 2) * kstep; const char* b2 = last ? nB : cB + (size_t)(t + 2) * kstep;
;             const char* a3 = a2 + kstep; const char* b3 = b2 + kstep;
;             if (last && has_next) S.a_ready(nxt);
;             if constexpr (SP2) {
;             PG8_LDB(B0, 0, 0); PG8_LDB(B1, 0, 1); PG8_SCHED; PG8_LDA(At, 0, 0); PG8_STAGE(PG8_SA(1, 1), a1 + hstepA, voffA);
;             PG8_WAIT_V(8); PG8_WAIT_L(0); PG8_BAR; PG8_MMA(0, 0, At, B0); PG8_MMA(0, 1, At, B1); PG8_BAR; PG8_SCHED;
;             PG8_LDA(At, 0, 1); PG8_STAGE(PG8_SB(0, 0), b2, voffB); PG8_STAGE(PG8_SB(0, 1), b2 + hstepB, voffB); PG8_STAGE(PG8_SA(0, 0), a2, voffA);
;             PG8_WAIT_V(8); PG8_WAIT_L(0); PG8_BAR; PG8_MMA(1, 0, At, B0); PG8_MMA(1, 1, At, B1); PG8_BAR; PG8_SCHED;
.LBB0_1231:
	ds_read_b128 v[112:115], v185
	ds_read_b128 v[116:119], v185 offset:1024
	ds_read_b128 v[128:131], v185 offset:2048
	ds_read_b128 v[140:143], v185 offset:3072
	ds_read_b128 v[144:147], v188
	ds_read_b128 v[148:151], v188 offset:1024
	ds_read_b128 v[168:171], v188 offset:2048
	ds_read_b128 v[172:175], v188 offset:3072
	s_add_u32 s34, s30, 0xfffc0080
	s_addc_u32 s35, s31, -1
	s_cmp_eq_u32 s69, 12
	s_cselect_b32 s37, s21, s35
	s_cselect_b32 s36, s27, s34
	s_cselect_b32 s35, s19, s68
	s_cselect_b32 s34, s66, s67
	v_lshl_add_u64 v[180:181], s[30:31], 0, v[160:161]
	s_add_i32 m0, s29, 0xc000
	ds_read_b128 v[176:179], v189
	ds_read_b128 v[192:195], v189 offset:1024
	ds_read_b128 v[196:199], v189 offset:2048
	ds_read_b128 v[200:203], v189 offset:3072
	ds_read_b128 v[204:207], v189 offset:4096
	ds_read_b128 v[208:211], v189 offset:5120
	ds_read_b128 v[212:215], v189 offset:6144
	ds_read_b128 v[216:219], v189 offset:7168
	global_load_lds_dwordx4 v[180:181], off
	v_lshl_add_u64 v[180:181], s[30:31], 0, v[162:163]
	s_add_i32 m0, s29, 0xe000
	s_nop 0
	global_load_lds_dwordx4 v[180:181], off
	s_waitcnt vmcnt(8)
	s_waitcnt lgkmcnt(0)
	s_barrier
	s_setprio 1
	v_mfma_f32_16x16x32_bf16 v[136:139], v[112:115], v[176:179], v[136:139]
	v_mfma_f32_16x16x32_bf16 v[132:135], v[128:131], v[176:179], v[132:135]
	v_mfma_f32_16x16x32_bf16 v[108:111], v[112:115], v[196:199], v[108:111]
	v_mfma_f32_16x16x32_bf16 v[104:107], v[128:131], v[196:199], v[104:107]
	v_mfma_f32_16x16x32_bf16 v[92:95], v[112:115], v[204:207], v[92:95]
	v_mfma_f32_16x16x32_bf16 v[88:91], v[128:131], v[204:207], v[88:91]
	v_mfma_f32_16x16x32_bf16 v[76:79], v[112:115], v[212:215], v[76:79]
	v_mfma_f32_16x16x32_bf16 v[72:75], v[128:131], v[212:215], v[72:75]
	v_mfma_f32_16x16x32_bf16 v[136:139], v[116:119], v[192:195], v[136:139]
	v_mfma_f32_16x16x32_bf16 v[132:135], v[140:143], v[192:195], v[132:135]
	v_mfma_f32_16x16x32_bf16 v[108:111], v[116:119], v[200:203], v[108:111]
	v_mfma_f32_16x16x32_bf16 v[104:107], v[140:143], v[200:203], v[104:107]
	v_mfma_f32_16x16x32_bf16 v[92:95], v[116:119], v[208:211], v[92:95]
	v_mfma_f32_16x16x32_bf16 v[88:91], v[140:143], v[208:211], v[88:91]
	v_mfma_f32_16x16x32_bf16 v[76:79], v[116:119], v[216:219], v[76:79]
	v_mfma_f32_16x16x32_bf16 v[72:75], v[140:143], v[216:219], v[72:75]
	s_setprio 1
	v_mfma_f32_16x16x32_bf16 v[124:127], v[144:147], v[176:179], v[124:127]
	v_mfma_f32_16x16x32_bf16 v[120:123], v[168:171], v[176:179], v[120:123]
	v_mfma_f32_16x16x32_bf16 v[100:103], v[144:147], v[196:199], v[100:103]
	v_mfma_f32_16x16x32_bf16 v[96:99], v[168:171], v[196:199], v[96:99]
	v_mfma_f32_16x16x32_bf16 v[84:87], v[144:147], v[204:207], v[84:87]
	v_mfma_f32_16x16x32_bf16 v[80:83], v[168:171], v[204:207], v[80:83]
	v_mfma_f32_16x16x32_bf16 v[68:71], v[144:147], v[212:215], v[68:71]
	v_mfma_f32_16x16x32_bf16 v[64:67], v[168:171], v[212:215], v[64:67]
	v_mfma_f32_16x16x32_bf16 v[124:127], v[148:151], v[192:195], v[124:127]
	v_mfma_f32_16x16x32_bf16 v[120:123], v[172:175], v[192:195], v[120:123]
	v_mfma_f32_16x16x32_bf16 v[100:103], v[148:151], v[200:203], v[100:103]
	v_mfma_f32_16x16x32_bf16 v[96:99], v[172:175], v[200:203], v[96:99]
	v_mfma_f32_16x16x32_bf16 v[84:87], v[148:151], v[208:211], v[84:87]
	v_mfma_f32_16x16x32_bf16 v[80:83], v[172:175], v[208:211], v[80:83]
	v_mfma_f32_16x16x32_bf16 v[68:71], v[148:151], v[216:219], v[68:71]
	v_mfma_f32_16x16x32_bf16 v[64:67], v[172:175], v[216:219], v[64:67]
	s_barrier
	s_setprio 0
	s_add_i32 s58, s49, s39
	v_lshl_add_u64 v[180:181], s[34:35], 0, v[154:155]
	s_mov_b32 m0, s58
	ds_read_b128 v[176:179], v189 offset:16384
	ds_read_b128 v[192:195], v189 offset:17408
	ds_read_b128 v[196:199], v189 offset:18432
	ds_read_b128 v[200:203], v189 offset:19456
	ds_read_b128 v[204:207], v189 offset:20480
	ds_read_b128 v[208:211], v189 offset:21504
	ds_read_b128 v[212:215], v189 offset:22528
	ds_read_b128 v[216:219], v189 offset:23552
	global_load_lds_dwordx4 v[180:181], off
	s_add_i32 m0, s58, 0x2000
	s_add_u32 s58, s34, 0x40000
	v_lshl_add_u64 v[220:221], s[34:35], 0, v[158:159]
	s_addc_u32 s59, s35, 0
	s_add_i32 s73, s64, s39
	global_load_lds_dwordx4 v[220:221], off
	v_lshl_add_u64 v[222:223], s[58:59], 0, v[154:155]
	s_mov_b32 m0, s73
	v_lshl_add_u64 v[224:225], s[36:37], 0, v[156:157]
	global_load_lds_dwordx4 v[222:223], off
	v_lshl_add_u64 v[222:223], s[58:59], 0, v[158:159]
	s_add_i32 m0, s73, 0x2000
	s_nop 0
	global_load_lds_dwordx4 v[222:223], off
	v_lshl_add_u64 v[222:223], s[36:37], 0, v[152:153]
	s_mov_b32 m0, s29
	s_nop 0
	global_load_lds_dwordx4 v[222:223], off
	s_mov_b32 m0, s40
	s_nop 0
	global_load_lds_dwordx4 v[224:225], off
	s_waitcnt vmcnt(8)
	s_waitcnt lgkmcnt(0)
	s_barrier
; #define PG8_STAGE(bufoff, gbase, voff) do { _Pragma("unroll") for (int _i = 0; _i < 2; ++_i) \
;         __builtin_amdgcn_global_load_lds((const unsigned*)((const char*)(gbase) + (voff)[_i]), (PG8_LAS unsigned*)(lds + (bufoff) + ldsw + _i * 8192), 16, 0, 0); } while (0)
; #define PG8_LDA(dst, b, h) do { _Pragma("unroll") for (int m = 0; m < 4; ++m) _Pragma("unroll") for (int k = 0; k < 2; ++k) dst[m][k] = *(const PG8_LAS bf16x8*)(lds + PG8_SA(b, h) + aoff + m * 2048 + k * 1024); } while (0)
; #define PG8_LDB(dst, b, h) do { _Pragma("unroll") for (int n = 0; n < 2; ++n) _Pragma("unroll") for (int k = 0; k < 2; ++k) dst[n][k] = *(const PG8_LAS bf16x8*)(lds + PG8_SB(b, h) + boff + n * 2048 + k * 1024); } while (0)
; #define PG8_MMA(ai, bj, At, Bt) do { __builtin_amdgcn_s_setprio(1); _Pragma("unroll") for (int m = 0; m < 4; ++m) _Pragma("unroll") for (int n = 0; n < 2; ++n) _Pragma("unroll") for (int k = 0; k < 2; ++k) \
;         acc[ai][bj][m][n] = __builtin_amdgcn_mfma_f32_16x16x32_bf16(Bt[n][k], At[m][k], acc[ai][bj][m][n], 0, 0, 0); __builtin_amdgcn_s_setprio(0); } while (0)
; #define PG8_WAIT_V(n) asm volatile("s_waitcnt vmcnt(" #n ")" ::: "memory")
; #define PG8_WAIT_L(n) asm volatile("s_waitcnt lgkmcnt(" #n ")" ::: "memory")
; #define PG8_BAR __builtin_amdgcn_s_barrier()
; #define PG8_SCHED __builtin_amdgcn_sched_barrier(0)
; template <class Epi, class Sched, bool ALIGN_EPI = false, bool SP2 = false>
; __device__ __forceinline__ void gemm_phase(PG8_LAS unsigned char* lds, const Gemm g, const Sched& S, const Epi& E) {
;     ...
;             PG8_WAIT_V(8); PG8_WAIT_L(0); PG8_BAR; PG8_MMA(1, 0, At, B0); PG8_MMA(1, 1, At, B1); PG8_BAR; PG8_SCHED;
;             PG8_LDB(B0, 1, 0); PG8_LDB(B1, 1, 1); PG8_SCHED; PG8_LDA(At, 1, 0); PG8_STAGE(PG8_SA(0, 1), a2 + hstepA, voffA);
;             PG8_WAIT_V(8); PG8_WAIT_L(0); PG8_BAR; PG8_MMA(0, 0, At, B0); PG8_MMA(0, 1, At, B1); PG8_BAR; PG8_SCHED;
	s_setprio 1
	v_mfma_f32_16x16x32_bf16 v[60:63], v[112:115], v[176:179], v[60:63]
	v_mfma_f32_16x16x32_bf16 v[56:59], v[128:131], v[176:179], v[56:59]
	v_mfma_f32_16x16x32_bf16 v[44:47], v[112:115], v[196:199], v[44:47]
	v_mfma_f32_16x16x32_bf16 v[40:43], v[128:131], v[196:199], v[40:43]
	v_mfma_f32_16x16x32_bf16 v[28:31], v[112:115], v[204:207], v[28:31]
	v_mfma_f32_16x16x32_bf16 v[24:27], v[128:131], v[204:207], v[24:27]
	v_mfma_f32_16x16x32_bf16 v[12:15], v[112:115], v[212:215], v[12:15]
	v_mfma_f32_16x16x32_bf16 v[8:11], v[128:131], v[212:215], v[8:11]
	v_mfma_f32_16x16x32_bf16 v[60:63], v[116:119], v[192:195], v[60:63]
	v_mfma_f32_16x16x32_bf16 v[56:59], v[140:143], v[192:195], v[56:59]
	v_mfma_f32_16x16x32_bf16 v[44:47], v[116:119], v[200:203], v[44:47]
	v_mfma_f32_16x16x32_bf16 v[40:43], v[140:143], v[200:203], v[40:43]
	v_mfma_f32_16x16x32_bf16 v[28:31], v[116:119], v[208:211], v[28:31]
	v_mfma_f32_16x16x32_bf16 v[24:27], v[140:143], v[208:211], v[24:27]
	v_mfma_f32_16x16x32_bf16 v[12:15], v[116:119], v[216:219], v[12:15]
	v_mfma_f32_16x16x32_bf16 v[8:11], v[140:143], v[216:219], v[8:11]
	s_setprio 1
	v_mfma_f32_16x16x32_bf16 v[52:55], v[144:147], v[176:179], v[52:55]
	v_mfma_f32_16x16x32_bf16 v[48:51], v[168:171], v[176:179], v[48:51]
	v_mfma_f32_16x16x32_bf16 v[36:39], v[144:147], v[196:199], v[36:39]
	v_mfma_f32_16x16x32_bf16 v[32:35], v[168:171], v[196:199], v[32:35]
	v_mfma_f32_16x16x32_bf16 v[20:23], v[144:147], v[204:207], v[20:23]
	v_mfma_f32_16x16x32_bf16 v[16:19], v[168:171], v[204:207], v[16:19]
	v_mfma_f32_16x16x32_bf16 v[4:7], v[144:147], v[212:215], v[4:7]
	v_mfma_f32_16x16x32_bf16 v[0:3], v[168:171], v[212:215], v[0:3]
	v_mfma_f32_16x16x32_bf16 v[52:55], v[148:151], v[192:195], v[52:55]
	v_mfma_f32_16x16x32_bf16 v[48:51], v[172:175], v[192:195], v[48:51]
	v_mfma_f32_16x16x32_bf16 v[36:39], v[148:151], v[200:203], v[36:39]
	v_mfma_f32_16x16x32_bf16 v[32:35], v[172:175], v[200:203], v[32:35]
	v_mfma_f32_16x16x32_bf16 v[20:23], v[148:151], v[208:211], v[20:23]
	v_mfma_f32_16x16x32_bf16 v[16:19], v[172:175], v[208:211], v[16:19]
	v_mfma_f32_16x16x32_bf16 v[4:7], v[148:151], v[216:219], v[4:7]
	v_mfma_f32_16x16x32_bf16 v[0:3], v[172:175], v[216:219], v[0:3]
	s_barrier
	s_setprio 0
	s_add_i32 s58, 0, 0x18000
	s_add_i32 s59, 0, 0x1c000
	v_add_u32_e32 v140, s58, v183
	v_add_u32_e32 v172, s59, v183
	ds_read_b128 v[112:115], v140
	ds_read_b128 v[116:119], v140 offset:1024
	ds_read_b128 v[128:131], v140 offset:2048
	ds_read_b128 v[140:143], v140 offset:3072
	ds_read_b128 v[144:147], v172
	ds_read_b128 v[148:151], v172 offset:1024
	ds_read_b128 v[168:171], v172 offset:2048
	ds_read_b128 v[172:175], v172 offset:3072
	s_add_u32 s36, s36, 0x40000
	s_addc_u32 s37, s37, 0
	s_mov_b32 m0, s41
	v_lshl_add_u64 v[226:227], s[36:37], 0, v[152:153]
	ds_read_b128 v[176:179], v189 offset:32768
	ds_read_b128 v[192:195], v189 offset:33792
	ds_read_b128 v[196:199], v189 offset:34816
	ds_read_b128 v[200:203], v189 offset:35840
	ds_read_b128 v[204:207], v189 offset:36864
	ds_read_b128 v[208:211], v189 offset:37888
	ds_read_b128 v[212:215], v189 offset:38912
	ds_read_b128 v[216:219], v189 offset:39936
	global_load_lds_dwordx4 v[226:227], off
	v_lshl_add_u64 v[226:227], s[36:37], 0, v[156:157]
	s_mov_b32 m0, s42
	s_nop 0
	global_load_lds_dwordx4 v[226:227], off
	s_waitcnt vmcnt(8)
	s_waitcnt lgkmcnt(0)
	s_barrier
	s_setprio 1
	v_mfma_f32_16x16x32_bf16 v[136:139], v[112:115], v[176:179], v[136:139]
	v_mfma_f32_16x16x32_bf16 v[132:135], v[128:131], v[176:179], v[132:135]
	v_mfma_f32_16x16x32_bf16 v[108:111], v[112:115], v[196:199], v[108:111]
	v_mfma_f32_16x16x32_bf16 v[104:107], v[128:131], v[196:199], v[104:107]
	v_mfma_f32_16x16x32_bf16 v[92:95], v[112:115], v[204:207], v[92:95]
	v_mfma_f32_16x16x32_bf16 v[88:91], v[128:131], v[204:207], v[88:91]
	v_mfma_f32_16x16x32_bf16 v[76:79], v[112:115], v[212:215], v[76:79]
	v_mfma_f32_16x16x32_bf16 v[72:75], v[128:131], v[212:215], v[72:75]
	v_mfma_f32_16x16x32_bf16 v[136:139], v[116:119], v[192:195], v[136:139]
	v_mfma_f32_16x16x32_bf16 v[132:135], v[140:143], v[192:195], v[132:135]
	v_mfma_f32_16x16x32_bf16 v[108:111], v[116:119], v[200:203], v[108:111]
	v_mfma_f32_16x16x32_bf16 v[104:107], v[140:143], v[200:203], v[104:107]
	v_mfma_f32_16x16x32_bf16 v[92:95], v[116:119], v[208:211], v[92:95]
	v_mfma_f32_16x16x32_bf16 v[88:91], v[140:143], v[208:211], v[88:91]
	v_mfma_f32_16x16x32_bf16 v[76:79], v[116:119], v[216:219], v[76:79]
	v_mfma_f32_16x16x32_bf16 v[72:75], v[140:143], v[216:219], v[72:75]
	s_setprio 1
	v_mfma_f32_16x16x32_bf16 v[124:127], v[144:147], v[176:179], v[124:127]
	v_mfma_f32_16x16x32_bf16 v[120:123], v[168:171], v[176:179], v[120:123]
	v_mfma_f32_16x16x32_bf16 v[100:103], v[144:147], v[196:199], v[100:103]
	v_mfma_f32_16x16x32_bf16 v[96:99], v[168:171], v[196:199], v[96:99]
	v_mfma_f32_16x16x32_bf16 v[84:87], v[144:147], v[204:207], v[84:87]
	v_mfma_f32_16x16x32_bf16 v[80:83], v[168:171], v[204:207], v[80:83]
	v_mfma_f32_16x16x32_bf16 v[68:71], v[144:147], v[212:215], v[68:71]
	v_mfma_f32_16x16x32_bf16 v[64:67], v[168:171], v[212:215], v[64:67]
	v_mfma_f32_16x16x32_bf16 v[124:127], v[148:151], v[192:195], v[124:127]
	v_mfma_f32_16x16x32_bf16 v[120:123], v[172:175], v[192:195], v[120:123]
	v_mfma_f32_16x16x32_bf16 v[100:103], v[148:151], v[200:203], v[100:103]
	v_mfma_f32_16x16x32_bf16 v[96:99], v[172:175], v[200:203], v[96:99]
	v_mfma_f32_16x16x32_bf16 v[84:87], v[148:151], v[208:211], v[84:87]
	v_mfma_f32_16x16x32_bf16 v[80:83], v[172:175], v[208:211], v[80:83]
	v_mfma_f32_16x16x32_bf16 v[68:71], v[148:151], v[216:219], v[68:71]
	v_mfma_f32_16x16x32_bf16 v[64:67], v[172:175], v[216:219], v[64:67]
	s_barrier
; #define PG8_STAGE(bufoff, gbase, voff) do { _Pragma("unroll") for (int _i = 0; _i < 2; ++_i) \
;         __builtin_amdgcn_global_load_lds((const unsigned*)((const char*)(gbase) + (voff)[_i]), (PG8_LAS unsigned*)(lds + (bufoff) + ldsw + _i * 8192), 16, 0, 0); } while (0)
; #define PG8_LDA(dst, b, h) do { _Pragma("unroll") for (int m = 0; m < 4; ++m) _Pragma("unroll") for (int k = 0; k < 2; ++k) dst[m][k] = *(const PG8_LAS bf16x8*)(lds + PG8_SA(b, h) + aoff + m * 2048 + k * 1024); } while (0)
; #define PG8_MMA(ai, bj, At, Bt) do { __builtin_amdgcn_s_setprio(1); _Pragma("unroll") for (int m = 0; m < 4; ++m) _Pragma("unroll") for (int n = 0; n < 2; ++n) _Pragma("unroll") for (int k = 0; k < 2; ++k) \
;         acc[ai][bj][m][n] = __builtin_amdgcn_mfma_f32_16x16x32_bf16(Bt[n][k], At[m][k], acc[ai][bj][m][n], 0, 0, 0); __builtin_amdgcn_s_setprio(0); } while (0)
; #define PG8_WAIT_V(n) asm volatile("s_waitcnt vmcnt(" #n ")" ::: "memory")
; #define PG8_WAIT_L(n) asm volatile("s_waitcnt lgkmcnt(" #n ")" ::: "memory")
; #define PG8_BAR __builtin_amdgcn_s_barrier()
; #define PG8_SCHED __builtin_amdgcn_sched_barrier(0)
; template <class Epi, class Sched, bool ALIGN_EPI = false, bool SP2 = false>
; __device__ __forceinline__ void gemm_phase(PG8_LAS unsigned char* lds, const Gemm g, const Sched& S, const Epi& E) {
;     ...
;             PG8_LDA(At, 1, 1); PG8_STAGE(PG8_SB(1, 0), b3, voffB); PG8_STAGE(PG8_SB(1, 1), b3 + hstepB, voffB); PG8_STAGE(PG8_SA(1, 0), a3, voffA);
;             PG8_WAIT_V(8); PG8_WAIT_L(0); PG8_BAR; PG8_MMA(1, 0, At, B0); PG8_MMA(1, 1, At, B1); PG8_BAR; PG8_SCHED;
;     ...
;         if constexpr (ALIGN_EPI) { if (wr == 0) PG8_BAR; }
	s_setprio 0
	s_add_i32 s36, s58, s39
	v_lshl_add_u64 v[180:181], v[180:181], 0, s[14:15]
	s_mov_b32 m0, s36
	ds_read_b128 v[176:179], v189 offset:49152
	ds_read_b128 v[192:195], v189 offset:50176
	ds_read_b128 v[196:199], v189 offset:51200
	ds_read_b128 v[200:203], v189 offset:52224
	ds_read_b128 v[204:207], v189 offset:53248
	ds_read_b128 v[208:211], v189 offset:54272
	ds_read_b128 v[212:215], v189 offset:55296
	ds_read_b128 v[216:219], v189 offset:56320
	global_load_lds_dwordx4 v[180:181], off
	s_add_i32 m0, s36, 0x2000
	s_add_u32 s34, s34, 0x40080
	v_lshl_add_u64 v[180:181], v[220:221], 0, s[14:15]
	s_addc_u32 s35, s35, 0
	s_add_i32 s36, s59, s39
	global_load_lds_dwordx4 v[180:181], off
	v_lshl_add_u64 v[180:181], s[34:35], 0, v[154:155]
	s_mov_b32 m0, s36
	s_nop 0
	global_load_lds_dwordx4 v[180:181], off
	v_lshl_add_u64 v[180:181], s[34:35], 0, v[158:159]
	s_add_i32 m0, s36, 0x2000
	s_nop 0
	global_load_lds_dwordx4 v[180:181], off
	v_lshl_add_u64 v[180:181], v[222:223], 0, s[14:15]
	s_mov_b32 m0, s44
	s_nop 0
	global_load_lds_dwordx4 v[180:181], off
	v_lshl_add_u64 v[180:181], v[224:225], 0, s[14:15]
	s_mov_b32 m0, s45
	s_nop 0
	global_load_lds_dwordx4 v[180:181], off
	s_waitcnt vmcnt(8)
	s_waitcnt lgkmcnt(0)
	s_barrier
	s_setprio 1
	v_mfma_f32_16x16x32_bf16 v[60:63], v[112:115], v[176:179], v[60:63]
	v_mfma_f32_16x16x32_bf16 v[56:59], v[128:131], v[176:179], v[56:59]
	v_mfma_f32_16x16x32_bf16 v[44:47], v[112:115], v[196:199], v[44:47]
	v_mfma_f32_16x16x32_bf16 v[40:43], v[128:131], v[196:199], v[40:43]
	v_mfma_f32_16x16x32_bf16 v[28:31], v[112:115], v[204:207], v[28:31]
	v_mfma_f32_16x16x32_bf16 v[24:27], v[128:131], v[204:207], v[24:27]
	v_mfma_f32_16x16x32_bf16 v[12:15], v[112:115], v[212:215], v[12:15]
	v_mfma_f32_16x16x32_bf16 v[8:11], v[128:131], v[212:215], v[8:11]
	v_mfma_f32_16x16x32_bf16 v[60:63], v[116:119], v[192:195], v[60:63]
	v_mfma_f32_16x16x32_bf16 v[56:59], v[140:143], v[192:195], v[56:59]
	v_mfma_f32_16x16x32_bf16 v[44:47], v[116:119], v[200:203], v[44:47]
	v_mfma_f32_16x16x32_bf16 v[40:43], v[140:143], v[200:203], v[40:43]
	v_mfma_f32_16x16x32_bf16 v[28:31], v[116:119], v[208:211], v[28:31]
	v_mfma_f32_16x16x32_bf16 v[24:27], v[140:143], v[208:211], v[24:27]
	v_mfma_f32_16x16x32_bf16 v[12:15], v[116:119], v[216:219], v[12:15]
	v_mfma_f32_16x16x32_bf16 v[8:11], v[140:143], v[216:219], v[8:11]
	s_setprio 1
	v_mfma_f32_16x16x32_bf16 v[52:55], v[144:147], v[176:179], v[52:55]
	v_mfma_f32_16x16x32_bf16 v[48:51], v[168:171], v[176:179], v[48:51]
	v_mfma_f32_16x16x32_bf16 v[36:39], v[144:147], v[196:199], v[36:39]
	v_mfma_f32_16x16x32_bf16 v[32:35], v[168:171], v[196:199], v[32:35]
	v_mfma_f32_16x16x32_bf16 v[20:23], v[144:147], v[204:207], v[20:23]
	v_mfma_f32_16x16x32_bf16 v[16:19], v[168:171], v[204:207], v[16:19]
	v_mfma_f32_16x16x32_bf16 v[4:7], v[144:147], v[212:215], v[4:7]
	v_mfma_f32_16x16x32_bf16 v[0:3], v[168:171], v[212:215], v[0:3]
	v_mfma_f32_16x16x32_bf16 v[52:55], v[148:151], v[192:195], v[52:55]
	v_mfma_f32_16x16x32_bf16 v[48:51], v[172:175], v[192:195], v[48:51]
	v_mfma_f32_16x16x32_bf16 v[36:39], v[148:151], v[200:203], v[36:39]
	v_mfma_f32_16x16x32_bf16 v[32:35], v[172:175], v[200:203], v[32:35]
	v_mfma_f32_16x16x32_bf16 v[20:23], v[148:151], v[208:211], v[20:23]
	v_mfma_f32_16x16x32_bf16 v[16:19], v[172:175], v[208:211], v[16:19]
	v_mfma_f32_16x16x32_bf16 v[4:7], v[148:151], v[216:219], v[4:7]
	v_mfma_f32_16x16x32_bf16 v[0:3], v[172:175], v[216:219], v[0:3]
	s_barrier
	s_setprio 0
	s_add_i32 s69, s69, 2
	s_add_u32 s30, s30, 0x100
	s_addc_u32 s31, s31, 0
	s_add_u32 s67, s67, 0x100
	s_addc_u32 s68, s68, 0
	s_cmp_gt_u32 s69, 13
	s_cbranch_scc0 .LBB0_1231
	s_and_b64 vcc, exec, s[16:17]
	s_cbranch_vccz .LBB0_1234
	s_barrier
